# branch epilogue rewritten as software-pipelined stream (prefetch 8 groups ahead, bias loaded once) + in-proj vsec store widening
# speedup vs baseline: 1.0405x; 1.0082x over previous
; DI u32 pack2(float a, float b) { f2_t v = {a, b}; bf2_t r = __builtin_convertvector(v, bf2_t); return __builtin_bit_cast(u32, r); }
; DI int get_tid() { int t = threadIdx.x; asm volatile("" : "+v"(t)); return t; }
; DI int vperm(int s) { return (s & ~12) | ((s & 4) << 1) | ((s & 8) >> 1); }
; DI void inproj_tile8(const Params& P, const WsPtrs& W, int layer, int mt, int nt, unsigned char* smem) {
;     ...
;     const int tid2 = get_tid();
;     const int wid = tid2 >> 6, lane = tid2 & 63, wr = wid >> 2, wc = wid & 3, fr = lane & 15, fq = lane >> 4;
;     u16* vT = (n0 < O_DV) ? W.BVT : W.DVT;
;     const int nrel0 = (n0 < O_DV) ? n0 - O_BV : n0 - O_DV;
; #pragma unroll
;     for (int ai = 0; ai < 2; ++ai)
; #pragma unroll
;       for (int m = 0; m < 4; ++m) {
;         const int tl = ai * 128 + wr * 64 + m * 16 + fq * 4;
;         const f32x4 sc = *(const f32x4*)(rs + tl);
;         const int mg = m0 + tl, bl = mg >> 12, sp = vperm(mg & 4095);
; #pragma unroll
;         for (int bj = 0; bj < 2; ++bj)
; #pragma unroll
;           for (int n = 0; n < 2; ++n) {
;             const int nrel = nrel0 + bj * 128 + wc * 32 + n * 16 + fr, hh = nrel >> 7, dv = nrel & 127;
;             f32x4v a = acc[ai][bj][m][n];
;             u32x2 o2; o2.x = pack2(a.x * sc.x, a.y * sc.y); o2.y = pack2(a.z * sc.z, a.w * sc.w);
;             *(u32x2*)(vT + ((size_t)((bl * 8 + hh) * 128 + dv)) * 4096 + sp) = o2;
;           }
;       }
;     return;
.LBB0_182:
	s_or_b64 exec, exec, s[4:5]
	v_mbcnt_lo_u32_b32 v196, -1, 0
	v_mbcnt_hi_u32_b32 v196, -1, v196
	v_lshrrev_b32_e32 v196, 5, v196
	v_mul_u32_u24_e32 v196, 24, v196
	v_add_u32_e32 v196, 0xffffffe0, v196
	v_mov_b32_e32 v197, -1
	s_cmp_lt_u32 s25, 20
	v_mov_b32_e32 v0, v250
	s_cselect_b64 s[4:5], -1, 0
	s_and_b64 s[4:5], s[4:5], exec
	v_lshrrev_b32_e32 v132, 2, v0
	v_readlane_b32 s4, v255, 23
	v_ashrrev_i32_e32 v130, 2, v0
	v_and_b32_e32 v132, 12, v132
	s_movk_i32 s6, 0xffc0
	s_movk_i32 s2, 0xf000
	s_cselect_b32 s4, s4, s84
	v_and_or_b32 v142, v130, s6, v132
	v_lshrrev_b32_e32 v130, 3, v0
	v_and_b32_e32 v131, 15, v0
	s_cselect_b32 s2, s2, 0xffffec00
	s_cselect_b32 s5, s79, s22
	s_add_u32 s4, s62, s4
	v_and_b32_e32 v130, 4, v130
	v_lshrrev_b32_e32 v0, 1, v0
	s_addc_u32 s5, s63, s5
	v_and_or_b32 v130, v0, 8, v130
	v_and_b32_e32 v0, 0x60, v0
	s_add_i32 s2, s2, s10
	v_or3_b32 v131, v131, s2, v0
	s_add_i32 s2, 64, 0x24000
	v_lshl_add_u32 v133, v142, 2, s2
	ds_read_b128 v[134:137], v133
	v_add_u32_e32 v132, s14, v142
	v_ashrrev_i32_e32 v138, 2, v132
	v_and_b32_e32 v138, 0xfffffc00, v138
	s_movk_i32 s6, 0xfc0
	v_add_u32_e32 v138, v138, v131
	s_waitcnt lgkmcnt(0)
	v_pk_mul_f32 v[116:117], v[116:117], v[136:137]
	v_pk_mul_f32 v[114:115], v[114:115], v[134:135]
	v_and_or_b32 v0, v132, s6, v130
	v_cvt_pk_bf16_f32 v200, v114, v115
	v_cvt_pk_bf16_f32 v201, v116, v117
	v_or_b32_e32 v116, 16, v138
	v_lshlrev_b32_e32 v0, 1, v0
	v_ashrrev_i32_e32 v117, 31, v116
	v_lshl_add_u64 v[140:141], s[4:5], 0, v[0:1]
	v_lshlrev_b64 v[116:117], 13, v[116:117]
	v_pk_mul_f32 v[120:121], v[120:121], v[136:137]
	v_pk_mul_f32 v[118:119], v[118:119], v[134:135]
	v_ashrrev_i32_e32 v139, 31, v138
	v_lshl_add_u64 v[116:117], v[140:141], 0, v[116:117]
	v_cvt_pk_bf16_f32 v204, v118, v119
	v_cvt_pk_bf16_f32 v205, v120, v121
	v_lshlrev_b64 v[120:121], 13, v[138:139]
	s_nop 0
	v_or_b32_e32 v114, 0x80, v138
	v_lshl_add_u64 v[120:121], v[140:141], 0, v[120:121]
	v_ashrrev_i32_e32 v115, 31, v114
	s_nop 0
	v_pk_mul_f32 v[116:117], v[128:129], v[136:137]
	v_pk_mul_f32 v[118:119], v[126:127], v[134:135]
	v_lshlrev_b64 v[114:115], 13, v[114:115]
	v_cvt_pk_bf16_f32 v208, v118, v119
	v_cvt_pk_bf16_f32 v209, v116, v117
	v_lshl_add_u64 v[114:115], v[140:141], 0, v[114:115]
	s_nop 0
	v_pk_mul_f32 v[114:115], v[124:125], v[136:137]
	v_pk_mul_f32 v[116:117], v[122:123], v[134:135]
	v_or_b32_e32 v0, 16, v142
	v_cvt_pk_bf16_f32 v212, v116, v117
	v_cvt_pk_bf16_f32 v213, v114, v115
	v_or_b32_e32 v114, 0x90, v138
	v_ashrrev_i32_e32 v115, 31, v114
	v_lshlrev_b64 v[114:115], 13, v[114:115]
	v_lshl_add_u64 v[114:115], v[140:141], 0, v[114:115]
	s_nop 0
	v_lshl_add_u32 v114, v0, 2, s2
	ds_read_b128 v[114:117], v114
	v_add_u32_e32 v0, s14, v0
	s_movk_i32 s7, 0xfd0
	v_and_or_b32 v119, v0, s7, v130
	v_ashrrev_i32_e32 v0, 2, v0
	v_and_b32_e32 v0, 0xfffffc00, v0
	v_add_u32_e32 v118, v0, v131
	s_waitcnt lgkmcnt(0)
	v_pk_mul_f32 v[100:101], v[100:101], v[116:117]
	v_pk_mul_f32 v[98:99], v[98:99], v[114:115]
	v_lshlrev_b32_e32 v0, 1, v119
	v_cvt_pk_bf16_f32 v202, v98, v99
	v_cvt_pk_bf16_f32 v203, v100, v101
	v_or_b32_e32 v100, 16, v118
	v_ashrrev_i32_e32 v101, 31, v100
	v_lshl_add_u64 v[120:121], s[4:5], 0, v[0:1]
	v_lshlrev_b64 v[100:101], 13, v[100:101]
	v_pk_mul_f32 v[104:105], v[104:105], v[116:117]
	v_pk_mul_f32 v[102:103], v[102:103], v[114:115]
	v_ashrrev_i32_e32 v119, 31, v118
	v_lshl_add_u64 v[100:101], v[120:121], 0, v[100:101]
	v_cvt_pk_bf16_f32 v206, v102, v103
	v_cvt_pk_bf16_f32 v207, v104, v105
	v_lshlrev_b64 v[104:105], 13, v[118:119]
	v_lshl_add_u64 v[198:199], v[100:101], 0, v[196:197]
	s_nop 1
	v_permlane32_swap_b32_e32 v200, v202
	v_permlane32_swap_b32_e32 v201, v203
	global_store_dwordx4 v[198:199], v[200:203], off
	v_or_b32_e32 v98, 0x80, v118
	v_lshl_add_u64 v[104:105], v[120:121], 0, v[104:105]
	v_ashrrev_i32_e32 v99, 31, v98
	v_lshl_add_u64 v[198:199], v[104:105], 0, v[196:197]
	s_nop 1
	v_permlane32_swap_b32_e32 v204, v206
	v_permlane32_swap_b32_e32 v205, v207
	global_store_dwordx4 v[198:199], v[204:207], off
	v_pk_mul_f32 v[100:101], v[112:113], v[116:117]
	v_pk_mul_f32 v[102:103], v[110:111], v[114:115]
	v_lshlrev_b64 v[98:99], 13, v[98:99]
	v_cvt_pk_bf16_f32 v210, v102, v103
	v_cvt_pk_bf16_f32 v211, v100, v101
	v_lshl_add_u64 v[98:99], v[120:121], 0, v[98:99]
	v_lshl_add_u64 v[198:199], v[98:99], 0, v[196:197]
	s_nop 1
	v_permlane32_swap_b32_e32 v208, v210
	v_permlane32_swap_b32_e32 v209, v211
	global_store_dwordx4 v[198:199], v[208:211], off
	v_pk_mul_f32 v[98:99], v[108:109], v[116:117]
	v_pk_mul_f32 v[100:101], v[106:107], v[114:115]
	v_or_b32_e32 v0, 32, v142
	v_cvt_pk_bf16_f32 v214, v100, v101
	v_cvt_pk_bf16_f32 v215, v98, v99
	v_or_b32_e32 v98, 0x90, v118
	v_ashrrev_i32_e32 v99, 31, v98
	v_lshlrev_b64 v[98:99], 13, v[98:99]
	v_lshl_add_u64 v[98:99], v[120:121], 0, v[98:99]
	v_lshl_add_u64 v[198:199], v[98:99], 0, v[196:197]
	s_nop 1
	v_permlane32_swap_b32_e32 v212, v214
	v_permlane32_swap_b32_e32 v213, v215
	global_store_dwordx4 v[198:199], v[212:215], off
	v_lshl_add_u32 v98, v0, 2, s2
	ds_read_b128 v[98:101], v98
	v_add_u32_e32 v0, s14, v0
	s_movk_i32 s8, 0xfe0
	v_and_or_b32 v103, v0, s8, v130
	v_ashrrev_i32_e32 v0, 2, v0
	v_and_b32_e32 v0, 0xfffffc00, v0
	v_add_u32_e32 v102, v0, v131
	s_waitcnt lgkmcnt(0)
; DI u32 pack2(float a, float b) { f2_t v = {a, b}; bf2_t r = __builtin_convertvector(v, bf2_t); return __builtin_bit_cast(u32, r); }
; DI int get_tid() { int t = threadIdx.x; asm volatile("" : "+v"(t)); return t; }
; DI int vperm(int s) { return (s & ~12) | ((s & 4) << 1) | ((s & 8) >> 1); }
; DI void inproj_tile8(const Params& P, const WsPtrs& W, int layer, int mt, int nt, unsigned char* smem) {
;     ...
;     const int tid2 = get_tid();
;     const int wid = tid2 >> 6, lane = tid2 & 63, wr = wid >> 2, wc = wid & 3, fr = lane & 15, fq = lane >> 4;
;     u16* vT = (n0 < O_DV) ? W.BVT : W.DVT;
;     const int nrel0 = (n0 < O_DV) ? n0 - O_BV : n0 - O_DV;
; #pragma unroll
;     for (int ai = 0; ai < 2; ++ai)
; #pragma unroll
;       for (int m = 0; m < 4; ++m) {
;         const int tl = ai * 128 + wr * 64 + m * 16 + fq * 4;
;         const f32x4 sc = *(const f32x4*)(rs + tl);
;         const int mg = m0 + tl, bl = mg >> 12, sp = vperm(mg & 4095);
; #pragma unroll
;         for (int bj = 0; bj < 2; ++bj)
; #pragma unroll
;           for (int n = 0; n < 2; ++n) {
;             const int nrel = nrel0 + bj * 128 + wc * 32 + n * 16 + fr, hh = nrel >> 7, dv = nrel & 127;
;             f32x4v a = acc[ai][bj][m][n];
;             u32x2 o2; o2.x = pack2(a.x * sc.x, a.y * sc.y); o2.y = pack2(a.z * sc.z, a.w * sc.w);
;             *(u32x2*)(vT + ((size_t)((bl * 8 + hh) * 128 + dv)) * 4096 + sp) = o2;
;           }
;       }
;     return;
	v_pk_mul_f32 v[84:85], v[84:85], v[100:101]
	v_pk_mul_f32 v[82:83], v[82:83], v[98:99]
	v_lshlrev_b32_e32 v0, 1, v103
	v_cvt_pk_bf16_f32 v200, v82, v83
	v_cvt_pk_bf16_f32 v201, v84, v85
	v_or_b32_e32 v84, 16, v102
	v_ashrrev_i32_e32 v85, 31, v84
	v_lshl_add_u64 v[104:105], s[4:5], 0, v[0:1]
	v_lshlrev_b64 v[84:85], 13, v[84:85]
	v_pk_mul_f32 v[88:89], v[88:89], v[100:101]
	v_pk_mul_f32 v[86:87], v[86:87], v[98:99]
	v_ashrrev_i32_e32 v103, 31, v102
	v_lshl_add_u64 v[84:85], v[104:105], 0, v[84:85]
	v_cvt_pk_bf16_f32 v204, v86, v87
	v_cvt_pk_bf16_f32 v205, v88, v89
	v_lshlrev_b64 v[88:89], 13, v[102:103]
	s_nop 0
	v_or_b32_e32 v82, 0x80, v102
	v_lshl_add_u64 v[88:89], v[104:105], 0, v[88:89]
	v_ashrrev_i32_e32 v83, 31, v82
	s_nop 0
	v_pk_mul_f32 v[84:85], v[96:97], v[100:101]
	v_pk_mul_f32 v[86:87], v[94:95], v[98:99]
	v_lshlrev_b64 v[82:83], 13, v[82:83]
	v_cvt_pk_bf16_f32 v208, v86, v87
	v_cvt_pk_bf16_f32 v209, v84, v85
	v_lshl_add_u64 v[82:83], v[104:105], 0, v[82:83]
	s_nop 0
	v_pk_mul_f32 v[82:83], v[92:93], v[100:101]
	v_pk_mul_f32 v[84:85], v[90:91], v[98:99]
	v_or_b32_e32 v0, 48, v142
	v_cvt_pk_bf16_f32 v212, v84, v85
	v_cvt_pk_bf16_f32 v213, v82, v83
	v_or_b32_e32 v82, 0x90, v102
	v_ashrrev_i32_e32 v83, 31, v82
	v_lshlrev_b64 v[82:83], 13, v[82:83]
	v_lshl_add_u64 v[82:83], v[104:105], 0, v[82:83]
	s_nop 0
	v_lshl_add_u32 v82, v0, 2, s2
	ds_read_b128 v[82:85], v82
	v_add_u32_e32 v0, s14, v0
	s_movk_i32 s2, 0xff0
	v_and_or_b32 v87, v0, s2, v130
	v_ashrrev_i32_e32 v0, 2, v0
	v_and_b32_e32 v0, 0xfffffc00, v0
	v_add_u32_e32 v86, v0, v131
	s_waitcnt lgkmcnt(0)
	v_pk_mul_f32 v[68:69], v[68:69], v[84:85]
	v_pk_mul_f32 v[66:67], v[66:67], v[82:83]
	v_lshlrev_b32_e32 v0, 1, v87
	v_cvt_pk_bf16_f32 v202, v66, v67
	v_cvt_pk_bf16_f32 v203, v68, v69
	v_or_b32_e32 v68, 16, v86
	v_ashrrev_i32_e32 v69, 31, v68
	v_lshl_add_u64 v[88:89], s[4:5], 0, v[0:1]
	v_lshlrev_b64 v[68:69], 13, v[68:69]
	v_pk_mul_f32 v[72:73], v[72:73], v[84:85]
	v_pk_mul_f32 v[70:71], v[70:71], v[82:83]
	v_ashrrev_i32_e32 v87, 31, v86
	v_lshl_add_u64 v[68:69], v[88:89], 0, v[68:69]
	v_cvt_pk_bf16_f32 v206, v70, v71
	v_cvt_pk_bf16_f32 v207, v72, v73
	v_lshlrev_b64 v[72:73], 13, v[86:87]
	v_lshl_add_u64 v[198:199], v[68:69], 0, v[196:197]
	s_nop 1
	v_permlane32_swap_b32_e32 v200, v202
	v_permlane32_swap_b32_e32 v201, v203
	global_store_dwordx4 v[198:199], v[200:203], off
	v_or_b32_e32 v66, 0x80, v86
	v_lshl_add_u64 v[72:73], v[88:89], 0, v[72:73]
	v_ashrrev_i32_e32 v67, 31, v66
	v_lshl_add_u64 v[198:199], v[72:73], 0, v[196:197]
	s_nop 1
	v_permlane32_swap_b32_e32 v204, v206
	v_permlane32_swap_b32_e32 v205, v207
	global_store_dwordx4 v[198:199], v[204:207], off
	v_pk_mul_f32 v[68:69], v[80:81], v[84:85]
	v_pk_mul_f32 v[70:71], v[78:79], v[82:83]
	v_lshlrev_b64 v[66:67], 13, v[66:67]
	v_cvt_pk_bf16_f32 v210, v70, v71
	v_cvt_pk_bf16_f32 v211, v68, v69
	v_lshl_add_u64 v[66:67], v[88:89], 0, v[66:67]
	v_lshl_add_u64 v[198:199], v[66:67], 0, v[196:197]
	s_nop 1
	v_permlane32_swap_b32_e32 v208, v210
	v_permlane32_swap_b32_e32 v209, v211
	global_store_dwordx4 v[198:199], v[208:211], off
	v_pk_mul_f32 v[66:67], v[76:77], v[84:85]
	v_pk_mul_f32 v[68:69], v[74:75], v[82:83]
	v_add_u32_e32 v0, 0x80, v132
	v_cvt_pk_bf16_f32 v214, v68, v69
	v_cvt_pk_bf16_f32 v215, v66, v67
	v_or_b32_e32 v66, 0x90, v86
	v_ashrrev_i32_e32 v67, 31, v66
	v_lshlrev_b64 v[66:67], 13, v[66:67]
	v_lshl_add_u64 v[66:67], v[88:89], 0, v[66:67]
	v_lshl_add_u64 v[198:199], v[66:67], 0, v[196:197]
	s_nop 1
	v_permlane32_swap_b32_e32 v212, v214
	v_permlane32_swap_b32_e32 v213, v215
	global_store_dwordx4 v[198:199], v[212:215], off
	ds_read_b128 v[66:69], v133 offset:512
	v_and_or_b32 v71, v0, s6, v130
	v_ashrrev_i32_e32 v0, 2, v0
	v_and_b32_e32 v0, 0xfffffc00, v0
	v_add_u32_e32 v70, v0, v131
	s_waitcnt lgkmcnt(0)
	v_pk_mul_f32 v[52:53], v[52:53], v[68:69]
	v_pk_mul_f32 v[50:51], v[50:51], v[66:67]
	v_lshlrev_b32_e32 v0, 1, v71
	v_cvt_pk_bf16_f32 v200, v50, v51
	v_cvt_pk_bf16_f32 v201, v52, v53
	v_or_b32_e32 v52, 16, v70
	v_ashrrev_i32_e32 v53, 31, v52
	v_lshl_add_u64 v[72:73], s[4:5], 0, v[0:1]
	v_lshlrev_b64 v[52:53], 13, v[52:53]
	v_pk_mul_f32 v[60:61], v[60:61], v[68:69]
	v_pk_mul_f32 v[58:59], v[58:59], v[66:67]
	v_ashrrev_i32_e32 v71, 31, v70
	v_lshl_add_u64 v[52:53], v[72:73], 0, v[52:53]
	v_cvt_pk_bf16_f32 v204, v58, v59
	v_cvt_pk_bf16_f32 v205, v60, v61
	v_lshlrev_b64 v[60:61], 13, v[70:71]
	s_nop 0
	v_or_b32_e32 v50, 0x80, v70
	v_lshl_add_u64 v[60:61], v[72:73], 0, v[60:61]
	v_ashrrev_i32_e32 v51, 31, v50
	s_nop 0
	v_pk_mul_f32 v[52:53], v[64:65], v[68:69]
	v_pk_mul_f32 v[58:59], v[62:63], v[66:67]
	v_lshlrev_b64 v[50:51], 13, v[50:51]
	v_cvt_pk_bf16_f32 v208, v58, v59
	v_cvt_pk_bf16_f32 v209, v52, v53
	v_lshl_add_u64 v[50:51], v[72:73], 0, v[50:51]
	s_nop 0
	v_pk_mul_f32 v[50:51], v[56:57], v[68:69]
	v_pk_mul_f32 v[52:53], v[54:55], v[66:67]
	v_add_u32_e32 v0, 0x90, v132
	v_cvt_pk_bf16_f32 v212, v52, v53
	v_cvt_pk_bf16_f32 v213, v50, v51
	v_or_b32_e32 v50, 0x90, v70
	v_ashrrev_i32_e32 v51, 31, v50
	v_lshlrev_b64 v[50:51], 13, v[50:51]
	v_lshl_add_u64 v[50:51], v[72:73], 0, v[50:51]
	s_nop 0
	ds_read_b128 v[50:53], v133 offset:576
	v_and_or_b32 v55, v0, s7, v130
	v_ashrrev_i32_e32 v0, 2, v0
	v_and_b32_e32 v0, 0xfffffc00, v0
	v_add_u32_e32 v54, v0, v131
	s_waitcnt lgkmcnt(0)
; DI u32 pack2(float a, float b) { f2_t v = {a, b}; bf2_t r = __builtin_convertvector(v, bf2_t); return __builtin_bit_cast(u32, r); }
; DI int get_tid() { int t = threadIdx.x; asm volatile("" : "+v"(t)); return t; }
; DI int vperm(int s) { return (s & ~12) | ((s & 4) << 1) | ((s & 8) >> 1); }
; DI void inproj_tile8(const Params& P, const WsPtrs& W, int layer, int mt, int nt, unsigned char* smem) {
;     ...
;     const int tid2 = get_tid();
;     const int wid = tid2 >> 6, lane = tid2 & 63, wr = wid >> 2, wc = wid & 3, fr = lane & 15, fq = lane >> 4;
;     u16* vT = (n0 < O_DV) ? W.BVT : W.DVT;
;     const int nrel0 = (n0 < O_DV) ? n0 - O_BV : n0 - O_DV;
; #pragma unroll
;     for (int ai = 0; ai < 2; ++ai)
; #pragma unroll
;       for (int m = 0; m < 4; ++m) {
;         const int tl = ai * 128 + wr * 64 + m * 16 + fq * 4;
;         const f32x4 sc = *(const f32x4*)(rs + tl);
;         const int mg = m0 + tl, bl = mg >> 12, sp = vperm(mg & 4095);
; #pragma unroll
;         for (int bj = 0; bj < 2; ++bj)
; #pragma unroll
;           for (int n = 0; n < 2; ++n) {
;             const int nrel = nrel0 + bj * 128 + wc * 32 + n * 16 + fr, hh = nrel >> 7, dv = nrel & 127;
;             f32x4v a = acc[ai][bj][m][n];
;             u32x2 o2; o2.x = pack2(a.x * sc.x, a.y * sc.y); o2.y = pack2(a.z * sc.z, a.w * sc.w);
;             *(u32x2*)(vT + ((size_t)((bl * 8 + hh) * 128 + dv)) * 4096 + sp) = o2;
;           }
;       }
;     return;
	v_pk_mul_f32 v[36:37], v[36:37], v[52:53]
	v_pk_mul_f32 v[34:35], v[34:35], v[50:51]
	v_lshlrev_b32_e32 v0, 1, v55
	v_cvt_pk_bf16_f32 v202, v34, v35
	v_cvt_pk_bf16_f32 v203, v36, v37
	v_or_b32_e32 v36, 16, v54
	v_ashrrev_i32_e32 v37, 31, v36
	v_lshl_add_u64 v[56:57], s[4:5], 0, v[0:1]
	v_lshlrev_b64 v[36:37], 13, v[36:37]
	v_pk_mul_f32 v[44:45], v[44:45], v[52:53]
	v_pk_mul_f32 v[42:43], v[42:43], v[50:51]
	v_ashrrev_i32_e32 v55, 31, v54
	v_lshl_add_u64 v[36:37], v[56:57], 0, v[36:37]
	v_cvt_pk_bf16_f32 v206, v42, v43
	v_cvt_pk_bf16_f32 v207, v44, v45
	v_lshlrev_b64 v[44:45], 13, v[54:55]
	v_lshl_add_u64 v[198:199], v[36:37], 0, v[196:197]
	s_nop 1
	v_permlane32_swap_b32_e32 v200, v202
	v_permlane32_swap_b32_e32 v201, v203
	global_store_dwordx4 v[198:199], v[200:203], off
	v_or_b32_e32 v34, 0x80, v54
	v_lshl_add_u64 v[44:45], v[56:57], 0, v[44:45]
	v_ashrrev_i32_e32 v35, 31, v34
	v_lshl_add_u64 v[198:199], v[44:45], 0, v[196:197]
	s_nop 1
	v_permlane32_swap_b32_e32 v204, v206
	v_permlane32_swap_b32_e32 v205, v207
	global_store_dwordx4 v[198:199], v[204:207], off
	v_pk_mul_f32 v[36:37], v[48:49], v[52:53]
	v_pk_mul_f32 v[42:43], v[46:47], v[50:51]
	v_lshlrev_b64 v[34:35], 13, v[34:35]
	v_cvt_pk_bf16_f32 v210, v42, v43
	v_cvt_pk_bf16_f32 v211, v36, v37
	v_lshl_add_u64 v[34:35], v[56:57], 0, v[34:35]
	v_lshl_add_u64 v[198:199], v[34:35], 0, v[196:197]
	s_nop 1
	v_permlane32_swap_b32_e32 v208, v210
	v_permlane32_swap_b32_e32 v209, v211
	global_store_dwordx4 v[198:199], v[208:211], off
	v_pk_mul_f32 v[34:35], v[40:41], v[52:53]
	v_pk_mul_f32 v[36:37], v[38:39], v[50:51]
	v_add_u32_e32 v0, 0xa0, v132
	v_cvt_pk_bf16_f32 v214, v36, v37
	v_cvt_pk_bf16_f32 v215, v34, v35
	v_or_b32_e32 v34, 0x90, v54
	v_ashrrev_i32_e32 v35, 31, v34
	v_lshlrev_b64 v[34:35], 13, v[34:35]
	v_lshl_add_u64 v[34:35], v[56:57], 0, v[34:35]
	v_lshl_add_u64 v[198:199], v[34:35], 0, v[196:197]
	s_nop 1
	v_permlane32_swap_b32_e32 v212, v214
	v_permlane32_swap_b32_e32 v213, v215
	global_store_dwordx4 v[198:199], v[212:215], off
	ds_read_b128 v[34:37], v133 offset:640
	v_and_or_b32 v39, v0, s8, v130
	v_ashrrev_i32_e32 v0, 2, v0
	v_and_b32_e32 v0, 0xfffffc00, v0
	v_add_u32_e32 v38, v0, v131
	s_waitcnt lgkmcnt(0)
	v_pk_mul_f32 v[20:21], v[20:21], v[36:37]
	v_pk_mul_f32 v[18:19], v[18:19], v[34:35]
	v_lshlrev_b32_e32 v0, 1, v39
	v_cvt_pk_bf16_f32 v200, v18, v19
	v_cvt_pk_bf16_f32 v201, v20, v21
	v_or_b32_e32 v20, 16, v38
	v_ashrrev_i32_e32 v21, 31, v20
	v_lshl_add_u64 v[40:41], s[4:5], 0, v[0:1]
	v_lshlrev_b64 v[20:21], 13, v[20:21]
	v_pk_mul_f32 v[28:29], v[28:29], v[36:37]
	v_pk_mul_f32 v[26:27], v[26:27], v[34:35]
	v_ashrrev_i32_e32 v39, 31, v38
	v_lshl_add_u64 v[20:21], v[40:41], 0, v[20:21]
	v_cvt_pk_bf16_f32 v204, v26, v27
	v_cvt_pk_bf16_f32 v205, v28, v29
	v_lshlrev_b64 v[28:29], 13, v[38:39]
	s_nop 0
	v_or_b32_e32 v18, 0x80, v38
	v_lshl_add_u64 v[28:29], v[40:41], 0, v[28:29]
	v_ashrrev_i32_e32 v19, 31, v18
	s_nop 0
	v_pk_mul_f32 v[20:21], v[32:33], v[36:37]
	v_pk_mul_f32 v[26:27], v[30:31], v[34:35]
	v_lshlrev_b64 v[18:19], 13, v[18:19]
	v_cvt_pk_bf16_f32 v208, v26, v27
	v_cvt_pk_bf16_f32 v209, v20, v21
	v_lshl_add_u64 v[18:19], v[40:41], 0, v[18:19]
	s_nop 0
	v_pk_mul_f32 v[18:19], v[24:25], v[36:37]
	v_pk_mul_f32 v[20:21], v[22:23], v[34:35]
	v_add_u32_e32 v0, 0xb0, v132
	v_cvt_pk_bf16_f32 v212, v20, v21
	v_cvt_pk_bf16_f32 v213, v18, v19
	v_or_b32_e32 v18, 0x90, v38
	v_ashrrev_i32_e32 v19, 31, v18
	v_lshlrev_b64 v[18:19], 13, v[18:19]
	v_lshl_add_u64 v[18:19], v[40:41], 0, v[18:19]
	s_nop 0
	ds_read_b128 v[18:21], v133 offset:704
	v_and_or_b32 v23, v0, s2, v130
	v_ashrrev_i32_e32 v0, 2, v0
	v_and_b32_e32 v0, 0xfffffc00, v0
	v_add_u32_e32 v22, v0, v131
	s_waitcnt lgkmcnt(0)
	v_pk_mul_f32 v[8:9], v[8:9], v[20:21]
	v_pk_mul_f32 v[6:7], v[6:7], v[18:19]
	v_lshlrev_b32_e32 v0, 1, v23
	v_cvt_pk_bf16_f32 v202, v6, v7
	v_cvt_pk_bf16_f32 v203, v8, v9
	v_or_b32_e32 v8, 16, v22
	v_ashrrev_i32_e32 v9, 31, v8
	v_lshl_add_u64 v[24:25], s[4:5], 0, v[0:1]
	v_lshlrev_b64 v[8:9], 13, v[8:9]
	v_lshl_add_u64 v[8:9], v[24:25], 0, v[8:9]
	v_pk_mul_f32 v[4:5], v[4:5], v[20:21]
	v_pk_mul_f32 v[2:3], v[2:3], v[18:19]
	v_lshl_add_u64 v[198:199], v[8:9], 0, v[196:197]
	s_nop 1
	v_permlane32_swap_b32_e32 v200, v202
	v_permlane32_swap_b32_e32 v201, v203
	global_store_dwordx4 v[198:199], v[200:203], off
	v_or_b32_e32 v6, 0x80, v22
	v_cvt_pk_bf16_f32 v214, v2, v3
	v_cvt_pk_bf16_f32 v215, v4, v5
	v_or_b32_e32 v4, 0x90, v22
	v_pk_mul_f32 v[16:17], v[16:17], v[20:21]
	v_pk_mul_f32 v[14:15], v[14:15], v[18:19]
	v_ashrrev_i32_e32 v23, 31, v22
	v_ashrrev_i32_e32 v7, 31, v6
	v_ashrrev_i32_e32 v5, 31, v4
	v_cvt_pk_bf16_f32 v206, v14, v15
	v_cvt_pk_bf16_f32 v207, v16, v17
	v_lshlrev_b64 v[16:17], 13, v[22:23]
	v_pk_mul_f32 v[8:9], v[12:13], v[20:21]
	v_pk_mul_f32 v[10:11], v[10:11], v[18:19]
	v_lshlrev_b64 v[6:7], 13, v[6:7]
	v_lshlrev_b64 v[4:5], 13, v[4:5]
	v_lshl_add_u64 v[16:17], v[24:25], 0, v[16:17]
	v_cvt_pk_bf16_f32 v210, v10, v11
	v_cvt_pk_bf16_f32 v211, v8, v9
	v_lshl_add_u64 v[6:7], v[24:25], 0, v[6:7]
	v_lshl_add_u64 v[4:5], v[24:25], 0, v[4:5]
	v_lshl_add_u64 v[198:199], v[16:17], 0, v[196:197]
	s_nop 1
	v_permlane32_swap_b32_e32 v204, v206
	v_permlane32_swap_b32_e32 v205, v207
	global_store_dwordx4 v[198:199], v[204:207], off
	v_lshl_add_u64 v[198:199], v[6:7], 0, v[196:197]
	s_nop 1
	v_permlane32_swap_b32_e32 v208, v210
	v_permlane32_swap_b32_e32 v209, v211
	global_store_dwordx4 v[198:199], v[208:211], off
	v_lshl_add_u64 v[198:199], v[4:5], 0, v[196:197]
	s_nop 1
	v_permlane32_swap_b32_e32 v212, v214
	v_permlane32_swap_b32_e32 v213, v215
	global_store_dwordx4 v[198:199], v[212:215], off

; DI u32 pack2(float a, float b) { f2_t v = {a, b}; bf2_t r = __builtin_convertvector(v, bf2_t); return __builtin_bit_cast(u32, r); }
; DI float bflo(u32 v) { return __uint_as_float(v << 16); }
; DI float bfhi(u32 v) { return __uint_as_float(v & 0xffff0000u); }
; DI void branch_tile8(const Params& P, const WsPtrs& W, int layer, int mt, int nt, unsigned char* smem) {
;     ...
;   for (int jb = 0; jb < 4; ++jb) {
;     f32x4v acc[2][2][4][2];
;     gemm8(W.W + (size_t)layer * W_LAYER + W_BR + (size_t)jb * 1048576, 1024, W.YMIX + jb * 1024, 4096, 1024, n0, m0, acc, smem);
;     ...
;             if (jb > 0) { const u32x2 pv = *(const u32x2*)(mp + f); v0 += bflo(pv.x); v1 += bfhi(pv.x); v2 += bflo(pv.y); v3 += bfhi(pv.y); }
;             u32x2 o2; o2.x = pack2(v0, v1); o2.y = pack2(v2, v3);
;             *(u32x2*)(mp + f) = o2;
.LBB0_703:
	s_add_i32 s84, s84, 1
	s_add_u32 s78, s78, 0x800
	s_addc_u32 s79, s79, 0
	s_add_u32 s80, s80, 0x200000
	s_addc_u32 s81, s81, 0
	s_cmp_lg_u32 s84, 4
	s_cbranch_scc0 .LBB0_701

; DI u32 pack2(float a, float b) { f2_t v = {a, b}; bf2_t r = __builtin_convertvector(v, bf2_t); return __builtin_bit_cast(u32, r); }
; DI float bflo(u32 v) { return __uint_as_float(v << 16); }
; DI float bfhi(u32 v) { return __uint_as_float(v & 0xffff0000u); }
; DI float sigmoidf_(float x) { return __builtin_amdgcn_rcpf(1.f + __builtin_amdgcn_exp2f(-LOG2E * x)); }
; DI void branch_tile8(const Params& P, const WsPtrs& W, int layer, int mt, int nt, unsigned char* smem) {
;     ...
;     const float* gbp = P.in[I_GATEB] + layer * 4096 + jb * 1024;
; #pragma unroll
;     for (int bj = 0; bj < 2; ++bj)
; #pragma unroll
;       for (int n = 0; n < 2; ++n) {
;         const int row = m0 + bj * 128 + wc * 32 + n * 16 + fr;
;         const u16* gp = W.Y + (size_t)row * LDY + O_GT + jb * 1024;
;         u16* mp = W.MERGED + (size_t)row * 1024;
; #pragma unroll
;         for (int ai = 0; ai < 2; ++ai)
; #pragma unroll
;           for (int m = 0; m < 4; ++m) {
;             const int f = n0 + ai * 128 + wr * 64 + m * 16 + fq * 4;
;             const u32x2 gv = *(const u32x2*)(gp + f);
;             const f32x4 b4 = *(const f32x4*)(gbp + f);
;             f32x4v a = acc[ai][bj][m][n];
;             float v0 = sigmoidf_(bflo(gv.x) + b4.x) * a.x, v1 = sigmoidf_(bfhi(gv.x) + b4.y) * a.y;
;             float v2 = sigmoidf_(bflo(gv.y) + b4.z) * a.z, v3 = sigmoidf_(bfhi(gv.y) + b4.w) * a.w;
;             if (jb > 0) { const u32x2 pv = *(const u32x2*)(mp + f); v0 += bflo(pv.x); v1 += bfhi(pv.x); v2 += bflo(pv.y); v3 += bfhi(pv.y); }
;             u32x2 o2; o2.x = pack2(v0, v1); o2.y = pack2(v2, v3);
;             *(u32x2*)(mp + f) = o2;
;           }
;       }
.LBB0_710:
	s_or_b64 exec, exec, s[6:7]
	v_mbcnt_lo_u32_b32 v136, -1, 0
	v_mbcnt_hi_u32_b32 v136, -1, v136
	v_bfe_u32 v136, v136, 4, 1
	v_mul_u32_u24_e32 v136, 24, v136
	v_mov_b32_e32 v137, 0
	v_mov_b32_e32 v0, v250
	s_lshl_b64 s[6:7], s[2:3], 2
	v_lshrrev_b32_e32 v131, 1, v0
	v_and_b32_e32 v130, 15, v0
	v_and_b32_e32 v131, 0x60, v131
	v_or3_b32 v134, v130, v131, s12
	v_ashrrev_i32_e32 v130, 2, v0
	s_add_u32 s6, s26, s6
	v_and_b32_e32 v130, 0xffffffc0, v130
	s_addc_u32 s7, s27, s7
	v_add_u32_e32 v130, s14, v130
	v_lshrrev_b32_e32 v0, 2, v0
	v_and_or_b32 v132, v0, 12, v130
	s_lshl_b32 s2, s2, 1
	v_ashrrev_i32_e32 v133, 31, v132
	v_ashrrev_i32_e32 v135, 31, v134
	s_mov_b64 s[20:21], 0x4000
	v_lshl_add_u64 v[130:131], v[132:133], 2, s[6:7]
	global_load_dwordx4 v[168:171], v[130:131], off
	global_load_dwordx4 v[172:175], v[130:131], off offset:64
	global_load_dwordx4 v[176:179], v[130:131], off offset:128
	global_load_dwordx4 v[180:183], v[130:131], off offset:192
	global_load_dwordx4 v[184:187], v[130:131], off offset:512
	global_load_dwordx4 v[188:191], v[130:131], off offset:576
	global_load_dwordx4 v[192:195], v[130:131], off offset:640
	global_load_dwordx4 v[196:199], v[130:131], off offset:704
	s_cmp_eq_u32 s84, 0
	s_cbranch_scc1 .Lbre_first
	v_mov_b64_e32 v[158:159], s[8:9]
	v_lshlrev_b64 v[160:161], 11, v[134:135]
	v_mad_i64_i32 v[158:159], s[22:23], v134, s33, v[158:159]
	v_lshl_add_u64 v[160:161], s[10:11], 0, v[160:161]
	v_lshl_add_u64 v[158:159], v[158:159], 0, s[2:3]
	v_lshl_add_u64 v[160:161], v[132:133], 1, v[160:161]
	v_lshl_add_u64 v[158:159], v[132:133], 1, v[158:159]
	v_lshl_add_u64 v[158:159], v[158:159], 0, s[20:21]
	global_load_dwordx2 v[162:163], v[158:159], off
	global_load_dwordx2 v[164:165], v[160:161], off
	global_load_dwordx2 v[166:167], v[158:159], off offset:32
	global_load_dwordx2 v[200:201], v[160:161], off offset:32
	global_load_dwordx2 v[202:203], v[158:159], off offset:64
	global_load_dwordx2 v[204:205], v[160:161], off offset:64
	global_load_dwordx2 v[206:207], v[158:159], off offset:96
	global_load_dwordx2 v[208:209], v[160:161], off offset:96
	global_load_dwordx2 v[210:211], v[158:159], off offset:256
	global_load_dwordx2 v[212:213], v[160:161], off offset:256
	global_load_dwordx2 v[214:215], v[158:159], off offset:288
	global_load_dwordx2 v[216:217], v[160:161], off offset:288
	global_load_dwordx2 v[218:219], v[158:159], off offset:320
	global_load_dwordx2 v[220:221], v[160:161], off offset:320
	global_load_dwordx2 v[222:223], v[158:159], off offset:352
	global_load_dwordx2 v[224:225], v[160:161], off offset:352
	v_or_b32_e32 v156, 0x10, v134
	v_ashrrev_i32_e32 v157, 31, v156
	v_mov_b64_e32 v[226:227], s[8:9]
	v_lshlrev_b64 v[230:231], 11, v[156:157]
	v_mad_i64_i32 v[226:227], s[22:23], v156, s33, v[226:227]
	v_lshl_add_u64 v[230:231], s[10:11], 0, v[230:231]
	v_lshl_add_u64 v[226:227], v[226:227], 0, s[2:3]
	v_lshl_add_u64 v[230:231], v[132:133], 1, v[230:231]
	v_lshl_add_u64 v[226:227], v[132:133], 1, v[226:227]
	v_lshl_add_u64 v[226:227], v[226:227], 0, s[20:21]
	global_load_dwordx2 v[232:233], v[226:227], off
	global_load_dwordx2 v[238:239], v[230:231], off
	s_waitcnt vmcnt(16)
	v_lshlrev_b32_e32 v138, 16, v162
	v_and_b32_e32 v139, 0xffff0000, v162
	v_lshlrev_b32_e32 v140, 16, v163
	v_and_b32_e32 v141, 0xffff0000, v163
	v_add_f32_e32 v138, v168, v138
	v_add_f32_e32 v139, v169, v139
	v_add_f32_e32 v140, v170, v140
	v_add_f32_e32 v141, v171, v141
	v_mul_f32_e32 v138, 0xbfb8aa3b, v138
	v_mul_f32_e32 v139, 0xbfb8aa3b, v139
	v_mul_f32_e32 v140, 0xbfb8aa3b, v140
	v_mul_f32_e32 v141, 0xbfb8aa3b, v141
	v_exp_f32_e32 v138, v138
	v_exp_f32_e32 v139, v139
	v_exp_f32_e32 v140, v140
	v_exp_f32_e32 v141, v141
	v_add_f32_e32 v138, 1.0, v138
	v_add_f32_e32 v139, 1.0, v139
	v_add_f32_e32 v140, 1.0, v140
	v_add_f32_e32 v141, 1.0, v141
	v_rcp_f32_e32 v138, v138
	v_rcp_f32_e32 v139, v139
	v_rcp_f32_e32 v140, v140
	v_rcp_f32_e32 v141, v141
	v_lshlrev_b32_e32 v142, 16, v164
	v_and_b32_e32 v143, 0xffff0000, v164
	v_lshlrev_b32_e32 v144, 16, v165
	v_and_b32_e32 v145, 0xffff0000, v165
	v_pk_mul_f32 v[126:127], v[126:127], v[138:139]
	v_pk_mul_f32 v[128:129], v[128:129], v[140:141]
	v_pk_add_f32 v[126:127], v[126:127], v[142:143]
	v_pk_add_f32 v[128:129], v[128:129], v[144:145]
	v_cvt_pk_bf16_f32 v146, v126, v127
	v_cvt_pk_bf16_f32 v147, v128, v129
	global_load_dwordx2 v[158:159], v[226:227], off offset:32
	global_load_dwordx2 v[162:163], v[230:231], off offset:32
	s_waitcnt vmcnt(16)
	v_lshlrev_b32_e32 v138, 16, v166
	v_and_b32_e32 v139, 0xffff0000, v166
	v_lshlrev_b32_e32 v140, 16, v167
	v_and_b32_e32 v141, 0xffff0000, v167
	v_add_f32_e32 v138, v172, v138
	v_add_f32_e32 v139, v173, v139
	v_add_f32_e32 v140, v174, v140
	v_add_f32_e32 v141, v175, v141
	v_mul_f32_e32 v138, 0xbfb8aa3b, v138
	v_mul_f32_e32 v139, 0xbfb8aa3b, v139
	v_mul_f32_e32 v140, 0xbfb8aa3b, v140
	v_mul_f32_e32 v141, 0xbfb8aa3b, v141
	v_exp_f32_e32 v138, v138
	v_exp_f32_e32 v139, v139
	v_exp_f32_e32 v140, v140
	v_exp_f32_e32 v141, v141
	v_add_f32_e32 v138, 1.0, v138
	v_add_f32_e32 v139, 1.0, v139
	v_add_f32_e32 v140, 1.0, v140
	v_add_f32_e32 v141, 1.0, v141
	v_rcp_f32_e32 v138, v138
	v_rcp_f32_e32 v139, v139
	v_rcp_f32_e32 v140, v140
	v_rcp_f32_e32 v141, v141
	v_lshlrev_b32_e32 v142, 16, v200
	v_and_b32_e32 v143, 0xffff0000, v200
	v_lshlrev_b32_e32 v144, 16, v201
	v_and_b32_e32 v145, 0xffff0000, v201
	v_pk_mul_f32 v[122:123], v[122:123], v[138:139]
	v_pk_mul_f32 v[124:125], v[124:125], v[140:141]
	v_pk_add_f32 v[122:123], v[122:123], v[142:143]
	v_pk_add_f32 v[124:125], v[124:125], v[144:145]
	v_cvt_pk_bf16_f32 v148, v122, v123
	v_cvt_pk_bf16_f32 v149, v124, v125
	v_lshl_add_u64 v[154:155], v[160:161], 0, v[136:137]
	s_nop 1
	v_permlane16_swap_b32_e32 v146, v148
	v_permlane16_swap_b32_e32 v147, v149
	global_store_dwordx4 v[154:155], v[146:149], off
	global_load_dwordx2 v[164:165], v[226:227], off offset:64
	global_load_dwordx2 v[126:127], v[230:231], off offset:64
	s_waitcnt vmcnt(17)
; DI u32 pack2(float a, float b) { f2_t v = {a, b}; bf2_t r = __builtin_convertvector(v, bf2_t); return __builtin_bit_cast(u32, r); }
; DI float bflo(u32 v) { return __uint_as_float(v << 16); }
; DI float bfhi(u32 v) { return __uint_as_float(v & 0xffff0000u); }
; DI float sigmoidf_(float x) { return __builtin_amdgcn_rcpf(1.f + __builtin_amdgcn_exp2f(-LOG2E * x)); }
; DI void branch_tile8(const Params& P, const WsPtrs& W, int layer, int mt, int nt, unsigned char* smem) {
;     ...
;     const float* gbp = P.in[I_GATEB] + layer * 4096 + jb * 1024;
; #pragma unroll
;     for (int bj = 0; bj < 2; ++bj)
; #pragma unroll
;       for (int n = 0; n < 2; ++n) {
;         const int row = m0 + bj * 128 + wc * 32 + n * 16 + fr;
;         const u16* gp = W.Y + (size_t)row * LDY + O_GT + jb * 1024;
;         u16* mp = W.MERGED + (size_t)row * 1024;
; #pragma unroll
;         for (int ai = 0; ai < 2; ++ai)
; #pragma unroll
;           for (int m = 0; m < 4; ++m) {
;             const int f = n0 + ai * 128 + wr * 64 + m * 16 + fq * 4;
;             const u32x2 gv = *(const u32x2*)(gp + f);
;             const f32x4 b4 = *(const f32x4*)(gbp + f);
;             f32x4v a = acc[ai][bj][m][n];
;             float v0 = sigmoidf_(bflo(gv.x) + b4.x) * a.x, v1 = sigmoidf_(bfhi(gv.x) + b4.y) * a.y;
;             float v2 = sigmoidf_(bflo(gv.y) + b4.z) * a.z, v3 = sigmoidf_(bfhi(gv.y) + b4.w) * a.w;
;             if (jb > 0) { const u32x2 pv = *(const u32x2*)(mp + f); v0 += bflo(pv.x); v1 += bfhi(pv.x); v2 += bflo(pv.y); v3 += bfhi(pv.y); }
;             u32x2 o2; o2.x = pack2(v0, v1); o2.y = pack2(v2, v3);
;             *(u32x2*)(mp + f) = o2;
;           }
;       }
	v_lshlrev_b32_e32 v138, 16, v202
	v_and_b32_e32 v139, 0xffff0000, v202
	v_lshlrev_b32_e32 v140, 16, v203
	v_and_b32_e32 v141, 0xffff0000, v203
	v_add_f32_e32 v138, v176, v138
	v_add_f32_e32 v139, v177, v139
	v_add_f32_e32 v140, v178, v140
	v_add_f32_e32 v141, v179, v141
	v_mul_f32_e32 v138, 0xbfb8aa3b, v138
	v_mul_f32_e32 v139, 0xbfb8aa3b, v139
	v_mul_f32_e32 v140, 0xbfb8aa3b, v140
	v_mul_f32_e32 v141, 0xbfb8aa3b, v141
	v_exp_f32_e32 v138, v138
	v_exp_f32_e32 v139, v139
	v_exp_f32_e32 v140, v140
	v_exp_f32_e32 v141, v141
	v_add_f32_e32 v138, 1.0, v138
	v_add_f32_e32 v139, 1.0, v139
	v_add_f32_e32 v140, 1.0, v140
	v_add_f32_e32 v141, 1.0, v141
	v_rcp_f32_e32 v138, v138
	v_rcp_f32_e32 v139, v139
	v_rcp_f32_e32 v140, v140
	v_rcp_f32_e32 v141, v141
	v_lshlrev_b32_e32 v142, 16, v204
	v_and_b32_e32 v143, 0xffff0000, v204
	v_lshlrev_b32_e32 v144, 16, v205
	v_and_b32_e32 v145, 0xffff0000, v205
	v_pk_mul_f32 v[118:119], v[118:119], v[138:139]
	v_pk_mul_f32 v[120:121], v[120:121], v[140:141]
	v_pk_add_f32 v[118:119], v[118:119], v[142:143]
	v_pk_add_f32 v[120:121], v[120:121], v[144:145]
	v_cvt_pk_bf16_f32 v150, v118, v119
	v_cvt_pk_bf16_f32 v151, v120, v121
	global_load_dwordx2 v[128:129], v[226:227], off offset:96
	global_load_dwordx2 v[166:167], v[230:231], off offset:96
	s_waitcnt vmcnt(17)
	v_lshlrev_b32_e32 v138, 16, v206
	v_and_b32_e32 v139, 0xffff0000, v206
	v_lshlrev_b32_e32 v140, 16, v207
	v_and_b32_e32 v141, 0xffff0000, v207
	v_add_f32_e32 v138, v180, v138
	v_add_f32_e32 v139, v181, v139
	v_add_f32_e32 v140, v182, v140
	v_add_f32_e32 v141, v183, v141
	v_mul_f32_e32 v138, 0xbfb8aa3b, v138
	v_mul_f32_e32 v139, 0xbfb8aa3b, v139
	v_mul_f32_e32 v140, 0xbfb8aa3b, v140
	v_mul_f32_e32 v141, 0xbfb8aa3b, v141
	v_exp_f32_e32 v138, v138
	v_exp_f32_e32 v139, v139
	v_exp_f32_e32 v140, v140
	v_exp_f32_e32 v141, v141
	v_add_f32_e32 v138, 1.0, v138
	v_add_f32_e32 v139, 1.0, v139
	v_add_f32_e32 v140, 1.0, v140
	v_add_f32_e32 v141, 1.0, v141
	v_rcp_f32_e32 v138, v138
	v_rcp_f32_e32 v139, v139
	v_rcp_f32_e32 v140, v140
	v_rcp_f32_e32 v141, v141
	v_lshlrev_b32_e32 v142, 16, v208
	v_and_b32_e32 v143, 0xffff0000, v208
	v_lshlrev_b32_e32 v144, 16, v209
	v_and_b32_e32 v145, 0xffff0000, v209
	v_pk_mul_f32 v[114:115], v[114:115], v[138:139]
	v_pk_mul_f32 v[116:117], v[116:117], v[140:141]
	v_pk_add_f32 v[114:115], v[114:115], v[142:143]
	v_pk_add_f32 v[116:117], v[116:117], v[144:145]
	v_cvt_pk_bf16_f32 v152, v114, v115
	v_cvt_pk_bf16_f32 v153, v116, v117
	v_lshl_add_u64 v[154:155], v[160:161], 0, v[136:137]
	s_nop 1
	v_permlane16_swap_b32_e32 v150, v152
	v_permlane16_swap_b32_e32 v151, v153
	global_store_dwordx4 v[154:155], v[150:153], off offset:64
	global_load_dwordx2 v[200:201], v[226:227], off offset:256
	global_load_dwordx2 v[122:123], v[230:231], off offset:256
	s_waitcnt vmcnt(18)
	v_lshlrev_b32_e32 v138, 16, v210
	v_and_b32_e32 v139, 0xffff0000, v210
	v_lshlrev_b32_e32 v140, 16, v211
	v_and_b32_e32 v141, 0xffff0000, v211
	v_add_f32_e32 v138, v184, v138
	v_add_f32_e32 v139, v185, v139
	v_add_f32_e32 v140, v186, v140
	v_add_f32_e32 v141, v187, v141
	v_mul_f32_e32 v138, 0xbfb8aa3b, v138
	v_mul_f32_e32 v139, 0xbfb8aa3b, v139
	v_mul_f32_e32 v140, 0xbfb8aa3b, v140
	v_mul_f32_e32 v141, 0xbfb8aa3b, v141
	v_exp_f32_e32 v138, v138
	v_exp_f32_e32 v139, v139
	v_exp_f32_e32 v140, v140
	v_exp_f32_e32 v141, v141
	v_add_f32_e32 v138, 1.0, v138
	v_add_f32_e32 v139, 1.0, v139
	v_add_f32_e32 v140, 1.0, v140
	v_add_f32_e32 v141, 1.0, v141
	v_rcp_f32_e32 v138, v138
	v_rcp_f32_e32 v139, v139
	v_rcp_f32_e32 v140, v140
	v_rcp_f32_e32 v141, v141
	v_lshlrev_b32_e32 v142, 16, v212
	v_and_b32_e32 v143, 0xffff0000, v212
	v_lshlrev_b32_e32 v144, 16, v213
	v_and_b32_e32 v145, 0xffff0000, v213
	v_pk_mul_f32 v[110:111], v[110:111], v[138:139]
	v_pk_mul_f32 v[112:113], v[112:113], v[140:141]
	v_pk_add_f32 v[110:111], v[110:111], v[142:143]
	v_pk_add_f32 v[112:113], v[112:113], v[144:145]
	v_cvt_pk_bf16_f32 v146, v110, v111
	v_cvt_pk_bf16_f32 v147, v112, v113
	global_load_dwordx2 v[124:125], v[226:227], off offset:288
	global_load_dwordx2 v[202:203], v[230:231], off offset:288
	s_waitcnt vmcnt(18)
	v_lshlrev_b32_e32 v138, 16, v214
	v_and_b32_e32 v139, 0xffff0000, v214
	v_lshlrev_b32_e32 v140, 16, v215
	v_and_b32_e32 v141, 0xffff0000, v215
	v_add_f32_e32 v138, v188, v138
	v_add_f32_e32 v139, v189, v139
	v_add_f32_e32 v140, v190, v140
	v_add_f32_e32 v141, v191, v141
	v_mul_f32_e32 v138, 0xbfb8aa3b, v138
	v_mul_f32_e32 v139, 0xbfb8aa3b, v139
	v_mul_f32_e32 v140, 0xbfb8aa3b, v140
	v_mul_f32_e32 v141, 0xbfb8aa3b, v141
	v_exp_f32_e32 v138, v138
	v_exp_f32_e32 v139, v139
	v_exp_f32_e32 v140, v140
	v_exp_f32_e32 v141, v141
	v_add_f32_e32 v138, 1.0, v138
	v_add_f32_e32 v139, 1.0, v139
	v_add_f32_e32 v140, 1.0, v140
	v_add_f32_e32 v141, 1.0, v141
	v_rcp_f32_e32 v138, v138
	v_rcp_f32_e32 v139, v139
	v_rcp_f32_e32 v140, v140
	v_rcp_f32_e32 v141, v141
	v_lshlrev_b32_e32 v142, 16, v216
	v_and_b32_e32 v143, 0xffff0000, v216
	v_lshlrev_b32_e32 v144, 16, v217
	v_and_b32_e32 v145, 0xffff0000, v217
	v_pk_mul_f32 v[106:107], v[106:107], v[138:139]
	v_pk_mul_f32 v[108:109], v[108:109], v[140:141]
	v_pk_add_f32 v[106:107], v[106:107], v[142:143]
	v_pk_add_f32 v[108:109], v[108:109], v[144:145]
	v_cvt_pk_bf16_f32 v148, v106, v107
	v_cvt_pk_bf16_f32 v149, v108, v109
	v_lshl_add_u64 v[154:155], v[160:161], 0, v[136:137]
	s_nop 1
	v_permlane16_swap_b32_e32 v146, v148
	v_permlane16_swap_b32_e32 v147, v149
	global_store_dwordx4 v[154:155], v[146:149], off offset:256
	global_load_dwordx2 v[204:205], v[226:227], off offset:320
	global_load_dwordx2 v[118:119], v[230:231], off offset:320
	s_waitcnt vmcnt(19)
; DI u32 pack2(float a, float b) { f2_t v = {a, b}; bf2_t r = __builtin_convertvector(v, bf2_t); return __builtin_bit_cast(u32, r); }
; DI float bflo(u32 v) { return __uint_as_float(v << 16); }
; DI float bfhi(u32 v) { return __uint_as_float(v & 0xffff0000u); }
; DI float sigmoidf_(float x) { return __builtin_amdgcn_rcpf(1.f + __builtin_amdgcn_exp2f(-LOG2E * x)); }
; DI void branch_tile8(const Params& P, const WsPtrs& W, int layer, int mt, int nt, unsigned char* smem) {
;     ...
;     const float* gbp = P.in[I_GATEB] + layer * 4096 + jb * 1024;
; #pragma unroll
;     for (int bj = 0; bj < 2; ++bj)
; #pragma unroll
;       for (int n = 0; n < 2; ++n) {
;         const int row = m0 + bj * 128 + wc * 32 + n * 16 + fr;
;         const u16* gp = W.Y + (size_t)row * LDY + O_GT + jb * 1024;
;         u16* mp = W.MERGED + (size_t)row * 1024;
; #pragma unroll
;         for (int ai = 0; ai < 2; ++ai)
; #pragma unroll
;           for (int m = 0; m < 4; ++m) {
;             const int f = n0 + ai * 128 + wr * 64 + m * 16 + fq * 4;
;             const u32x2 gv = *(const u32x2*)(gp + f);
;             const f32x4 b4 = *(const f32x4*)(gbp + f);
;             f32x4v a = acc[ai][bj][m][n];
;             float v0 = sigmoidf_(bflo(gv.x) + b4.x) * a.x, v1 = sigmoidf_(bfhi(gv.x) + b4.y) * a.y;
;             float v2 = sigmoidf_(bflo(gv.y) + b4.z) * a.z, v3 = sigmoidf_(bfhi(gv.y) + b4.w) * a.w;
;             if (jb > 0) { const u32x2 pv = *(const u32x2*)(mp + f); v0 += bflo(pv.x); v1 += bfhi(pv.x); v2 += bflo(pv.y); v3 += bfhi(pv.y); }
;             u32x2 o2; o2.x = pack2(v0, v1); o2.y = pack2(v2, v3);
;             *(u32x2*)(mp + f) = o2;
;           }
;       }
	v_lshlrev_b32_e32 v138, 16, v218
	v_and_b32_e32 v139, 0xffff0000, v218
	v_lshlrev_b32_e32 v140, 16, v219
	v_and_b32_e32 v141, 0xffff0000, v219
	v_add_f32_e32 v138, v192, v138
	v_add_f32_e32 v139, v193, v139
	v_add_f32_e32 v140, v194, v140
	v_add_f32_e32 v141, v195, v141
	v_mul_f32_e32 v138, 0xbfb8aa3b, v138
	v_mul_f32_e32 v139, 0xbfb8aa3b, v139
	v_mul_f32_e32 v140, 0xbfb8aa3b, v140
	v_mul_f32_e32 v141, 0xbfb8aa3b, v141
	v_exp_f32_e32 v138, v138
	v_exp_f32_e32 v139, v139
	v_exp_f32_e32 v140, v140
	v_exp_f32_e32 v141, v141
	v_add_f32_e32 v138, 1.0, v138
	v_add_f32_e32 v139, 1.0, v139
	v_add_f32_e32 v140, 1.0, v140
	v_add_f32_e32 v141, 1.0, v141
	v_rcp_f32_e32 v138, v138
	v_rcp_f32_e32 v139, v139
	v_rcp_f32_e32 v140, v140
	v_rcp_f32_e32 v141, v141
	v_lshlrev_b32_e32 v142, 16, v220
	v_and_b32_e32 v143, 0xffff0000, v220
	v_lshlrev_b32_e32 v144, 16, v221
	v_and_b32_e32 v145, 0xffff0000, v221
	v_pk_mul_f32 v[102:103], v[102:103], v[138:139]
	v_pk_mul_f32 v[104:105], v[104:105], v[140:141]
	v_pk_add_f32 v[102:103], v[102:103], v[142:143]
	v_pk_add_f32 v[104:105], v[104:105], v[144:145]
	v_cvt_pk_bf16_f32 v150, v102, v103
	v_cvt_pk_bf16_f32 v151, v104, v105
	global_load_dwordx2 v[120:121], v[226:227], off offset:352
	global_load_dwordx2 v[206:207], v[230:231], off offset:352
	s_waitcnt vmcnt(19)
	v_lshlrev_b32_e32 v138, 16, v222
	v_and_b32_e32 v139, 0xffff0000, v222
	v_lshlrev_b32_e32 v140, 16, v223
	v_and_b32_e32 v141, 0xffff0000, v223
	v_add_f32_e32 v138, v196, v138
	v_add_f32_e32 v139, v197, v139
	v_add_f32_e32 v140, v198, v140
	v_add_f32_e32 v141, v199, v141
	v_mul_f32_e32 v138, 0xbfb8aa3b, v138
	v_mul_f32_e32 v139, 0xbfb8aa3b, v139
	v_mul_f32_e32 v140, 0xbfb8aa3b, v140
	v_mul_f32_e32 v141, 0xbfb8aa3b, v141
	v_exp_f32_e32 v138, v138
	v_exp_f32_e32 v139, v139
	v_exp_f32_e32 v140, v140
	v_exp_f32_e32 v141, v141
	v_add_f32_e32 v138, 1.0, v138
	v_add_f32_e32 v139, 1.0, v139
	v_add_f32_e32 v140, 1.0, v140
	v_add_f32_e32 v141, 1.0, v141
	v_rcp_f32_e32 v138, v138
	v_rcp_f32_e32 v139, v139
	v_rcp_f32_e32 v140, v140
	v_rcp_f32_e32 v141, v141
	v_lshlrev_b32_e32 v142, 16, v224
	v_and_b32_e32 v143, 0xffff0000, v224
	v_lshlrev_b32_e32 v144, 16, v225
	v_and_b32_e32 v145, 0xffff0000, v225
	v_pk_mul_f32 v[98:99], v[98:99], v[138:139]
	v_pk_mul_f32 v[100:101], v[100:101], v[140:141]
	v_pk_add_f32 v[98:99], v[98:99], v[142:143]
	v_pk_add_f32 v[100:101], v[100:101], v[144:145]
	v_cvt_pk_bf16_f32 v152, v98, v99
	v_cvt_pk_bf16_f32 v153, v100, v101
	v_lshl_add_u64 v[154:155], v[160:161], 0, v[136:137]
	s_nop 1
	v_permlane16_swap_b32_e32 v150, v152
	v_permlane16_swap_b32_e32 v151, v153
	global_store_dwordx4 v[154:155], v[150:153], off offset:320
	v_or_b32_e32 v156, 0x80, v134
	v_ashrrev_i32_e32 v157, 31, v156
	v_mov_b64_e32 v[208:209], s[8:9]
	v_lshlrev_b64 v[114:115], 11, v[156:157]
	v_mad_i64_i32 v[208:209], s[22:23], v156, s33, v[208:209]
	v_lshl_add_u64 v[114:115], s[10:11], 0, v[114:115]
	v_lshl_add_u64 v[208:209], v[208:209], 0, s[2:3]
	v_lshl_add_u64 v[114:115], v[132:133], 1, v[114:115]
	v_lshl_add_u64 v[208:209], v[132:133], 1, v[208:209]
	v_lshl_add_u64 v[208:209], v[208:209], 0, s[20:21]
	global_load_dwordx2 v[116:117], v[208:209], off
	global_load_dwordx2 v[210:211], v[114:115], off
	s_waitcnt vmcnt(20)
	v_lshlrev_b32_e32 v138, 16, v232
	v_and_b32_e32 v139, 0xffff0000, v232
	v_lshlrev_b32_e32 v140, 16, v233
	v_and_b32_e32 v141, 0xffff0000, v233
	v_add_f32_e32 v138, v168, v138
	v_add_f32_e32 v139, v169, v139
	v_add_f32_e32 v140, v170, v140
	v_add_f32_e32 v141, v171, v141
	v_mul_f32_e32 v138, 0xbfb8aa3b, v138
	v_mul_f32_e32 v139, 0xbfb8aa3b, v139
	v_mul_f32_e32 v140, 0xbfb8aa3b, v140
	v_mul_f32_e32 v141, 0xbfb8aa3b, v141
	v_exp_f32_e32 v138, v138
	v_exp_f32_e32 v139, v139
	v_exp_f32_e32 v140, v140
	v_exp_f32_e32 v141, v141
	v_add_f32_e32 v138, 1.0, v138
	v_add_f32_e32 v139, 1.0, v139
	v_add_f32_e32 v140, 1.0, v140
	v_add_f32_e32 v141, 1.0, v141
	v_rcp_f32_e32 v138, v138
	v_rcp_f32_e32 v139, v139
	v_rcp_f32_e32 v140, v140
	v_rcp_f32_e32 v141, v141
	v_lshlrev_b32_e32 v142, 16, v238
	v_and_b32_e32 v143, 0xffff0000, v238
	v_lshlrev_b32_e32 v144, 16, v239
	v_and_b32_e32 v145, 0xffff0000, v239
	v_pk_mul_f32 v[94:95], v[94:95], v[138:139]
	v_pk_mul_f32 v[96:97], v[96:97], v[140:141]
	v_pk_add_f32 v[94:95], v[94:95], v[142:143]
	v_pk_add_f32 v[96:97], v[96:97], v[144:145]
	v_cvt_pk_bf16_f32 v146, v94, v95
	v_cvt_pk_bf16_f32 v147, v96, v97
	global_load_dwordx2 v[212:213], v[208:209], off offset:32
	global_load_dwordx2 v[110:111], v[114:115], off offset:32
	s_waitcnt vmcnt(20)
	v_lshlrev_b32_e32 v138, 16, v158
	v_and_b32_e32 v139, 0xffff0000, v158
	v_lshlrev_b32_e32 v140, 16, v159
	v_and_b32_e32 v141, 0xffff0000, v159
	v_add_f32_e32 v138, v172, v138
	v_add_f32_e32 v139, v173, v139
	v_add_f32_e32 v140, v174, v140
	v_add_f32_e32 v141, v175, v141
	v_mul_f32_e32 v138, 0xbfb8aa3b, v138
	v_mul_f32_e32 v139, 0xbfb8aa3b, v139
	v_mul_f32_e32 v140, 0xbfb8aa3b, v140
	v_mul_f32_e32 v141, 0xbfb8aa3b, v141
	v_exp_f32_e32 v138, v138
	v_exp_f32_e32 v139, v139
	v_exp_f32_e32 v140, v140
	v_exp_f32_e32 v141, v141
	v_add_f32_e32 v138, 1.0, v138
	v_add_f32_e32 v139, 1.0, v139
	v_add_f32_e32 v140, 1.0, v140
	v_add_f32_e32 v141, 1.0, v141
	v_rcp_f32_e32 v138, v138
	v_rcp_f32_e32 v139, v139
	v_rcp_f32_e32 v140, v140
	v_rcp_f32_e32 v141, v141
	v_lshlrev_b32_e32 v142, 16, v162
	v_and_b32_e32 v143, 0xffff0000, v162
	v_lshlrev_b32_e32 v144, 16, v163
	v_and_b32_e32 v145, 0xffff0000, v163
	v_pk_mul_f32 v[90:91], v[90:91], v[138:139]
	v_pk_mul_f32 v[92:93], v[92:93], v[140:141]
	v_pk_add_f32 v[90:91], v[90:91], v[142:143]
	v_pk_add_f32 v[92:93], v[92:93], v[144:145]
	v_cvt_pk_bf16_f32 v148, v90, v91
	v_cvt_pk_bf16_f32 v149, v92, v93
	v_lshl_add_u64 v[154:155], v[230:231], 0, v[136:137]
	s_nop 1
	v_permlane16_swap_b32_e32 v146, v148
	v_permlane16_swap_b32_e32 v147, v149
	global_store_dwordx4 v[154:155], v[146:149], off
	global_load_dwordx2 v[112:113], v[208:209], off offset:64
	global_load_dwordx2 v[214:215], v[114:115], off offset:64
	s_waitcnt vmcnt(20)
; DI u32 pack2(float a, float b) { f2_t v = {a, b}; bf2_t r = __builtin_convertvector(v, bf2_t); return __builtin_bit_cast(u32, r); }
; DI float bflo(u32 v) { return __uint_as_float(v << 16); }
; DI float bfhi(u32 v) { return __uint_as_float(v & 0xffff0000u); }
; DI float sigmoidf_(float x) { return __builtin_amdgcn_rcpf(1.f + __builtin_amdgcn_exp2f(-LOG2E * x)); }
; DI void branch_tile8(const Params& P, const WsPtrs& W, int layer, int mt, int nt, unsigned char* smem) {
;     ...
;     const float* gbp = P.in[I_GATEB] + layer * 4096 + jb * 1024;
; #pragma unroll
;     for (int bj = 0; bj < 2; ++bj)
; #pragma unroll
;       for (int n = 0; n < 2; ++n) {
;         const int row = m0 + bj * 128 + wc * 32 + n * 16 + fr;
;         const u16* gp = W.Y + (size_t)row * LDY + O_GT + jb * 1024;
;         u16* mp = W.MERGED + (size_t)row * 1024;
; #pragma unroll
;         for (int ai = 0; ai < 2; ++ai)
; #pragma unroll
;           for (int m = 0; m < 4; ++m) {
;             const int f = n0 + ai * 128 + wr * 64 + m * 16 + fq * 4;
;             const u32x2 gv = *(const u32x2*)(gp + f);
;             const f32x4 b4 = *(const f32x4*)(gbp + f);
;             f32x4v a = acc[ai][bj][m][n];
;             float v0 = sigmoidf_(bflo(gv.x) + b4.x) * a.x, v1 = sigmoidf_(bfhi(gv.x) + b4.y) * a.y;
;             float v2 = sigmoidf_(bflo(gv.y) + b4.z) * a.z, v3 = sigmoidf_(bfhi(gv.y) + b4.w) * a.w;
;             if (jb > 0) { const u32x2 pv = *(const u32x2*)(mp + f); v0 += bflo(pv.x); v1 += bfhi(pv.x); v2 += bflo(pv.y); v3 += bfhi(pv.y); }
;             u32x2 o2; o2.x = pack2(v0, v1); o2.y = pack2(v2, v3);
;             *(u32x2*)(mp + f) = o2;
;           }
;       }
	v_lshlrev_b32_e32 v138, 16, v164
	v_and_b32_e32 v139, 0xffff0000, v164
	v_lshlrev_b32_e32 v140, 16, v165
	v_and_b32_e32 v141, 0xffff0000, v165
	v_add_f32_e32 v138, v176, v138
	v_add_f32_e32 v139, v177, v139
	v_add_f32_e32 v140, v178, v140
	v_add_f32_e32 v141, v179, v141
	v_mul_f32_e32 v138, 0xbfb8aa3b, v138
	v_mul_f32_e32 v139, 0xbfb8aa3b, v139
	v_mul_f32_e32 v140, 0xbfb8aa3b, v140
	v_mul_f32_e32 v141, 0xbfb8aa3b, v141
	v_exp_f32_e32 v138, v138
	v_exp_f32_e32 v139, v139
	v_exp_f32_e32 v140, v140
	v_exp_f32_e32 v141, v141
	v_add_f32_e32 v138, 1.0, v138
	v_add_f32_e32 v139, 1.0, v139
	v_add_f32_e32 v140, 1.0, v140
	v_add_f32_e32 v141, 1.0, v141
	v_rcp_f32_e32 v138, v138
	v_rcp_f32_e32 v139, v139
	v_rcp_f32_e32 v140, v140
	v_rcp_f32_e32 v141, v141
	v_lshlrev_b32_e32 v142, 16, v126
	v_and_b32_e32 v143, 0xffff0000, v126
	v_lshlrev_b32_e32 v144, 16, v127
	v_and_b32_e32 v145, 0xffff0000, v127
	v_pk_mul_f32 v[86:87], v[86:87], v[138:139]
	v_pk_mul_f32 v[88:89], v[88:89], v[140:141]
	v_pk_add_f32 v[86:87], v[86:87], v[142:143]
	v_pk_add_f32 v[88:89], v[88:89], v[144:145]
	v_cvt_pk_bf16_f32 v150, v86, v87
	v_cvt_pk_bf16_f32 v151, v88, v89
	global_load_dwordx2 v[216:217], v[208:209], off offset:96
	global_load_dwordx2 v[106:107], v[114:115], off offset:96
	s_waitcnt vmcnt(20)
	v_lshlrev_b32_e32 v138, 16, v128
	v_and_b32_e32 v139, 0xffff0000, v128
	v_lshlrev_b32_e32 v140, 16, v129
	v_and_b32_e32 v141, 0xffff0000, v129
	v_add_f32_e32 v138, v180, v138
	v_add_f32_e32 v139, v181, v139
	v_add_f32_e32 v140, v182, v140
	v_add_f32_e32 v141, v183, v141
	v_mul_f32_e32 v138, 0xbfb8aa3b, v138
	v_mul_f32_e32 v139, 0xbfb8aa3b, v139
	v_mul_f32_e32 v140, 0xbfb8aa3b, v140
	v_mul_f32_e32 v141, 0xbfb8aa3b, v141
	v_exp_f32_e32 v138, v138
	v_exp_f32_e32 v139, v139
	v_exp_f32_e32 v140, v140
	v_exp_f32_e32 v141, v141
	v_add_f32_e32 v138, 1.0, v138
	v_add_f32_e32 v139, 1.0, v139
	v_add_f32_e32 v140, 1.0, v140
	v_add_f32_e32 v141, 1.0, v141
	v_rcp_f32_e32 v138, v138
	v_rcp_f32_e32 v139, v139
	v_rcp_f32_e32 v140, v140
	v_rcp_f32_e32 v141, v141
	v_lshlrev_b32_e32 v142, 16, v166
	v_and_b32_e32 v143, 0xffff0000, v166
	v_lshlrev_b32_e32 v144, 16, v167
	v_and_b32_e32 v145, 0xffff0000, v167
	v_pk_mul_f32 v[82:83], v[82:83], v[138:139]
	v_pk_mul_f32 v[84:85], v[84:85], v[140:141]
	v_pk_add_f32 v[82:83], v[82:83], v[142:143]
	v_pk_add_f32 v[84:85], v[84:85], v[144:145]
	v_cvt_pk_bf16_f32 v152, v82, v83
	v_cvt_pk_bf16_f32 v153, v84, v85
	v_lshl_add_u64 v[154:155], v[230:231], 0, v[136:137]
	s_nop 1
	v_permlane16_swap_b32_e32 v150, v152
	v_permlane16_swap_b32_e32 v151, v153
	global_store_dwordx4 v[154:155], v[150:153], off offset:64
	global_load_dwordx2 v[108:109], v[208:209], off offset:256
	global_load_dwordx2 v[218:219], v[114:115], off offset:256
	s_waitcnt vmcnt(20)
	v_lshlrev_b32_e32 v138, 16, v200
	v_and_b32_e32 v139, 0xffff0000, v200
	v_lshlrev_b32_e32 v140, 16, v201
	v_and_b32_e32 v141, 0xffff0000, v201
	v_add_f32_e32 v138, v184, v138
	v_add_f32_e32 v139, v185, v139
	v_add_f32_e32 v140, v186, v140
	v_add_f32_e32 v141, v187, v141
	v_mul_f32_e32 v138, 0xbfb8aa3b, v138
	v_mul_f32_e32 v139, 0xbfb8aa3b, v139
	v_mul_f32_e32 v140, 0xbfb8aa3b, v140
	v_mul_f32_e32 v141, 0xbfb8aa3b, v141
	v_exp_f32_e32 v138, v138
	v_exp_f32_e32 v139, v139
	v_exp_f32_e32 v140, v140
	v_exp_f32_e32 v141, v141
	v_add_f32_e32 v138, 1.0, v138
	v_add_f32_e32 v139, 1.0, v139
	v_add_f32_e32 v140, 1.0, v140
	v_add_f32_e32 v141, 1.0, v141
	v_rcp_f32_e32 v138, v138
	v_rcp_f32_e32 v139, v139
	v_rcp_f32_e32 v140, v140
	v_rcp_f32_e32 v141, v141
	v_lshlrev_b32_e32 v142, 16, v122
	v_and_b32_e32 v143, 0xffff0000, v122
	v_lshlrev_b32_e32 v144, 16, v123
	v_and_b32_e32 v145, 0xffff0000, v123
	v_pk_mul_f32 v[78:79], v[78:79], v[138:139]
	v_pk_mul_f32 v[80:81], v[80:81], v[140:141]
	v_pk_add_f32 v[78:79], v[78:79], v[142:143]
	v_pk_add_f32 v[80:81], v[80:81], v[144:145]
	v_cvt_pk_bf16_f32 v146, v78, v79
	v_cvt_pk_bf16_f32 v147, v80, v81
	global_load_dwordx2 v[220:221], v[208:209], off offset:288
	global_load_dwordx2 v[102:103], v[114:115], off offset:288
	s_waitcnt vmcnt(20)
	v_lshlrev_b32_e32 v138, 16, v124
	v_and_b32_e32 v139, 0xffff0000, v124
	v_lshlrev_b32_e32 v140, 16, v125
	v_and_b32_e32 v141, 0xffff0000, v125
	v_add_f32_e32 v138, v188, v138
	v_add_f32_e32 v139, v189, v139
	v_add_f32_e32 v140, v190, v140
	v_add_f32_e32 v141, v191, v141
	v_mul_f32_e32 v138, 0xbfb8aa3b, v138
	v_mul_f32_e32 v139, 0xbfb8aa3b, v139
	v_mul_f32_e32 v140, 0xbfb8aa3b, v140
	v_mul_f32_e32 v141, 0xbfb8aa3b, v141
	v_exp_f32_e32 v138, v138
	v_exp_f32_e32 v139, v139
	v_exp_f32_e32 v140, v140
	v_exp_f32_e32 v141, v141
	v_add_f32_e32 v138, 1.0, v138
	v_add_f32_e32 v139, 1.0, v139
	v_add_f32_e32 v140, 1.0, v140
	v_add_f32_e32 v141, 1.0, v141
	v_rcp_f32_e32 v138, v138
	v_rcp_f32_e32 v139, v139
	v_rcp_f32_e32 v140, v140
	v_rcp_f32_e32 v141, v141
	v_lshlrev_b32_e32 v142, 16, v202
	v_and_b32_e32 v143, 0xffff0000, v202
	v_lshlrev_b32_e32 v144, 16, v203
	v_and_b32_e32 v145, 0xffff0000, v203
	v_pk_mul_f32 v[74:75], v[74:75], v[138:139]
	v_pk_mul_f32 v[76:77], v[76:77], v[140:141]
	v_pk_add_f32 v[74:75], v[74:75], v[142:143]
	v_pk_add_f32 v[76:77], v[76:77], v[144:145]
	v_cvt_pk_bf16_f32 v148, v74, v75
	v_cvt_pk_bf16_f32 v149, v76, v77
	v_lshl_add_u64 v[154:155], v[230:231], 0, v[136:137]
	s_nop 1
	v_permlane16_swap_b32_e32 v146, v148
	v_permlane16_swap_b32_e32 v147, v149
	global_store_dwordx4 v[154:155], v[146:149], off offset:256
	global_load_dwordx2 v[104:105], v[208:209], off offset:320
	global_load_dwordx2 v[226:227], v[114:115], off offset:320
	s_waitcnt vmcnt(20)
; DI u32 pack2(float a, float b) { f2_t v = {a, b}; bf2_t r = __builtin_convertvector(v, bf2_t); return __builtin_bit_cast(u32, r); }
; DI float bflo(u32 v) { return __uint_as_float(v << 16); }
; DI float bfhi(u32 v) { return __uint_as_float(v & 0xffff0000u); }
; DI float sigmoidf_(float x) { return __builtin_amdgcn_rcpf(1.f + __builtin_amdgcn_exp2f(-LOG2E * x)); }
; DI void branch_tile8(const Params& P, const WsPtrs& W, int layer, int mt, int nt, unsigned char* smem) {
;     ...
;     const float* gbp = P.in[I_GATEB] + layer * 4096 + jb * 1024;
; #pragma unroll
;     for (int bj = 0; bj < 2; ++bj)
; #pragma unroll
;       for (int n = 0; n < 2; ++n) {
;         const int row = m0 + bj * 128 + wc * 32 + n * 16 + fr;
;         const u16* gp = W.Y + (size_t)row * LDY + O_GT + jb * 1024;
;         u16* mp = W.MERGED + (size_t)row * 1024;
; #pragma unroll
;         for (int ai = 0; ai < 2; ++ai)
; #pragma unroll
;           for (int m = 0; m < 4; ++m) {
;             const int f = n0 + ai * 128 + wr * 64 + m * 16 + fq * 4;
;             const u32x2 gv = *(const u32x2*)(gp + f);
;             const f32x4 b4 = *(const f32x4*)(gbp + f);
;             f32x4v a = acc[ai][bj][m][n];
;             float v0 = sigmoidf_(bflo(gv.x) + b4.x) * a.x, v1 = sigmoidf_(bfhi(gv.x) + b4.y) * a.y;
;             float v2 = sigmoidf_(bflo(gv.y) + b4.z) * a.z, v3 = sigmoidf_(bfhi(gv.y) + b4.w) * a.w;
;             if (jb > 0) { const u32x2 pv = *(const u32x2*)(mp + f); v0 += bflo(pv.x); v1 += bfhi(pv.x); v2 += bflo(pv.y); v3 += bfhi(pv.y); }
;             u32x2 o2; o2.x = pack2(v0, v1); o2.y = pack2(v2, v3);
;             *(u32x2*)(mp + f) = o2;
;           }
;       }
	v_lshlrev_b32_e32 v138, 16, v204
	v_and_b32_e32 v139, 0xffff0000, v204
	v_lshlrev_b32_e32 v140, 16, v205
	v_and_b32_e32 v141, 0xffff0000, v205
	v_add_f32_e32 v138, v192, v138
	v_add_f32_e32 v139, v193, v139
	v_add_f32_e32 v140, v194, v140
	v_add_f32_e32 v141, v195, v141
	v_mul_f32_e32 v138, 0xbfb8aa3b, v138
	v_mul_f32_e32 v139, 0xbfb8aa3b, v139
	v_mul_f32_e32 v140, 0xbfb8aa3b, v140
	v_mul_f32_e32 v141, 0xbfb8aa3b, v141
	v_exp_f32_e32 v138, v138
	v_exp_f32_e32 v139, v139
	v_exp_f32_e32 v140, v140
	v_exp_f32_e32 v141, v141
	v_add_f32_e32 v138, 1.0, v138
	v_add_f32_e32 v139, 1.0, v139
	v_add_f32_e32 v140, 1.0, v140
	v_add_f32_e32 v141, 1.0, v141
	v_rcp_f32_e32 v138, v138
	v_rcp_f32_e32 v139, v139
	v_rcp_f32_e32 v140, v140
	v_rcp_f32_e32 v141, v141
	v_lshlrev_b32_e32 v142, 16, v118
	v_and_b32_e32 v143, 0xffff0000, v118
	v_lshlrev_b32_e32 v144, 16, v119
	v_and_b32_e32 v145, 0xffff0000, v119
	v_pk_mul_f32 v[70:71], v[70:71], v[138:139]
	v_pk_mul_f32 v[72:73], v[72:73], v[140:141]
	v_pk_add_f32 v[70:71], v[70:71], v[142:143]
	v_pk_add_f32 v[72:73], v[72:73], v[144:145]
	v_cvt_pk_bf16_f32 v150, v70, v71
	v_cvt_pk_bf16_f32 v151, v72, v73
	global_load_dwordx2 v[222:223], v[208:209], off offset:352
	global_load_dwordx2 v[224:225], v[114:115], off offset:352
	s_waitcnt vmcnt(20)
	v_lshlrev_b32_e32 v138, 16, v120
	v_and_b32_e32 v139, 0xffff0000, v120
	v_lshlrev_b32_e32 v140, 16, v121
	v_and_b32_e32 v141, 0xffff0000, v121
	v_add_f32_e32 v138, v196, v138
	v_add_f32_e32 v139, v197, v139
	v_add_f32_e32 v140, v198, v140
	v_add_f32_e32 v141, v199, v141
	v_mul_f32_e32 v138, 0xbfb8aa3b, v138
	v_mul_f32_e32 v139, 0xbfb8aa3b, v139
	v_mul_f32_e32 v140, 0xbfb8aa3b, v140
	v_mul_f32_e32 v141, 0xbfb8aa3b, v141
	v_exp_f32_e32 v138, v138
	v_exp_f32_e32 v139, v139
	v_exp_f32_e32 v140, v140
	v_exp_f32_e32 v141, v141
	v_add_f32_e32 v138, 1.0, v138
	v_add_f32_e32 v139, 1.0, v139
	v_add_f32_e32 v140, 1.0, v140
	v_add_f32_e32 v141, 1.0, v141
	v_rcp_f32_e32 v138, v138
	v_rcp_f32_e32 v139, v139
	v_rcp_f32_e32 v140, v140
	v_rcp_f32_e32 v141, v141
	v_lshlrev_b32_e32 v142, 16, v206
	v_and_b32_e32 v143, 0xffff0000, v206
	v_lshlrev_b32_e32 v144, 16, v207
	v_and_b32_e32 v145, 0xffff0000, v207
	v_pk_mul_f32 v[66:67], v[66:67], v[138:139]
	v_pk_mul_f32 v[68:69], v[68:69], v[140:141]
	v_pk_add_f32 v[66:67], v[66:67], v[142:143]
	v_pk_add_f32 v[68:69], v[68:69], v[144:145]
	v_cvt_pk_bf16_f32 v152, v66, v67
	v_cvt_pk_bf16_f32 v153, v68, v69
	v_lshl_add_u64 v[154:155], v[230:231], 0, v[136:137]
	s_nop 1
	v_permlane16_swap_b32_e32 v150, v152
	v_permlane16_swap_b32_e32 v151, v153
	global_store_dwordx4 v[154:155], v[150:153], off offset:320
	v_or_b32_e32 v156, 0x90, v134
	v_ashrrev_i32_e32 v157, 31, v156
	v_mov_b64_e32 v[98:99], s[8:9]
	v_lshlrev_b64 v[100:101], 11, v[156:157]
	v_mad_i64_i32 v[98:99], s[22:23], v156, s33, v[98:99]
	v_lshl_add_u64 v[100:101], s[10:11], 0, v[100:101]
	v_lshl_add_u64 v[98:99], v[98:99], 0, s[2:3]
	v_lshl_add_u64 v[100:101], v[132:133], 1, v[100:101]
	v_lshl_add_u64 v[98:99], v[132:133], 1, v[98:99]
	v_lshl_add_u64 v[98:99], v[98:99], 0, s[20:21]
	global_load_dwordx2 v[160:161], v[98:99], off
	global_load_dwordx2 v[232:233], v[100:101], off
	s_waitcnt vmcnt(20)
	v_lshlrev_b32_e32 v138, 16, v116
	v_and_b32_e32 v139, 0xffff0000, v116
	v_lshlrev_b32_e32 v140, 16, v117
	v_and_b32_e32 v141, 0xffff0000, v117
	v_add_f32_e32 v138, v168, v138
	v_add_f32_e32 v139, v169, v139
	v_add_f32_e32 v140, v170, v140
	v_add_f32_e32 v141, v171, v141
	v_mul_f32_e32 v138, 0xbfb8aa3b, v138
	v_mul_f32_e32 v139, 0xbfb8aa3b, v139
	v_mul_f32_e32 v140, 0xbfb8aa3b, v140
	v_mul_f32_e32 v141, 0xbfb8aa3b, v141
	v_exp_f32_e32 v138, v138
	v_exp_f32_e32 v139, v139
	v_exp_f32_e32 v140, v140
	v_exp_f32_e32 v141, v141
	v_add_f32_e32 v138, 1.0, v138
	v_add_f32_e32 v139, 1.0, v139
	v_add_f32_e32 v140, 1.0, v140
	v_add_f32_e32 v141, 1.0, v141
	v_rcp_f32_e32 v138, v138
	v_rcp_f32_e32 v139, v139
	v_rcp_f32_e32 v140, v140
	v_rcp_f32_e32 v141, v141
	v_lshlrev_b32_e32 v142, 16, v210
	v_and_b32_e32 v143, 0xffff0000, v210
	v_lshlrev_b32_e32 v144, 16, v211
	v_and_b32_e32 v145, 0xffff0000, v211
	v_pk_mul_f32 v[62:63], v[62:63], v[138:139]
	v_pk_mul_f32 v[64:65], v[64:65], v[140:141]
	v_pk_add_f32 v[62:63], v[62:63], v[142:143]
	v_pk_add_f32 v[64:65], v[64:65], v[144:145]
	v_cvt_pk_bf16_f32 v146, v62, v63
	v_cvt_pk_bf16_f32 v147, v64, v65
	global_load_dwordx2 v[238:239], v[98:99], off offset:32
	global_load_dwordx2 v[94:95], v[100:101], off offset:32
	s_waitcnt vmcnt(20)
	v_lshlrev_b32_e32 v138, 16, v212
	v_and_b32_e32 v139, 0xffff0000, v212
	v_lshlrev_b32_e32 v140, 16, v213
	v_and_b32_e32 v141, 0xffff0000, v213
	v_add_f32_e32 v138, v172, v138
	v_add_f32_e32 v139, v173, v139
	v_add_f32_e32 v140, v174, v140
	v_add_f32_e32 v141, v175, v141
	v_mul_f32_e32 v138, 0xbfb8aa3b, v138
	v_mul_f32_e32 v139, 0xbfb8aa3b, v139
	v_mul_f32_e32 v140, 0xbfb8aa3b, v140
	v_mul_f32_e32 v141, 0xbfb8aa3b, v141
	v_exp_f32_e32 v138, v138
	v_exp_f32_e32 v139, v139
	v_exp_f32_e32 v140, v140
	v_exp_f32_e32 v141, v141
	v_add_f32_e32 v138, 1.0, v138
	v_add_f32_e32 v139, 1.0, v139
	v_add_f32_e32 v140, 1.0, v140
	v_add_f32_e32 v141, 1.0, v141
	v_rcp_f32_e32 v138, v138
	v_rcp_f32_e32 v139, v139
	v_rcp_f32_e32 v140, v140
	v_rcp_f32_e32 v141, v141
	v_lshlrev_b32_e32 v142, 16, v110
	v_and_b32_e32 v143, 0xffff0000, v110
	v_lshlrev_b32_e32 v144, 16, v111
	v_and_b32_e32 v145, 0xffff0000, v111
	v_pk_mul_f32 v[58:59], v[58:59], v[138:139]
	v_pk_mul_f32 v[60:61], v[60:61], v[140:141]
	v_pk_add_f32 v[58:59], v[58:59], v[142:143]
	v_pk_add_f32 v[60:61], v[60:61], v[144:145]
	v_cvt_pk_bf16_f32 v148, v58, v59
	v_cvt_pk_bf16_f32 v149, v60, v61
	v_lshl_add_u64 v[154:155], v[114:115], 0, v[136:137]
	s_nop 1
	v_permlane16_swap_b32_e32 v146, v148
	v_permlane16_swap_b32_e32 v147, v149
	global_store_dwordx4 v[154:155], v[146:149], off
	global_load_dwordx2 v[96:97], v[98:99], off offset:64
	global_load_dwordx2 v[158:159], v[100:101], off offset:64
	s_waitcnt vmcnt(20)
; DI u32 pack2(float a, float b) { f2_t v = {a, b}; bf2_t r = __builtin_convertvector(v, bf2_t); return __builtin_bit_cast(u32, r); }
; DI float bflo(u32 v) { return __uint_as_float(v << 16); }
; DI float bfhi(u32 v) { return __uint_as_float(v & 0xffff0000u); }
; DI float sigmoidf_(float x) { return __builtin_amdgcn_rcpf(1.f + __builtin_amdgcn_exp2f(-LOG2E * x)); }
; DI void branch_tile8(const Params& P, const WsPtrs& W, int layer, int mt, int nt, unsigned char* smem) {
;     ...
;     const float* gbp = P.in[I_GATEB] + layer * 4096 + jb * 1024;
; #pragma unroll
;     for (int bj = 0; bj < 2; ++bj)
; #pragma unroll
;       for (int n = 0; n < 2; ++n) {
;         const int row = m0 + bj * 128 + wc * 32 + n * 16 + fr;
;         const u16* gp = W.Y + (size_t)row * LDY + O_GT + jb * 1024;
;         u16* mp = W.MERGED + (size_t)row * 1024;
; #pragma unroll
;         for (int ai = 0; ai < 2; ++ai)
; #pragma unroll
;           for (int m = 0; m < 4; ++m) {
;             const int f = n0 + ai * 128 + wr * 64 + m * 16 + fq * 4;
;             const u32x2 gv = *(const u32x2*)(gp + f);
;             const f32x4 b4 = *(const f32x4*)(gbp + f);
;             f32x4v a = acc[ai][bj][m][n];
;             float v0 = sigmoidf_(bflo(gv.x) + b4.x) * a.x, v1 = sigmoidf_(bfhi(gv.x) + b4.y) * a.y;
;             float v2 = sigmoidf_(bflo(gv.y) + b4.z) * a.z, v3 = sigmoidf_(bfhi(gv.y) + b4.w) * a.w;
;             if (jb > 0) { const u32x2 pv = *(const u32x2*)(mp + f); v0 += bflo(pv.x); v1 += bfhi(pv.x); v2 += bflo(pv.y); v3 += bfhi(pv.y); }
;             u32x2 o2; o2.x = pack2(v0, v1); o2.y = pack2(v2, v3);
;             *(u32x2*)(mp + f) = o2;
;           }
;       }
	v_lshlrev_b32_e32 v138, 16, v112
	v_and_b32_e32 v139, 0xffff0000, v112
	v_lshlrev_b32_e32 v140, 16, v113
	v_and_b32_e32 v141, 0xffff0000, v113
	v_add_f32_e32 v138, v176, v138
	v_add_f32_e32 v139, v177, v139
	v_add_f32_e32 v140, v178, v140
	v_add_f32_e32 v141, v179, v141
	v_mul_f32_e32 v138, 0xbfb8aa3b, v138
	v_mul_f32_e32 v139, 0xbfb8aa3b, v139
	v_mul_f32_e32 v140, 0xbfb8aa3b, v140
	v_mul_f32_e32 v141, 0xbfb8aa3b, v141
	v_exp_f32_e32 v138, v138
	v_exp_f32_e32 v139, v139
	v_exp_f32_e32 v140, v140
	v_exp_f32_e32 v141, v141
	v_add_f32_e32 v138, 1.0, v138
	v_add_f32_e32 v139, 1.0, v139
	v_add_f32_e32 v140, 1.0, v140
	v_add_f32_e32 v141, 1.0, v141
	v_rcp_f32_e32 v138, v138
	v_rcp_f32_e32 v139, v139
	v_rcp_f32_e32 v140, v140
	v_rcp_f32_e32 v141, v141
	v_lshlrev_b32_e32 v142, 16, v214
	v_and_b32_e32 v143, 0xffff0000, v214
	v_lshlrev_b32_e32 v144, 16, v215
	v_and_b32_e32 v145, 0xffff0000, v215
	v_pk_mul_f32 v[54:55], v[54:55], v[138:139]
	v_pk_mul_f32 v[56:57], v[56:57], v[140:141]
	v_pk_add_f32 v[54:55], v[54:55], v[142:143]
	v_pk_add_f32 v[56:57], v[56:57], v[144:145]
	v_cvt_pk_bf16_f32 v150, v54, v55
	v_cvt_pk_bf16_f32 v151, v56, v57
	global_load_dwordx2 v[162:163], v[98:99], off offset:96
	global_load_dwordx2 v[90:91], v[100:101], off offset:96
	s_waitcnt vmcnt(20)
	v_lshlrev_b32_e32 v138, 16, v216
	v_and_b32_e32 v139, 0xffff0000, v216
	v_lshlrev_b32_e32 v140, 16, v217
	v_and_b32_e32 v141, 0xffff0000, v217
	v_add_f32_e32 v138, v180, v138
	v_add_f32_e32 v139, v181, v139
	v_add_f32_e32 v140, v182, v140
	v_add_f32_e32 v141, v183, v141
	v_mul_f32_e32 v138, 0xbfb8aa3b, v138
	v_mul_f32_e32 v139, 0xbfb8aa3b, v139
	v_mul_f32_e32 v140, 0xbfb8aa3b, v140
	v_mul_f32_e32 v141, 0xbfb8aa3b, v141
	v_exp_f32_e32 v138, v138
	v_exp_f32_e32 v139, v139
	v_exp_f32_e32 v140, v140
	v_exp_f32_e32 v141, v141
	v_add_f32_e32 v138, 1.0, v138
	v_add_f32_e32 v139, 1.0, v139
	v_add_f32_e32 v140, 1.0, v140
	v_add_f32_e32 v141, 1.0, v141
	v_rcp_f32_e32 v138, v138
	v_rcp_f32_e32 v139, v139
	v_rcp_f32_e32 v140, v140
	v_rcp_f32_e32 v141, v141
	v_lshlrev_b32_e32 v142, 16, v106
	v_and_b32_e32 v143, 0xffff0000, v106
	v_lshlrev_b32_e32 v144, 16, v107
	v_and_b32_e32 v145, 0xffff0000, v107
	v_pk_mul_f32 v[50:51], v[50:51], v[138:139]
	v_pk_mul_f32 v[52:53], v[52:53], v[140:141]
	v_pk_add_f32 v[50:51], v[50:51], v[142:143]
	v_pk_add_f32 v[52:53], v[52:53], v[144:145]
	v_cvt_pk_bf16_f32 v152, v50, v51
	v_cvt_pk_bf16_f32 v153, v52, v53
	v_lshl_add_u64 v[154:155], v[114:115], 0, v[136:137]
	s_nop 1
	v_permlane16_swap_b32_e32 v150, v152
	v_permlane16_swap_b32_e32 v151, v153
	global_store_dwordx4 v[154:155], v[150:153], off offset:64
	global_load_dwordx2 v[92:93], v[98:99], off offset:256
	global_load_dwordx2 v[164:165], v[100:101], off offset:256
	s_waitcnt vmcnt(20)
	v_lshlrev_b32_e32 v138, 16, v108
	v_and_b32_e32 v139, 0xffff0000, v108
	v_lshlrev_b32_e32 v140, 16, v109
	v_and_b32_e32 v141, 0xffff0000, v109
	v_add_f32_e32 v138, v184, v138
	v_add_f32_e32 v139, v185, v139
	v_add_f32_e32 v140, v186, v140
	v_add_f32_e32 v141, v187, v141
	v_mul_f32_e32 v138, 0xbfb8aa3b, v138
	v_mul_f32_e32 v139, 0xbfb8aa3b, v139
	v_mul_f32_e32 v140, 0xbfb8aa3b, v140
	v_mul_f32_e32 v141, 0xbfb8aa3b, v141
	v_exp_f32_e32 v138, v138
	v_exp_f32_e32 v139, v139
	v_exp_f32_e32 v140, v140
	v_exp_f32_e32 v141, v141
	v_add_f32_e32 v138, 1.0, v138
	v_add_f32_e32 v139, 1.0, v139
	v_add_f32_e32 v140, 1.0, v140
	v_add_f32_e32 v141, 1.0, v141
	v_rcp_f32_e32 v138, v138
	v_rcp_f32_e32 v139, v139
	v_rcp_f32_e32 v140, v140
	v_rcp_f32_e32 v141, v141
	v_lshlrev_b32_e32 v142, 16, v218
	v_and_b32_e32 v143, 0xffff0000, v218
	v_lshlrev_b32_e32 v144, 16, v219
	v_and_b32_e32 v145, 0xffff0000, v219
	v_pk_mul_f32 v[46:47], v[46:47], v[138:139]
	v_pk_mul_f32 v[48:49], v[48:49], v[140:141]
	v_pk_add_f32 v[46:47], v[46:47], v[142:143]
	v_pk_add_f32 v[48:49], v[48:49], v[144:145]
	v_cvt_pk_bf16_f32 v146, v46, v47
	v_cvt_pk_bf16_f32 v147, v48, v49
	global_load_dwordx2 v[126:127], v[98:99], off offset:288
	global_load_dwordx2 v[86:87], v[100:101], off offset:288
	s_waitcnt vmcnt(20)
	v_lshlrev_b32_e32 v138, 16, v220
	v_and_b32_e32 v139, 0xffff0000, v220
	v_lshlrev_b32_e32 v140, 16, v221
	v_and_b32_e32 v141, 0xffff0000, v221
	v_add_f32_e32 v138, v188, v138
	v_add_f32_e32 v139, v189, v139
	v_add_f32_e32 v140, v190, v140
	v_add_f32_e32 v141, v191, v141
	v_mul_f32_e32 v138, 0xbfb8aa3b, v138
	v_mul_f32_e32 v139, 0xbfb8aa3b, v139
	v_mul_f32_e32 v140, 0xbfb8aa3b, v140
	v_mul_f32_e32 v141, 0xbfb8aa3b, v141
	v_exp_f32_e32 v138, v138
	v_exp_f32_e32 v139, v139
	v_exp_f32_e32 v140, v140
	v_exp_f32_e32 v141, v141
	v_add_f32_e32 v138, 1.0, v138
	v_add_f32_e32 v139, 1.0, v139
	v_add_f32_e32 v140, 1.0, v140
	v_add_f32_e32 v141, 1.0, v141
	v_rcp_f32_e32 v138, v138
	v_rcp_f32_e32 v139, v139
	v_rcp_f32_e32 v140, v140
	v_rcp_f32_e32 v141, v141
	v_lshlrev_b32_e32 v142, 16, v102
	v_and_b32_e32 v143, 0xffff0000, v102
	v_lshlrev_b32_e32 v144, 16, v103
	v_and_b32_e32 v145, 0xffff0000, v103
	v_pk_mul_f32 v[42:43], v[42:43], v[138:139]
	v_pk_mul_f32 v[44:45], v[44:45], v[140:141]
	v_pk_add_f32 v[42:43], v[42:43], v[142:143]
	v_pk_add_f32 v[44:45], v[44:45], v[144:145]
	v_cvt_pk_bf16_f32 v148, v42, v43
	v_cvt_pk_bf16_f32 v149, v44, v45
	v_lshl_add_u64 v[154:155], v[114:115], 0, v[136:137]
	s_nop 1
	v_permlane16_swap_b32_e32 v146, v148
	v_permlane16_swap_b32_e32 v147, v149
	global_store_dwordx4 v[154:155], v[146:149], off offset:256
	global_load_dwordx2 v[88:89], v[98:99], off offset:320
	global_load_dwordx2 v[128:129], v[100:101], off offset:320
	s_waitcnt vmcnt(20)
; DI u32 pack2(float a, float b) { f2_t v = {a, b}; bf2_t r = __builtin_convertvector(v, bf2_t); return __builtin_bit_cast(u32, r); }
; DI float bflo(u32 v) { return __uint_as_float(v << 16); }
; DI float bfhi(u32 v) { return __uint_as_float(v & 0xffff0000u); }
; DI float sigmoidf_(float x) { return __builtin_amdgcn_rcpf(1.f + __builtin_amdgcn_exp2f(-LOG2E * x)); }
; DI void branch_tile8(const Params& P, const WsPtrs& W, int layer, int mt, int nt, unsigned char* smem) {
;     ...
;     const float* gbp = P.in[I_GATEB] + layer * 4096 + jb * 1024;
; #pragma unroll
;     for (int bj = 0; bj < 2; ++bj)
; #pragma unroll
;       for (int n = 0; n < 2; ++n) {
;         const int row = m0 + bj * 128 + wc * 32 + n * 16 + fr;
;         const u16* gp = W.Y + (size_t)row * LDY + O_GT + jb * 1024;
;         u16* mp = W.MERGED + (size_t)row * 1024;
; #pragma unroll
;         for (int ai = 0; ai < 2; ++ai)
; #pragma unroll
;           for (int m = 0; m < 4; ++m) {
;             const int f = n0 + ai * 128 + wr * 64 + m * 16 + fq * 4;
;             const u32x2 gv = *(const u32x2*)(gp + f);
;             const f32x4 b4 = *(const f32x4*)(gbp + f);
;             f32x4v a = acc[ai][bj][m][n];
;             float v0 = sigmoidf_(bflo(gv.x) + b4.x) * a.x, v1 = sigmoidf_(bfhi(gv.x) + b4.y) * a.y;
;             float v2 = sigmoidf_(bflo(gv.y) + b4.z) * a.z, v3 = sigmoidf_(bfhi(gv.y) + b4.w) * a.w;
;             if (jb > 0) { const u32x2 pv = *(const u32x2*)(mp + f); v0 += bflo(pv.x); v1 += bfhi(pv.x); v2 += bflo(pv.y); v3 += bfhi(pv.y); }
;             u32x2 o2; o2.x = pack2(v0, v1); o2.y = pack2(v2, v3);
;             *(u32x2*)(mp + f) = o2;
;           }
;       }
	v_lshlrev_b32_e32 v138, 16, v104
	v_and_b32_e32 v139, 0xffff0000, v104
	v_lshlrev_b32_e32 v140, 16, v105
	v_and_b32_e32 v141, 0xffff0000, v105
	v_add_f32_e32 v138, v192, v138
	v_add_f32_e32 v139, v193, v139
	v_add_f32_e32 v140, v194, v140
	v_add_f32_e32 v141, v195, v141
	v_mul_f32_e32 v138, 0xbfb8aa3b, v138
	v_mul_f32_e32 v139, 0xbfb8aa3b, v139
	v_mul_f32_e32 v140, 0xbfb8aa3b, v140
	v_mul_f32_e32 v141, 0xbfb8aa3b, v141
	v_exp_f32_e32 v138, v138
	v_exp_f32_e32 v139, v139
	v_exp_f32_e32 v140, v140
	v_exp_f32_e32 v141, v141
	v_add_f32_e32 v138, 1.0, v138
	v_add_f32_e32 v139, 1.0, v139
	v_add_f32_e32 v140, 1.0, v140
	v_add_f32_e32 v141, 1.0, v141
	v_rcp_f32_e32 v138, v138
	v_rcp_f32_e32 v139, v139
	v_rcp_f32_e32 v140, v140
	v_rcp_f32_e32 v141, v141
	v_lshlrev_b32_e32 v142, 16, v226
	v_and_b32_e32 v143, 0xffff0000, v226
	v_lshlrev_b32_e32 v144, 16, v227
	v_and_b32_e32 v145, 0xffff0000, v227
	v_pk_mul_f32 v[38:39], v[38:39], v[138:139]
	v_pk_mul_f32 v[40:41], v[40:41], v[140:141]
	v_pk_add_f32 v[38:39], v[38:39], v[142:143]
	v_pk_add_f32 v[40:41], v[40:41], v[144:145]
	v_cvt_pk_bf16_f32 v150, v38, v39
	v_cvt_pk_bf16_f32 v151, v40, v41
	global_load_dwordx2 v[166:167], v[98:99], off offset:352
	global_load_dwordx2 v[82:83], v[100:101], off offset:352
	s_waitcnt vmcnt(20)
	v_lshlrev_b32_e32 v138, 16, v222
	v_and_b32_e32 v139, 0xffff0000, v222
	v_lshlrev_b32_e32 v140, 16, v223
	v_and_b32_e32 v141, 0xffff0000, v223
	v_add_f32_e32 v138, v196, v138
	v_add_f32_e32 v139, v197, v139
	v_add_f32_e32 v140, v198, v140
	v_add_f32_e32 v141, v199, v141
	v_mul_f32_e32 v138, 0xbfb8aa3b, v138
	v_mul_f32_e32 v139, 0xbfb8aa3b, v139
	v_mul_f32_e32 v140, 0xbfb8aa3b, v140
	v_mul_f32_e32 v141, 0xbfb8aa3b, v141
	v_exp_f32_e32 v138, v138
	v_exp_f32_e32 v139, v139
	v_exp_f32_e32 v140, v140
	v_exp_f32_e32 v141, v141
	v_add_f32_e32 v138, 1.0, v138
	v_add_f32_e32 v139, 1.0, v139
	v_add_f32_e32 v140, 1.0, v140
	v_add_f32_e32 v141, 1.0, v141
	v_rcp_f32_e32 v138, v138
	v_rcp_f32_e32 v139, v139
	v_rcp_f32_e32 v140, v140
	v_rcp_f32_e32 v141, v141
	v_lshlrev_b32_e32 v142, 16, v224
	v_and_b32_e32 v143, 0xffff0000, v224
	v_lshlrev_b32_e32 v144, 16, v225
	v_and_b32_e32 v145, 0xffff0000, v225
	v_pk_mul_f32 v[34:35], v[34:35], v[138:139]
	v_pk_mul_f32 v[36:37], v[36:37], v[140:141]
	v_pk_add_f32 v[34:35], v[34:35], v[142:143]
	v_pk_add_f32 v[36:37], v[36:37], v[144:145]
	v_cvt_pk_bf16_f32 v152, v34, v35
	v_cvt_pk_bf16_f32 v153, v36, v37
	v_lshl_add_u64 v[154:155], v[114:115], 0, v[136:137]
	s_nop 1
	v_permlane16_swap_b32_e32 v150, v152
	v_permlane16_swap_b32_e32 v151, v153
	global_store_dwordx4 v[154:155], v[150:153], off offset:320
	s_waitcnt vmcnt(18)
	v_lshlrev_b32_e32 v138, 16, v160
	v_and_b32_e32 v139, 0xffff0000, v160
	v_lshlrev_b32_e32 v140, 16, v161
	v_and_b32_e32 v141, 0xffff0000, v161
	v_add_f32_e32 v138, v168, v138
	v_add_f32_e32 v139, v169, v139
	v_add_f32_e32 v140, v170, v140
	v_add_f32_e32 v141, v171, v141
	v_mul_f32_e32 v138, 0xbfb8aa3b, v138
	v_mul_f32_e32 v139, 0xbfb8aa3b, v139
	v_mul_f32_e32 v140, 0xbfb8aa3b, v140
	v_mul_f32_e32 v141, 0xbfb8aa3b, v141
	v_exp_f32_e32 v138, v138
	v_exp_f32_e32 v139, v139
	v_exp_f32_e32 v140, v140
	v_exp_f32_e32 v141, v141
	v_add_f32_e32 v138, 1.0, v138
	v_add_f32_e32 v139, 1.0, v139
	v_add_f32_e32 v140, 1.0, v140
	v_add_f32_e32 v141, 1.0, v141
	v_rcp_f32_e32 v138, v138
	v_rcp_f32_e32 v139, v139
	v_rcp_f32_e32 v140, v140
	v_rcp_f32_e32 v141, v141
	v_lshlrev_b32_e32 v142, 16, v232
	v_and_b32_e32 v143, 0xffff0000, v232
	v_lshlrev_b32_e32 v144, 16, v233
	v_and_b32_e32 v145, 0xffff0000, v233
	v_pk_mul_f32 v[30:31], v[30:31], v[138:139]
	v_pk_mul_f32 v[32:33], v[32:33], v[140:141]
	v_pk_add_f32 v[30:31], v[30:31], v[142:143]
	v_pk_add_f32 v[32:33], v[32:33], v[144:145]
	v_cvt_pk_bf16_f32 v146, v30, v31
	v_cvt_pk_bf16_f32 v147, v32, v33
	s_waitcnt vmcnt(16)
	v_lshlrev_b32_e32 v138, 16, v238
	v_and_b32_e32 v139, 0xffff0000, v238
	v_lshlrev_b32_e32 v140, 16, v239
	v_and_b32_e32 v141, 0xffff0000, v239
	v_add_f32_e32 v138, v172, v138
	v_add_f32_e32 v139, v173, v139
	v_add_f32_e32 v140, v174, v140
	v_add_f32_e32 v141, v175, v141
	v_mul_f32_e32 v138, 0xbfb8aa3b, v138
	v_mul_f32_e32 v139, 0xbfb8aa3b, v139
	v_mul_f32_e32 v140, 0xbfb8aa3b, v140
	v_mul_f32_e32 v141, 0xbfb8aa3b, v141
	v_exp_f32_e32 v138, v138
	v_exp_f32_e32 v139, v139
	v_exp_f32_e32 v140, v140
	v_exp_f32_e32 v141, v141
	v_add_f32_e32 v138, 1.0, v138
	v_add_f32_e32 v139, 1.0, v139
	v_add_f32_e32 v140, 1.0, v140
	v_add_f32_e32 v141, 1.0, v141
	v_rcp_f32_e32 v138, v138
	v_rcp_f32_e32 v139, v139
	v_rcp_f32_e32 v140, v140
	v_rcp_f32_e32 v141, v141
	v_lshlrev_b32_e32 v142, 16, v94
	v_and_b32_e32 v143, 0xffff0000, v94
	v_lshlrev_b32_e32 v144, 16, v95
	v_and_b32_e32 v145, 0xffff0000, v95
	v_pk_mul_f32 v[26:27], v[26:27], v[138:139]
	v_pk_mul_f32 v[28:29], v[28:29], v[140:141]
	v_pk_add_f32 v[26:27], v[26:27], v[142:143]
	v_pk_add_f32 v[28:29], v[28:29], v[144:145]
	v_cvt_pk_bf16_f32 v148, v26, v27
	v_cvt_pk_bf16_f32 v149, v28, v29
	v_lshl_add_u64 v[154:155], v[100:101], 0, v[136:137]
	s_nop 1
	v_permlane16_swap_b32_e32 v146, v148
	v_permlane16_swap_b32_e32 v147, v149
	global_store_dwordx4 v[154:155], v[146:149], off
	s_waitcnt vmcnt(14)
; DI u32 pack2(float a, float b) { f2_t v = {a, b}; bf2_t r = __builtin_convertvector(v, bf2_t); return __builtin_bit_cast(u32, r); }
; DI float bflo(u32 v) { return __uint_as_float(v << 16); }
; DI float bfhi(u32 v) { return __uint_as_float(v & 0xffff0000u); }
; DI float sigmoidf_(float x) { return __builtin_amdgcn_rcpf(1.f + __builtin_amdgcn_exp2f(-LOG2E * x)); }
; DI void branch_tile8(const Params& P, const WsPtrs& W, int layer, int mt, int nt, unsigned char* smem) {
;     ...
;     const float* gbp = P.in[I_GATEB] + layer * 4096 + jb * 1024;
; #pragma unroll
;     for (int bj = 0; bj < 2; ++bj)
; #pragma unroll
;       for (int n = 0; n < 2; ++n) {
;         const int row = m0 + bj * 128 + wc * 32 + n * 16 + fr;
;         const u16* gp = W.Y + (size_t)row * LDY + O_GT + jb * 1024;
;         u16* mp = W.MERGED + (size_t)row * 1024;
; #pragma unroll
;         for (int ai = 0; ai < 2; ++ai)
; #pragma unroll
;           for (int m = 0; m < 4; ++m) {
;             const int f = n0 + ai * 128 + wr * 64 + m * 16 + fq * 4;
;             const u32x2 gv = *(const u32x2*)(gp + f);
;             const f32x4 b4 = *(const f32x4*)(gbp + f);
;             f32x4v a = acc[ai][bj][m][n];
;             float v0 = sigmoidf_(bflo(gv.x) + b4.x) * a.x, v1 = sigmoidf_(bfhi(gv.x) + b4.y) * a.y;
;             float v2 = sigmoidf_(bflo(gv.y) + b4.z) * a.z, v3 = sigmoidf_(bfhi(gv.y) + b4.w) * a.w;
;             if (jb > 0) { const u32x2 pv = *(const u32x2*)(mp + f); v0 += bflo(pv.x); v1 += bfhi(pv.x); v2 += bflo(pv.y); v3 += bfhi(pv.y); }
;             u32x2 o2; o2.x = pack2(v0, v1); o2.y = pack2(v2, v3);
;             *(u32x2*)(mp + f) = o2;
;           }
;       }
	v_lshlrev_b32_e32 v138, 16, v96
	v_and_b32_e32 v139, 0xffff0000, v96
	v_lshlrev_b32_e32 v140, 16, v97
	v_and_b32_e32 v141, 0xffff0000, v97
	v_add_f32_e32 v138, v176, v138
	v_add_f32_e32 v139, v177, v139
	v_add_f32_e32 v140, v178, v140
	v_add_f32_e32 v141, v179, v141
	v_mul_f32_e32 v138, 0xbfb8aa3b, v138
	v_mul_f32_e32 v139, 0xbfb8aa3b, v139
	v_mul_f32_e32 v140, 0xbfb8aa3b, v140
	v_mul_f32_e32 v141, 0xbfb8aa3b, v141
	v_exp_f32_e32 v138, v138
	v_exp_f32_e32 v139, v139
	v_exp_f32_e32 v140, v140
	v_exp_f32_e32 v141, v141
	v_add_f32_e32 v138, 1.0, v138
	v_add_f32_e32 v139, 1.0, v139
	v_add_f32_e32 v140, 1.0, v140
	v_add_f32_e32 v141, 1.0, v141
	v_rcp_f32_e32 v138, v138
	v_rcp_f32_e32 v139, v139
	v_rcp_f32_e32 v140, v140
	v_rcp_f32_e32 v141, v141
	v_lshlrev_b32_e32 v142, 16, v158
	v_and_b32_e32 v143, 0xffff0000, v158
	v_lshlrev_b32_e32 v144, 16, v159
	v_and_b32_e32 v145, 0xffff0000, v159
	v_pk_mul_f32 v[22:23], v[22:23], v[138:139]
	v_pk_mul_f32 v[24:25], v[24:25], v[140:141]
	v_pk_add_f32 v[22:23], v[22:23], v[142:143]
	v_pk_add_f32 v[24:25], v[24:25], v[144:145]
	v_cvt_pk_bf16_f32 v150, v22, v23
	v_cvt_pk_bf16_f32 v151, v24, v25
	s_waitcnt vmcnt(12)
	v_lshlrev_b32_e32 v138, 16, v162
	v_and_b32_e32 v139, 0xffff0000, v162
	v_lshlrev_b32_e32 v140, 16, v163
	v_and_b32_e32 v141, 0xffff0000, v163
	v_add_f32_e32 v138, v180, v138
	v_add_f32_e32 v139, v181, v139
	v_add_f32_e32 v140, v182, v140
	v_add_f32_e32 v141, v183, v141
	v_mul_f32_e32 v138, 0xbfb8aa3b, v138
	v_mul_f32_e32 v139, 0xbfb8aa3b, v139
	v_mul_f32_e32 v140, 0xbfb8aa3b, v140
	v_mul_f32_e32 v141, 0xbfb8aa3b, v141
	v_exp_f32_e32 v138, v138
	v_exp_f32_e32 v139, v139
	v_exp_f32_e32 v140, v140
	v_exp_f32_e32 v141, v141
	v_add_f32_e32 v138, 1.0, v138
	v_add_f32_e32 v139, 1.0, v139
	v_add_f32_e32 v140, 1.0, v140
	v_add_f32_e32 v141, 1.0, v141
	v_rcp_f32_e32 v138, v138
	v_rcp_f32_e32 v139, v139
	v_rcp_f32_e32 v140, v140
	v_rcp_f32_e32 v141, v141
	v_lshlrev_b32_e32 v142, 16, v90
	v_and_b32_e32 v143, 0xffff0000, v90
	v_lshlrev_b32_e32 v144, 16, v91
	v_and_b32_e32 v145, 0xffff0000, v91
	v_pk_mul_f32 v[18:19], v[18:19], v[138:139]
	v_pk_mul_f32 v[20:21], v[20:21], v[140:141]
	v_pk_add_f32 v[18:19], v[18:19], v[142:143]
	v_pk_add_f32 v[20:21], v[20:21], v[144:145]
	v_cvt_pk_bf16_f32 v152, v18, v19
	v_cvt_pk_bf16_f32 v153, v20, v21
	v_lshl_add_u64 v[154:155], v[100:101], 0, v[136:137]
	s_nop 1
	v_permlane16_swap_b32_e32 v150, v152
	v_permlane16_swap_b32_e32 v151, v153
	global_store_dwordx4 v[154:155], v[150:153], off offset:64
	s_waitcnt vmcnt(10)
	v_lshlrev_b32_e32 v138, 16, v92
	v_and_b32_e32 v139, 0xffff0000, v92
	v_lshlrev_b32_e32 v140, 16, v93
	v_and_b32_e32 v141, 0xffff0000, v93
	v_add_f32_e32 v138, v184, v138
	v_add_f32_e32 v139, v185, v139
	v_add_f32_e32 v140, v186, v140
	v_add_f32_e32 v141, v187, v141
	v_mul_f32_e32 v138, 0xbfb8aa3b, v138
	v_mul_f32_e32 v139, 0xbfb8aa3b, v139
	v_mul_f32_e32 v140, 0xbfb8aa3b, v140
	v_mul_f32_e32 v141, 0xbfb8aa3b, v141
	v_exp_f32_e32 v138, v138
	v_exp_f32_e32 v139, v139
	v_exp_f32_e32 v140, v140
	v_exp_f32_e32 v141, v141
	v_add_f32_e32 v138, 1.0, v138
	v_add_f32_e32 v139, 1.0, v139
	v_add_f32_e32 v140, 1.0, v140
	v_add_f32_e32 v141, 1.0, v141
	v_rcp_f32_e32 v138, v138
	v_rcp_f32_e32 v139, v139
	v_rcp_f32_e32 v140, v140
	v_rcp_f32_e32 v141, v141
	v_lshlrev_b32_e32 v142, 16, v164
	v_and_b32_e32 v143, 0xffff0000, v164
	v_lshlrev_b32_e32 v144, 16, v165
	v_and_b32_e32 v145, 0xffff0000, v165
	v_pk_mul_f32 v[14:15], v[14:15], v[138:139]
	v_pk_mul_f32 v[16:17], v[16:17], v[140:141]
	v_pk_add_f32 v[14:15], v[14:15], v[142:143]
	v_pk_add_f32 v[16:17], v[16:17], v[144:145]
	v_cvt_pk_bf16_f32 v146, v14, v15
	v_cvt_pk_bf16_f32 v147, v16, v17
	s_waitcnt vmcnt(8)
	v_lshlrev_b32_e32 v138, 16, v126
	v_and_b32_e32 v139, 0xffff0000, v126
	v_lshlrev_b32_e32 v140, 16, v127
	v_and_b32_e32 v141, 0xffff0000, v127
	v_add_f32_e32 v138, v188, v138
	v_add_f32_e32 v139, v189, v139
	v_add_f32_e32 v140, v190, v140
	v_add_f32_e32 v141, v191, v141
	v_mul_f32_e32 v138, 0xbfb8aa3b, v138
	v_mul_f32_e32 v139, 0xbfb8aa3b, v139
	v_mul_f32_e32 v140, 0xbfb8aa3b, v140
	v_mul_f32_e32 v141, 0xbfb8aa3b, v141
	v_exp_f32_e32 v138, v138
	v_exp_f32_e32 v139, v139
	v_exp_f32_e32 v140, v140
	v_exp_f32_e32 v141, v141
	v_add_f32_e32 v138, 1.0, v138
	v_add_f32_e32 v139, 1.0, v139
	v_add_f32_e32 v140, 1.0, v140
	v_add_f32_e32 v141, 1.0, v141
	v_rcp_f32_e32 v138, v138
	v_rcp_f32_e32 v139, v139
	v_rcp_f32_e32 v140, v140
	v_rcp_f32_e32 v141, v141
	v_lshlrev_b32_e32 v142, 16, v86
	v_and_b32_e32 v143, 0xffff0000, v86
	v_lshlrev_b32_e32 v144, 16, v87
	v_and_b32_e32 v145, 0xffff0000, v87
	v_pk_mul_f32 v[10:11], v[10:11], v[138:139]
	v_pk_mul_f32 v[12:13], v[12:13], v[140:141]
	v_pk_add_f32 v[10:11], v[10:11], v[142:143]
	v_pk_add_f32 v[12:13], v[12:13], v[144:145]
	v_cvt_pk_bf16_f32 v148, v10, v11
	v_cvt_pk_bf16_f32 v149, v12, v13
	v_lshl_add_u64 v[154:155], v[100:101], 0, v[136:137]
	s_nop 1
	v_permlane16_swap_b32_e32 v146, v148
	v_permlane16_swap_b32_e32 v147, v149
	global_store_dwordx4 v[154:155], v[146:149], off offset:256
	s_waitcnt vmcnt(6)
	v_lshlrev_b32_e32 v138, 16, v88
	v_and_b32_e32 v139, 0xffff0000, v88
	v_lshlrev_b32_e32 v140, 16, v89
	v_and_b32_e32 v141, 0xffff0000, v89
	v_add_f32_e32 v138, v192, v138
	v_add_f32_e32 v139, v193, v139
	v_add_f32_e32 v140, v194, v140
	v_add_f32_e32 v141, v195, v141
	v_mul_f32_e32 v138, 0xbfb8aa3b, v138
	v_mul_f32_e32 v139, 0xbfb8aa3b, v139
	v_mul_f32_e32 v140, 0xbfb8aa3b, v140
	v_mul_f32_e32 v141, 0xbfb8aa3b, v141
	v_exp_f32_e32 v138, v138
	v_exp_f32_e32 v139, v139
	v_exp_f32_e32 v140, v140
	v_exp_f32_e32 v141, v141
	v_add_f32_e32 v138, 1.0, v138
	v_add_f32_e32 v139, 1.0, v139
	v_add_f32_e32 v140, 1.0, v140
	v_add_f32_e32 v141, 1.0, v141
	v_rcp_f32_e32 v138, v138
	v_rcp_f32_e32 v139, v139
	v_rcp_f32_e32 v140, v140
	v_rcp_f32_e32 v141, v141
	v_lshlrev_b32_e32 v142, 16, v128
	v_and_b32_e32 v143, 0xffff0000, v128
	v_lshlrev_b32_e32 v144, 16, v129
	v_and_b32_e32 v145, 0xffff0000, v129
	v_pk_mul_f32 v[6:7], v[6:7], v[138:139]
	v_pk_mul_f32 v[8:9], v[8:9], v[140:141]
	v_pk_add_f32 v[6:7], v[6:7], v[142:143]
	v_pk_add_f32 v[8:9], v[8:9], v[144:145]
	v_cvt_pk_bf16_f32 v150, v6, v7
	v_cvt_pk_bf16_f32 v151, v8, v9
	s_waitcnt vmcnt(4)
; DI u32 pack2(float a, float b) { f2_t v = {a, b}; bf2_t r = __builtin_convertvector(v, bf2_t); return __builtin_bit_cast(u32, r); }
; DI float bflo(u32 v) { return __uint_as_float(v << 16); }
; DI float bfhi(u32 v) { return __uint_as_float(v & 0xffff0000u); }
; DI float sigmoidf_(float x) { return __builtin_amdgcn_rcpf(1.f + __builtin_amdgcn_exp2f(-LOG2E * x)); }
; DI void branch_tile8(const Params& P, const WsPtrs& W, int layer, int mt, int nt, unsigned char* smem) {
;     ...
;     const float* gbp = P.in[I_GATEB] + layer * 4096 + jb * 1024;
; #pragma unroll
;     for (int bj = 0; bj < 2; ++bj)
; #pragma unroll
;       for (int n = 0; n < 2; ++n) {
;         const int row = m0 + bj * 128 + wc * 32 + n * 16 + fr;
;         const u16* gp = W.Y + (size_t)row * LDY + O_GT + jb * 1024;
;         u16* mp = W.MERGED + (size_t)row * 1024;
; #pragma unroll
;         for (int ai = 0; ai < 2; ++ai)
; #pragma unroll
;           for (int m = 0; m < 4; ++m) {
;             const int f = n0 + ai * 128 + wr * 64 + m * 16 + fq * 4;
;             const u32x2 gv = *(const u32x2*)(gp + f);
;             const f32x4 b4 = *(const f32x4*)(gbp + f);
;             f32x4v a = acc[ai][bj][m][n];
;             float v0 = sigmoidf_(bflo(gv.x) + b4.x) * a.x, v1 = sigmoidf_(bfhi(gv.x) + b4.y) * a.y;
;             float v2 = sigmoidf_(bflo(gv.y) + b4.z) * a.z, v3 = sigmoidf_(bfhi(gv.y) + b4.w) * a.w;
;             if (jb > 0) { const u32x2 pv = *(const u32x2*)(mp + f); v0 += bflo(pv.x); v1 += bfhi(pv.x); v2 += bflo(pv.y); v3 += bfhi(pv.y); }
;             u32x2 o2; o2.x = pack2(v0, v1); o2.y = pack2(v2, v3);
;             *(u32x2*)(mp + f) = o2;
;           }
;       }
	v_lshlrev_b32_e32 v138, 16, v166
	v_and_b32_e32 v139, 0xffff0000, v166
	v_lshlrev_b32_e32 v140, 16, v167
	v_and_b32_e32 v141, 0xffff0000, v167
	v_add_f32_e32 v138, v196, v138
	v_add_f32_e32 v139, v197, v139
	v_add_f32_e32 v140, v198, v140
	v_add_f32_e32 v141, v199, v141
	v_mul_f32_e32 v138, 0xbfb8aa3b, v138
	v_mul_f32_e32 v139, 0xbfb8aa3b, v139
	v_mul_f32_e32 v140, 0xbfb8aa3b, v140
	v_mul_f32_e32 v141, 0xbfb8aa3b, v141
	v_exp_f32_e32 v138, v138
	v_exp_f32_e32 v139, v139
	v_exp_f32_e32 v140, v140
	v_exp_f32_e32 v141, v141
	v_add_f32_e32 v138, 1.0, v138
	v_add_f32_e32 v139, 1.0, v139
	v_add_f32_e32 v140, 1.0, v140
	v_add_f32_e32 v141, 1.0, v141
	v_rcp_f32_e32 v138, v138
	v_rcp_f32_e32 v139, v139
	v_rcp_f32_e32 v140, v140
	v_rcp_f32_e32 v141, v141
	v_lshlrev_b32_e32 v142, 16, v82
	v_and_b32_e32 v143, 0xffff0000, v82
	v_lshlrev_b32_e32 v144, 16, v83
	v_and_b32_e32 v145, 0xffff0000, v83
	v_pk_mul_f32 v[2:3], v[2:3], v[138:139]
	v_pk_mul_f32 v[4:5], v[4:5], v[140:141]
	v_pk_add_f32 v[2:3], v[2:3], v[142:143]
	v_pk_add_f32 v[4:5], v[4:5], v[144:145]
	v_cvt_pk_bf16_f32 v152, v2, v3
	v_cvt_pk_bf16_f32 v153, v4, v5
	v_lshl_add_u64 v[154:155], v[100:101], 0, v[136:137]
	s_nop 1
	v_permlane16_swap_b32_e32 v150, v152
	v_permlane16_swap_b32_e32 v151, v153
	global_store_dwordx4 v[154:155], v[150:153], off offset:320
	s_branch .LBB0_703
.Lbre_first:
	v_mov_b64_e32 v[158:159], s[8:9]
	v_lshlrev_b64 v[160:161], 11, v[134:135]
	v_mad_i64_i32 v[158:159], s[22:23], v134, s33, v[158:159]
	v_lshl_add_u64 v[160:161], s[10:11], 0, v[160:161]
	v_lshl_add_u64 v[158:159], v[158:159], 0, s[2:3]
	v_lshl_add_u64 v[160:161], v[132:133], 1, v[160:161]
	v_lshl_add_u64 v[158:159], v[132:133], 1, v[158:159]
	v_lshl_add_u64 v[158:159], v[158:159], 0, s[20:21]
	global_load_dwordx2 v[162:163], v[158:159], off
	global_load_dwordx2 v[164:165], v[158:159], off offset:32
	global_load_dwordx2 v[166:167], v[158:159], off offset:64
	global_load_dwordx2 v[200:201], v[158:159], off offset:96
	global_load_dwordx2 v[202:203], v[158:159], off offset:256
	global_load_dwordx2 v[204:205], v[158:159], off offset:288
	global_load_dwordx2 v[206:207], v[158:159], off offset:320
	global_load_dwordx2 v[208:209], v[158:159], off offset:352
	v_or_b32_e32 v156, 0x10, v134
	v_ashrrev_i32_e32 v157, 31, v156
	v_mov_b64_e32 v[210:211], s[8:9]
	v_lshlrev_b64 v[212:213], 11, v[156:157]
	v_mad_i64_i32 v[210:211], s[22:23], v156, s33, v[210:211]
	v_lshl_add_u64 v[212:213], s[10:11], 0, v[212:213]
	v_lshl_add_u64 v[210:211], v[210:211], 0, s[2:3]
	v_lshl_add_u64 v[212:213], v[132:133], 1, v[212:213]
	v_lshl_add_u64 v[210:211], v[132:133], 1, v[210:211]
	v_lshl_add_u64 v[210:211], v[210:211], 0, s[20:21]
	global_load_dwordx2 v[214:215], v[210:211], off
	s_waitcnt vmcnt(8)
	v_lshlrev_b32_e32 v138, 16, v162
	v_and_b32_e32 v139, 0xffff0000, v162
	v_lshlrev_b32_e32 v140, 16, v163
	v_and_b32_e32 v141, 0xffff0000, v163
	v_add_f32_e32 v138, v168, v138
	v_add_f32_e32 v139, v169, v139
	v_add_f32_e32 v140, v170, v140
	v_add_f32_e32 v141, v171, v141
	v_mul_f32_e32 v138, 0xbfb8aa3b, v138
	v_mul_f32_e32 v139, 0xbfb8aa3b, v139
	v_mul_f32_e32 v140, 0xbfb8aa3b, v140
	v_mul_f32_e32 v141, 0xbfb8aa3b, v141
	v_exp_f32_e32 v138, v138
	v_exp_f32_e32 v139, v139
	v_exp_f32_e32 v140, v140
	v_exp_f32_e32 v141, v141
	v_add_f32_e32 v138, 1.0, v138
	v_add_f32_e32 v139, 1.0, v139
	v_add_f32_e32 v140, 1.0, v140
	v_add_f32_e32 v141, 1.0, v141
	v_rcp_f32_e32 v138, v138
	v_rcp_f32_e32 v139, v139
	v_rcp_f32_e32 v140, v140
	v_rcp_f32_e32 v141, v141
	s_nop 0
	v_pk_mul_f32 v[126:127], v[126:127], v[138:139]
	v_pk_mul_f32 v[128:129], v[128:129], v[140:141]
	v_cvt_pk_bf16_f32 v146, v126, v127
	v_cvt_pk_bf16_f32 v147, v128, v129
	global_load_dwordx2 v[216:217], v[210:211], off offset:32
	s_waitcnt vmcnt(8)
	v_lshlrev_b32_e32 v138, 16, v164
	v_and_b32_e32 v139, 0xffff0000, v164
	v_lshlrev_b32_e32 v140, 16, v165
	v_and_b32_e32 v141, 0xffff0000, v165
	v_add_f32_e32 v138, v172, v138
	v_add_f32_e32 v139, v173, v139
	v_add_f32_e32 v140, v174, v140
	v_add_f32_e32 v141, v175, v141
	v_mul_f32_e32 v138, 0xbfb8aa3b, v138
	v_mul_f32_e32 v139, 0xbfb8aa3b, v139
	v_mul_f32_e32 v140, 0xbfb8aa3b, v140
	v_mul_f32_e32 v141, 0xbfb8aa3b, v141
	v_exp_f32_e32 v138, v138
	v_exp_f32_e32 v139, v139
	v_exp_f32_e32 v140, v140
	v_exp_f32_e32 v141, v141
	v_add_f32_e32 v138, 1.0, v138
	v_add_f32_e32 v139, 1.0, v139
	v_add_f32_e32 v140, 1.0, v140
	v_add_f32_e32 v141, 1.0, v141
	v_rcp_f32_e32 v138, v138
	v_rcp_f32_e32 v139, v139
	v_rcp_f32_e32 v140, v140
	v_rcp_f32_e32 v141, v141
	s_nop 0
	v_pk_mul_f32 v[122:123], v[122:123], v[138:139]
	v_pk_mul_f32 v[124:125], v[124:125], v[140:141]
	v_cvt_pk_bf16_f32 v148, v122, v123
	v_cvt_pk_bf16_f32 v149, v124, v125
	v_lshl_add_u64 v[154:155], v[160:161], 0, v[136:137]
	s_nop 1
	v_permlane16_swap_b32_e32 v146, v148
	v_permlane16_swap_b32_e32 v147, v149
	global_store_dwordx4 v[154:155], v[146:149], off
	global_load_dwordx2 v[218:219], v[210:211], off offset:64
	s_waitcnt vmcnt(9)
	v_lshlrev_b32_e32 v138, 16, v166
	v_and_b32_e32 v139, 0xffff0000, v166
	v_lshlrev_b32_e32 v140, 16, v167
	v_and_b32_e32 v141, 0xffff0000, v167
	v_add_f32_e32 v138, v176, v138
	v_add_f32_e32 v139, v177, v139
	v_add_f32_e32 v140, v178, v140
	v_add_f32_e32 v141, v179, v141
	v_mul_f32_e32 v138, 0xbfb8aa3b, v138
	v_mul_f32_e32 v139, 0xbfb8aa3b, v139
	v_mul_f32_e32 v140, 0xbfb8aa3b, v140
	v_mul_f32_e32 v141, 0xbfb8aa3b, v141
	v_exp_f32_e32 v138, v138
	v_exp_f32_e32 v139, v139
	v_exp_f32_e32 v140, v140
	v_exp_f32_e32 v141, v141
	v_add_f32_e32 v138, 1.0, v138
	v_add_f32_e32 v139, 1.0, v139
	v_add_f32_e32 v140, 1.0, v140
	v_add_f32_e32 v141, 1.0, v141
	v_rcp_f32_e32 v138, v138
	v_rcp_f32_e32 v139, v139
	v_rcp_f32_e32 v140, v140
	v_rcp_f32_e32 v141, v141
	s_nop 0
	v_pk_mul_f32 v[118:119], v[118:119], v[138:139]
	v_pk_mul_f32 v[120:121], v[120:121], v[140:141]
	v_cvt_pk_bf16_f32 v150, v118, v119
	v_cvt_pk_bf16_f32 v151, v120, v121
	global_load_dwordx2 v[220:221], v[210:211], off offset:96
	s_waitcnt vmcnt(9)
; DI u32 pack2(float a, float b) { f2_t v = {a, b}; bf2_t r = __builtin_convertvector(v, bf2_t); return __builtin_bit_cast(u32, r); }
; DI float bflo(u32 v) { return __uint_as_float(v << 16); }
; DI float bfhi(u32 v) { return __uint_as_float(v & 0xffff0000u); }
; DI float sigmoidf_(float x) { return __builtin_amdgcn_rcpf(1.f + __builtin_amdgcn_exp2f(-LOG2E * x)); }
; DI void branch_tile8(const Params& P, const WsPtrs& W, int layer, int mt, int nt, unsigned char* smem) {
;     ...
;     const float* gbp = P.in[I_GATEB] + layer * 4096 + jb * 1024;
; #pragma unroll
;     for (int bj = 0; bj < 2; ++bj)
; #pragma unroll
;       for (int n = 0; n < 2; ++n) {
;         const int row = m0 + bj * 128 + wc * 32 + n * 16 + fr;
;         const u16* gp = W.Y + (size_t)row * LDY + O_GT + jb * 1024;
;         u16* mp = W.MERGED + (size_t)row * 1024;
; #pragma unroll
;         for (int ai = 0; ai < 2; ++ai)
; #pragma unroll
;           for (int m = 0; m < 4; ++m) {
;             const int f = n0 + ai * 128 + wr * 64 + m * 16 + fq * 4;
;             const u32x2 gv = *(const u32x2*)(gp + f);
;             const f32x4 b4 = *(const f32x4*)(gbp + f);
;             f32x4v a = acc[ai][bj][m][n];
;             float v0 = sigmoidf_(bflo(gv.x) + b4.x) * a.x, v1 = sigmoidf_(bfhi(gv.x) + b4.y) * a.y;
;             float v2 = sigmoidf_(bflo(gv.y) + b4.z) * a.z, v3 = sigmoidf_(bfhi(gv.y) + b4.w) * a.w;
;             if (jb > 0) { const u32x2 pv = *(const u32x2*)(mp + f); v0 += bflo(pv.x); v1 += bfhi(pv.x); v2 += bflo(pv.y); v3 += bfhi(pv.y); }
;             u32x2 o2; o2.x = pack2(v0, v1); o2.y = pack2(v2, v3);
;             *(u32x2*)(mp + f) = o2;
;           }
;       }
	v_lshlrev_b32_e32 v138, 16, v200
	v_and_b32_e32 v139, 0xffff0000, v200
	v_lshlrev_b32_e32 v140, 16, v201
	v_and_b32_e32 v141, 0xffff0000, v201
	v_add_f32_e32 v138, v180, v138
	v_add_f32_e32 v139, v181, v139
	v_add_f32_e32 v140, v182, v140
	v_add_f32_e32 v141, v183, v141
	v_mul_f32_e32 v138, 0xbfb8aa3b, v138
	v_mul_f32_e32 v139, 0xbfb8aa3b, v139
	v_mul_f32_e32 v140, 0xbfb8aa3b, v140
	v_mul_f32_e32 v141, 0xbfb8aa3b, v141
	v_exp_f32_e32 v138, v138
	v_exp_f32_e32 v139, v139
	v_exp_f32_e32 v140, v140
	v_exp_f32_e32 v141, v141
	v_add_f32_e32 v138, 1.0, v138
	v_add_f32_e32 v139, 1.0, v139
	v_add_f32_e32 v140, 1.0, v140
	v_add_f32_e32 v141, 1.0, v141
	v_rcp_f32_e32 v138, v138
	v_rcp_f32_e32 v139, v139
	v_rcp_f32_e32 v140, v140
	v_rcp_f32_e32 v141, v141
	s_nop 0
	v_pk_mul_f32 v[114:115], v[114:115], v[138:139]
	v_pk_mul_f32 v[116:117], v[116:117], v[140:141]
	v_cvt_pk_bf16_f32 v152, v114, v115
	v_cvt_pk_bf16_f32 v153, v116, v117
	v_lshl_add_u64 v[154:155], v[160:161], 0, v[136:137]
	s_nop 1
	v_permlane16_swap_b32_e32 v150, v152
	v_permlane16_swap_b32_e32 v151, v153
	global_store_dwordx4 v[154:155], v[150:153], off offset:64
	global_load_dwordx2 v[222:223], v[210:211], off offset:256
	s_waitcnt vmcnt(10)
	v_lshlrev_b32_e32 v138, 16, v202
	v_and_b32_e32 v139, 0xffff0000, v202
	v_lshlrev_b32_e32 v140, 16, v203
	v_and_b32_e32 v141, 0xffff0000, v203
	v_add_f32_e32 v138, v184, v138
	v_add_f32_e32 v139, v185, v139
	v_add_f32_e32 v140, v186, v140
	v_add_f32_e32 v141, v187, v141
	v_mul_f32_e32 v138, 0xbfb8aa3b, v138
	v_mul_f32_e32 v139, 0xbfb8aa3b, v139
	v_mul_f32_e32 v140, 0xbfb8aa3b, v140
	v_mul_f32_e32 v141, 0xbfb8aa3b, v141
	v_exp_f32_e32 v138, v138
	v_exp_f32_e32 v139, v139
	v_exp_f32_e32 v140, v140
	v_exp_f32_e32 v141, v141
	v_add_f32_e32 v138, 1.0, v138
	v_add_f32_e32 v139, 1.0, v139
	v_add_f32_e32 v140, 1.0, v140
	v_add_f32_e32 v141, 1.0, v141
	v_rcp_f32_e32 v138, v138
	v_rcp_f32_e32 v139, v139
	v_rcp_f32_e32 v140, v140
	v_rcp_f32_e32 v141, v141
	s_nop 0
	v_pk_mul_f32 v[110:111], v[110:111], v[138:139]
	v_pk_mul_f32 v[112:113], v[112:113], v[140:141]
	v_cvt_pk_bf16_f32 v146, v110, v111
	v_cvt_pk_bf16_f32 v147, v112, v113
	global_load_dwordx2 v[224:225], v[210:211], off offset:288
	s_waitcnt vmcnt(10)
	v_lshlrev_b32_e32 v138, 16, v204
	v_and_b32_e32 v139, 0xffff0000, v204
	v_lshlrev_b32_e32 v140, 16, v205
	v_and_b32_e32 v141, 0xffff0000, v205
	v_add_f32_e32 v138, v188, v138
	v_add_f32_e32 v139, v189, v139
	v_add_f32_e32 v140, v190, v140
	v_add_f32_e32 v141, v191, v141
	v_mul_f32_e32 v138, 0xbfb8aa3b, v138
	v_mul_f32_e32 v139, 0xbfb8aa3b, v139
	v_mul_f32_e32 v140, 0xbfb8aa3b, v140
	v_mul_f32_e32 v141, 0xbfb8aa3b, v141
	v_exp_f32_e32 v138, v138
	v_exp_f32_e32 v139, v139
	v_exp_f32_e32 v140, v140
	v_exp_f32_e32 v141, v141
	v_add_f32_e32 v138, 1.0, v138
	v_add_f32_e32 v139, 1.0, v139
	v_add_f32_e32 v140, 1.0, v140
	v_add_f32_e32 v141, 1.0, v141
	v_rcp_f32_e32 v138, v138
	v_rcp_f32_e32 v139, v139
	v_rcp_f32_e32 v140, v140
	v_rcp_f32_e32 v141, v141
	s_nop 0
	v_pk_mul_f32 v[106:107], v[106:107], v[138:139]
	v_pk_mul_f32 v[108:109], v[108:109], v[140:141]
	v_cvt_pk_bf16_f32 v148, v106, v107
	v_cvt_pk_bf16_f32 v149, v108, v109
	v_lshl_add_u64 v[154:155], v[160:161], 0, v[136:137]
	s_nop 1
	v_permlane16_swap_b32_e32 v146, v148
	v_permlane16_swap_b32_e32 v147, v149
	global_store_dwordx4 v[154:155], v[146:149], off offset:256
	global_load_dwordx2 v[226:227], v[210:211], off offset:320
	s_waitcnt vmcnt(11)
	v_lshlrev_b32_e32 v138, 16, v206
	v_and_b32_e32 v139, 0xffff0000, v206
	v_lshlrev_b32_e32 v140, 16, v207
	v_and_b32_e32 v141, 0xffff0000, v207
	v_add_f32_e32 v138, v192, v138
	v_add_f32_e32 v139, v193, v139
	v_add_f32_e32 v140, v194, v140
	v_add_f32_e32 v141, v195, v141
	v_mul_f32_e32 v138, 0xbfb8aa3b, v138
	v_mul_f32_e32 v139, 0xbfb8aa3b, v139
	v_mul_f32_e32 v140, 0xbfb8aa3b, v140
	v_mul_f32_e32 v141, 0xbfb8aa3b, v141
	v_exp_f32_e32 v138, v138
	v_exp_f32_e32 v139, v139
	v_exp_f32_e32 v140, v140
	v_exp_f32_e32 v141, v141
	v_add_f32_e32 v138, 1.0, v138
	v_add_f32_e32 v139, 1.0, v139
	v_add_f32_e32 v140, 1.0, v140
	v_add_f32_e32 v141, 1.0, v141
	v_rcp_f32_e32 v138, v138
	v_rcp_f32_e32 v139, v139
	v_rcp_f32_e32 v140, v140
	v_rcp_f32_e32 v141, v141
	s_nop 0
	v_pk_mul_f32 v[102:103], v[102:103], v[138:139]
	v_pk_mul_f32 v[104:105], v[104:105], v[140:141]
	v_cvt_pk_bf16_f32 v150, v102, v103
	v_cvt_pk_bf16_f32 v151, v104, v105
	global_load_dwordx2 v[230:231], v[210:211], off offset:352
	s_waitcnt vmcnt(11)
	v_lshlrev_b32_e32 v138, 16, v208
	v_and_b32_e32 v139, 0xffff0000, v208
	v_lshlrev_b32_e32 v140, 16, v209
	v_and_b32_e32 v141, 0xffff0000, v209
	v_add_f32_e32 v138, v196, v138
	v_add_f32_e32 v139, v197, v139
	v_add_f32_e32 v140, v198, v140
	v_add_f32_e32 v141, v199, v141
	v_mul_f32_e32 v138, 0xbfb8aa3b, v138
	v_mul_f32_e32 v139, 0xbfb8aa3b, v139
	v_mul_f32_e32 v140, 0xbfb8aa3b, v140
	v_mul_f32_e32 v141, 0xbfb8aa3b, v141
	v_exp_f32_e32 v138, v138
	v_exp_f32_e32 v139, v139
	v_exp_f32_e32 v140, v140
	v_exp_f32_e32 v141, v141
	v_add_f32_e32 v138, 1.0, v138
	v_add_f32_e32 v139, 1.0, v139
	v_add_f32_e32 v140, 1.0, v140
	v_add_f32_e32 v141, 1.0, v141
	v_rcp_f32_e32 v138, v138
	v_rcp_f32_e32 v139, v139
	v_rcp_f32_e32 v140, v140
	v_rcp_f32_e32 v141, v141
	s_nop 0
	v_pk_mul_f32 v[98:99], v[98:99], v[138:139]
	v_pk_mul_f32 v[100:101], v[100:101], v[140:141]
	v_cvt_pk_bf16_f32 v152, v98, v99
	v_cvt_pk_bf16_f32 v153, v100, v101
	v_lshl_add_u64 v[154:155], v[160:161], 0, v[136:137]
	s_nop 1
	v_permlane16_swap_b32_e32 v150, v152
	v_permlane16_swap_b32_e32 v151, v153
	global_store_dwordx4 v[154:155], v[150:153], off offset:320
	v_or_b32_e32 v156, 0x80, v134
	v_ashrrev_i32_e32 v157, 31, v156
	v_mov_b64_e32 v[232:233], s[8:9]
	v_lshlrev_b64 v[238:239], 11, v[156:157]
	v_mad_i64_i32 v[232:233], s[22:23], v156, s33, v[232:233]
	v_lshl_add_u64 v[238:239], s[10:11], 0, v[238:239]
	v_lshl_add_u64 v[232:233], v[232:233], 0, s[2:3]
	v_lshl_add_u64 v[238:239], v[132:133], 1, v[238:239]
	v_lshl_add_u64 v[232:233], v[132:133], 1, v[232:233]
	v_lshl_add_u64 v[232:233], v[232:233], 0, s[20:21]
	global_load_dwordx2 v[158:159], v[232:233], off
	s_waitcnt vmcnt(12)
; DI u32 pack2(float a, float b) { f2_t v = {a, b}; bf2_t r = __builtin_convertvector(v, bf2_t); return __builtin_bit_cast(u32, r); }
; DI float bflo(u32 v) { return __uint_as_float(v << 16); }
; DI float bfhi(u32 v) { return __uint_as_float(v & 0xffff0000u); }
; DI float sigmoidf_(float x) { return __builtin_amdgcn_rcpf(1.f + __builtin_amdgcn_exp2f(-LOG2E * x)); }
; DI void branch_tile8(const Params& P, const WsPtrs& W, int layer, int mt, int nt, unsigned char* smem) {
;     ...
;     const float* gbp = P.in[I_GATEB] + layer * 4096 + jb * 1024;
; #pragma unroll
;     for (int bj = 0; bj < 2; ++bj)
; #pragma unroll
;       for (int n = 0; n < 2; ++n) {
;         const int row = m0 + bj * 128 + wc * 32 + n * 16 + fr;
;         const u16* gp = W.Y + (size_t)row * LDY + O_GT + jb * 1024;
;         u16* mp = W.MERGED + (size_t)row * 1024;
; #pragma unroll
;         for (int ai = 0; ai < 2; ++ai)
; #pragma unroll
;           for (int m = 0; m < 4; ++m) {
;             const int f = n0 + ai * 128 + wr * 64 + m * 16 + fq * 4;
;             const u32x2 gv = *(const u32x2*)(gp + f);
;             const f32x4 b4 = *(const f32x4*)(gbp + f);
;             f32x4v a = acc[ai][bj][m][n];
;             float v0 = sigmoidf_(bflo(gv.x) + b4.x) * a.x, v1 = sigmoidf_(bfhi(gv.x) + b4.y) * a.y;
;             float v2 = sigmoidf_(bflo(gv.y) + b4.z) * a.z, v3 = sigmoidf_(bfhi(gv.y) + b4.w) * a.w;
;             if (jb > 0) { const u32x2 pv = *(const u32x2*)(mp + f); v0 += bflo(pv.x); v1 += bfhi(pv.x); v2 += bflo(pv.y); v3 += bfhi(pv.y); }
;             u32x2 o2; o2.x = pack2(v0, v1); o2.y = pack2(v2, v3);
;             *(u32x2*)(mp + f) = o2;
;           }
;       }
	v_lshlrev_b32_e32 v138, 16, v214
	v_and_b32_e32 v139, 0xffff0000, v214
	v_lshlrev_b32_e32 v140, 16, v215
	v_and_b32_e32 v141, 0xffff0000, v215
	v_add_f32_e32 v138, v168, v138
	v_add_f32_e32 v139, v169, v139
	v_add_f32_e32 v140, v170, v140
	v_add_f32_e32 v141, v171, v141
	v_mul_f32_e32 v138, 0xbfb8aa3b, v138
	v_mul_f32_e32 v139, 0xbfb8aa3b, v139
	v_mul_f32_e32 v140, 0xbfb8aa3b, v140
	v_mul_f32_e32 v141, 0xbfb8aa3b, v141
	v_exp_f32_e32 v138, v138
	v_exp_f32_e32 v139, v139
	v_exp_f32_e32 v140, v140
	v_exp_f32_e32 v141, v141
	v_add_f32_e32 v138, 1.0, v138
	v_add_f32_e32 v139, 1.0, v139
	v_add_f32_e32 v140, 1.0, v140
	v_add_f32_e32 v141, 1.0, v141
	v_rcp_f32_e32 v138, v138
	v_rcp_f32_e32 v139, v139
	v_rcp_f32_e32 v140, v140
	v_rcp_f32_e32 v141, v141
	s_nop 0
	v_pk_mul_f32 v[94:95], v[94:95], v[138:139]
	v_pk_mul_f32 v[96:97], v[96:97], v[140:141]
	v_cvt_pk_bf16_f32 v146, v94, v95
	v_cvt_pk_bf16_f32 v147, v96, v97
	global_load_dwordx2 v[162:163], v[232:233], off offset:32
	s_waitcnt vmcnt(12)
	v_lshlrev_b32_e32 v138, 16, v216
	v_and_b32_e32 v139, 0xffff0000, v216
	v_lshlrev_b32_e32 v140, 16, v217
	v_and_b32_e32 v141, 0xffff0000, v217
	v_add_f32_e32 v138, v172, v138
	v_add_f32_e32 v139, v173, v139
	v_add_f32_e32 v140, v174, v140
	v_add_f32_e32 v141, v175, v141
	v_mul_f32_e32 v138, 0xbfb8aa3b, v138
	v_mul_f32_e32 v139, 0xbfb8aa3b, v139
	v_mul_f32_e32 v140, 0xbfb8aa3b, v140
	v_mul_f32_e32 v141, 0xbfb8aa3b, v141
	v_exp_f32_e32 v138, v138
	v_exp_f32_e32 v139, v139
	v_exp_f32_e32 v140, v140
	v_exp_f32_e32 v141, v141
	v_add_f32_e32 v138, 1.0, v138
	v_add_f32_e32 v139, 1.0, v139
	v_add_f32_e32 v140, 1.0, v140
	v_add_f32_e32 v141, 1.0, v141
	v_rcp_f32_e32 v138, v138
	v_rcp_f32_e32 v139, v139
	v_rcp_f32_e32 v140, v140
	v_rcp_f32_e32 v141, v141
	s_nop 0
	v_pk_mul_f32 v[90:91], v[90:91], v[138:139]
	v_pk_mul_f32 v[92:93], v[92:93], v[140:141]
	v_cvt_pk_bf16_f32 v148, v90, v91
	v_cvt_pk_bf16_f32 v149, v92, v93
	v_lshl_add_u64 v[154:155], v[212:213], 0, v[136:137]
	s_nop 1
	v_permlane16_swap_b32_e32 v146, v148
	v_permlane16_swap_b32_e32 v147, v149
	global_store_dwordx4 v[154:155], v[146:149], off
	global_load_dwordx2 v[126:127], v[232:233], off offset:64
	s_waitcnt vmcnt(12)
	v_lshlrev_b32_e32 v138, 16, v218
	v_and_b32_e32 v139, 0xffff0000, v218
	v_lshlrev_b32_e32 v140, 16, v219
	v_and_b32_e32 v141, 0xffff0000, v219
	v_add_f32_e32 v138, v176, v138
	v_add_f32_e32 v139, v177, v139
	v_add_f32_e32 v140, v178, v140
	v_add_f32_e32 v141, v179, v141
	v_mul_f32_e32 v138, 0xbfb8aa3b, v138
	v_mul_f32_e32 v139, 0xbfb8aa3b, v139
	v_mul_f32_e32 v140, 0xbfb8aa3b, v140
	v_mul_f32_e32 v141, 0xbfb8aa3b, v141
	v_exp_f32_e32 v138, v138
	v_exp_f32_e32 v139, v139
	v_exp_f32_e32 v140, v140
	v_exp_f32_e32 v141, v141
	v_add_f32_e32 v138, 1.0, v138
	v_add_f32_e32 v139, 1.0, v139
	v_add_f32_e32 v140, 1.0, v140
	v_add_f32_e32 v141, 1.0, v141
	v_rcp_f32_e32 v138, v138
	v_rcp_f32_e32 v139, v139
	v_rcp_f32_e32 v140, v140
	v_rcp_f32_e32 v141, v141
	s_nop 0
	v_pk_mul_f32 v[86:87], v[86:87], v[138:139]
	v_pk_mul_f32 v[88:89], v[88:89], v[140:141]
	v_cvt_pk_bf16_f32 v150, v86, v87
	v_cvt_pk_bf16_f32 v151, v88, v89
	global_load_dwordx2 v[128:129], v[232:233], off offset:96
	s_waitcnt vmcnt(12)
	v_lshlrev_b32_e32 v138, 16, v220
	v_and_b32_e32 v139, 0xffff0000, v220
	v_lshlrev_b32_e32 v140, 16, v221
	v_and_b32_e32 v141, 0xffff0000, v221
	v_add_f32_e32 v138, v180, v138
	v_add_f32_e32 v139, v181, v139
	v_add_f32_e32 v140, v182, v140
	v_add_f32_e32 v141, v183, v141
	v_mul_f32_e32 v138, 0xbfb8aa3b, v138
	v_mul_f32_e32 v139, 0xbfb8aa3b, v139
	v_mul_f32_e32 v140, 0xbfb8aa3b, v140
	v_mul_f32_e32 v141, 0xbfb8aa3b, v141
	v_exp_f32_e32 v138, v138
	v_exp_f32_e32 v139, v139
	v_exp_f32_e32 v140, v140
	v_exp_f32_e32 v141, v141
	v_add_f32_e32 v138, 1.0, v138
	v_add_f32_e32 v139, 1.0, v139
	v_add_f32_e32 v140, 1.0, v140
	v_add_f32_e32 v141, 1.0, v141
	v_rcp_f32_e32 v138, v138
	v_rcp_f32_e32 v139, v139
	v_rcp_f32_e32 v140, v140
	v_rcp_f32_e32 v141, v141
	s_nop 0
	v_pk_mul_f32 v[82:83], v[82:83], v[138:139]
	v_pk_mul_f32 v[84:85], v[84:85], v[140:141]
	v_cvt_pk_bf16_f32 v152, v82, v83
	v_cvt_pk_bf16_f32 v153, v84, v85
	v_lshl_add_u64 v[154:155], v[212:213], 0, v[136:137]
	s_nop 1
	v_permlane16_swap_b32_e32 v150, v152
	v_permlane16_swap_b32_e32 v151, v153
	global_store_dwordx4 v[154:155], v[150:153], off offset:64
	global_load_dwordx2 v[164:165], v[232:233], off offset:256
	s_waitcnt vmcnt(12)
	v_lshlrev_b32_e32 v138, 16, v222
	v_and_b32_e32 v139, 0xffff0000, v222
	v_lshlrev_b32_e32 v140, 16, v223
	v_and_b32_e32 v141, 0xffff0000, v223
	v_add_f32_e32 v138, v184, v138
	v_add_f32_e32 v139, v185, v139
	v_add_f32_e32 v140, v186, v140
	v_add_f32_e32 v141, v187, v141
	v_mul_f32_e32 v138, 0xbfb8aa3b, v138
	v_mul_f32_e32 v139, 0xbfb8aa3b, v139
	v_mul_f32_e32 v140, 0xbfb8aa3b, v140
	v_mul_f32_e32 v141, 0xbfb8aa3b, v141
	v_exp_f32_e32 v138, v138
	v_exp_f32_e32 v139, v139
	v_exp_f32_e32 v140, v140
	v_exp_f32_e32 v141, v141
	v_add_f32_e32 v138, 1.0, v138
	v_add_f32_e32 v139, 1.0, v139
	v_add_f32_e32 v140, 1.0, v140
	v_add_f32_e32 v141, 1.0, v141
	v_rcp_f32_e32 v138, v138
	v_rcp_f32_e32 v139, v139
	v_rcp_f32_e32 v140, v140
	v_rcp_f32_e32 v141, v141
	s_nop 0
	v_pk_mul_f32 v[78:79], v[78:79], v[138:139]
	v_pk_mul_f32 v[80:81], v[80:81], v[140:141]
	v_cvt_pk_bf16_f32 v146, v78, v79
	v_cvt_pk_bf16_f32 v147, v80, v81
	global_load_dwordx2 v[122:123], v[232:233], off offset:288
	s_waitcnt vmcnt(12)
; DI u32 pack2(float a, float b) { f2_t v = {a, b}; bf2_t r = __builtin_convertvector(v, bf2_t); return __builtin_bit_cast(u32, r); }
; DI float bflo(u32 v) { return __uint_as_float(v << 16); }
; DI float bfhi(u32 v) { return __uint_as_float(v & 0xffff0000u); }
; DI float sigmoidf_(float x) { return __builtin_amdgcn_rcpf(1.f + __builtin_amdgcn_exp2f(-LOG2E * x)); }
; DI void branch_tile8(const Params& P, const WsPtrs& W, int layer, int mt, int nt, unsigned char* smem) {
;     ...
;     const float* gbp = P.in[I_GATEB] + layer * 4096 + jb * 1024;
; #pragma unroll
;     for (int bj = 0; bj < 2; ++bj)
; #pragma unroll
;       for (int n = 0; n < 2; ++n) {
;         const int row = m0 + bj * 128 + wc * 32 + n * 16 + fr;
;         const u16* gp = W.Y + (size_t)row * LDY + O_GT + jb * 1024;
;         u16* mp = W.MERGED + (size_t)row * 1024;
; #pragma unroll
;         for (int ai = 0; ai < 2; ++ai)
; #pragma unroll
;           for (int m = 0; m < 4; ++m) {
;             const int f = n0 + ai * 128 + wr * 64 + m * 16 + fq * 4;
;             const u32x2 gv = *(const u32x2*)(gp + f);
;             const f32x4 b4 = *(const f32x4*)(gbp + f);
;             f32x4v a = acc[ai][bj][m][n];
;             float v0 = sigmoidf_(bflo(gv.x) + b4.x) * a.x, v1 = sigmoidf_(bfhi(gv.x) + b4.y) * a.y;
;             float v2 = sigmoidf_(bflo(gv.y) + b4.z) * a.z, v3 = sigmoidf_(bfhi(gv.y) + b4.w) * a.w;
;             if (jb > 0) { const u32x2 pv = *(const u32x2*)(mp + f); v0 += bflo(pv.x); v1 += bfhi(pv.x); v2 += bflo(pv.y); v3 += bfhi(pv.y); }
;             u32x2 o2; o2.x = pack2(v0, v1); o2.y = pack2(v2, v3);
;             *(u32x2*)(mp + f) = o2;
;           }
;       }
	v_lshlrev_b32_e32 v138, 16, v224
	v_and_b32_e32 v139, 0xffff0000, v224
	v_lshlrev_b32_e32 v140, 16, v225
	v_and_b32_e32 v141, 0xffff0000, v225
	v_add_f32_e32 v138, v188, v138
	v_add_f32_e32 v139, v189, v139
	v_add_f32_e32 v140, v190, v140
	v_add_f32_e32 v141, v191, v141
	v_mul_f32_e32 v138, 0xbfb8aa3b, v138
	v_mul_f32_e32 v139, 0xbfb8aa3b, v139
	v_mul_f32_e32 v140, 0xbfb8aa3b, v140
	v_mul_f32_e32 v141, 0xbfb8aa3b, v141
	v_exp_f32_e32 v138, v138
	v_exp_f32_e32 v139, v139
	v_exp_f32_e32 v140, v140
	v_exp_f32_e32 v141, v141
	v_add_f32_e32 v138, 1.0, v138
	v_add_f32_e32 v139, 1.0, v139
	v_add_f32_e32 v140, 1.0, v140
	v_add_f32_e32 v141, 1.0, v141
	v_rcp_f32_e32 v138, v138
	v_rcp_f32_e32 v139, v139
	v_rcp_f32_e32 v140, v140
	v_rcp_f32_e32 v141, v141
	s_nop 0
	v_pk_mul_f32 v[74:75], v[74:75], v[138:139]
	v_pk_mul_f32 v[76:77], v[76:77], v[140:141]
	v_cvt_pk_bf16_f32 v148, v74, v75
	v_cvt_pk_bf16_f32 v149, v76, v77
	v_lshl_add_u64 v[154:155], v[212:213], 0, v[136:137]
	s_nop 1
	v_permlane16_swap_b32_e32 v146, v148
	v_permlane16_swap_b32_e32 v147, v149
	global_store_dwordx4 v[154:155], v[146:149], off offset:256
	global_load_dwordx2 v[124:125], v[232:233], off offset:320
	s_waitcnt vmcnt(12)
	v_lshlrev_b32_e32 v138, 16, v226
	v_and_b32_e32 v139, 0xffff0000, v226
	v_lshlrev_b32_e32 v140, 16, v227
	v_and_b32_e32 v141, 0xffff0000, v227
	v_add_f32_e32 v138, v192, v138
	v_add_f32_e32 v139, v193, v139
	v_add_f32_e32 v140, v194, v140
	v_add_f32_e32 v141, v195, v141
	v_mul_f32_e32 v138, 0xbfb8aa3b, v138
	v_mul_f32_e32 v139, 0xbfb8aa3b, v139
	v_mul_f32_e32 v140, 0xbfb8aa3b, v140
	v_mul_f32_e32 v141, 0xbfb8aa3b, v141
	v_exp_f32_e32 v138, v138
	v_exp_f32_e32 v139, v139
	v_exp_f32_e32 v140, v140
	v_exp_f32_e32 v141, v141
	v_add_f32_e32 v138, 1.0, v138
	v_add_f32_e32 v139, 1.0, v139
	v_add_f32_e32 v140, 1.0, v140
	v_add_f32_e32 v141, 1.0, v141
	v_rcp_f32_e32 v138, v138
	v_rcp_f32_e32 v139, v139
	v_rcp_f32_e32 v140, v140
	v_rcp_f32_e32 v141, v141
	s_nop 0
	v_pk_mul_f32 v[70:71], v[70:71], v[138:139]
	v_pk_mul_f32 v[72:73], v[72:73], v[140:141]
	v_cvt_pk_bf16_f32 v150, v70, v71
	v_cvt_pk_bf16_f32 v151, v72, v73
	global_load_dwordx2 v[166:167], v[232:233], off offset:352
	s_waitcnt vmcnt(12)
	v_lshlrev_b32_e32 v138, 16, v230
	v_and_b32_e32 v139, 0xffff0000, v230
	v_lshlrev_b32_e32 v140, 16, v231
	v_and_b32_e32 v141, 0xffff0000, v231
	v_add_f32_e32 v138, v196, v138
	v_add_f32_e32 v139, v197, v139
	v_add_f32_e32 v140, v198, v140
	v_add_f32_e32 v141, v199, v141
	v_mul_f32_e32 v138, 0xbfb8aa3b, v138
	v_mul_f32_e32 v139, 0xbfb8aa3b, v139
	v_mul_f32_e32 v140, 0xbfb8aa3b, v140
	v_mul_f32_e32 v141, 0xbfb8aa3b, v141
	v_exp_f32_e32 v138, v138
	v_exp_f32_e32 v139, v139
	v_exp_f32_e32 v140, v140
	v_exp_f32_e32 v141, v141
	v_add_f32_e32 v138, 1.0, v138
	v_add_f32_e32 v139, 1.0, v139
	v_add_f32_e32 v140, 1.0, v140
	v_add_f32_e32 v141, 1.0, v141
	v_rcp_f32_e32 v138, v138
	v_rcp_f32_e32 v139, v139
	v_rcp_f32_e32 v140, v140
	v_rcp_f32_e32 v141, v141
	s_nop 0
	v_pk_mul_f32 v[66:67], v[66:67], v[138:139]
	v_pk_mul_f32 v[68:69], v[68:69], v[140:141]
	v_cvt_pk_bf16_f32 v152, v66, v67
	v_cvt_pk_bf16_f32 v153, v68, v69
	v_lshl_add_u64 v[154:155], v[212:213], 0, v[136:137]
	s_nop 1
	v_permlane16_swap_b32_e32 v150, v152
	v_permlane16_swap_b32_e32 v151, v153
	global_store_dwordx4 v[154:155], v[150:153], off offset:320
	v_or_b32_e32 v156, 0x90, v134
	v_ashrrev_i32_e32 v157, 31, v156
	v_mov_b64_e32 v[118:119], s[8:9]
	v_lshlrev_b64 v[120:121], 11, v[156:157]
	v_mad_i64_i32 v[118:119], s[22:23], v156, s33, v[118:119]
	v_lshl_add_u64 v[120:121], s[10:11], 0, v[120:121]
	v_lshl_add_u64 v[118:119], v[118:119], 0, s[2:3]
	v_lshl_add_u64 v[120:121], v[132:133], 1, v[120:121]
	v_lshl_add_u64 v[118:119], v[132:133], 1, v[118:119]
	v_lshl_add_u64 v[118:119], v[118:119], 0, s[20:21]
	global_load_dwordx2 v[200:201], v[118:119], off
	s_waitcnt vmcnt(12)
	v_lshlrev_b32_e32 v138, 16, v158
	v_and_b32_e32 v139, 0xffff0000, v158
	v_lshlrev_b32_e32 v140, 16, v159
	v_and_b32_e32 v141, 0xffff0000, v159
	v_add_f32_e32 v138, v168, v138
	v_add_f32_e32 v139, v169, v139
	v_add_f32_e32 v140, v170, v140
	v_add_f32_e32 v141, v171, v141
	v_mul_f32_e32 v138, 0xbfb8aa3b, v138
	v_mul_f32_e32 v139, 0xbfb8aa3b, v139
	v_mul_f32_e32 v140, 0xbfb8aa3b, v140
	v_mul_f32_e32 v141, 0xbfb8aa3b, v141
	v_exp_f32_e32 v138, v138
	v_exp_f32_e32 v139, v139
	v_exp_f32_e32 v140, v140
	v_exp_f32_e32 v141, v141
	v_add_f32_e32 v138, 1.0, v138
	v_add_f32_e32 v139, 1.0, v139
	v_add_f32_e32 v140, 1.0, v140
	v_add_f32_e32 v141, 1.0, v141
	v_rcp_f32_e32 v138, v138
	v_rcp_f32_e32 v139, v139
	v_rcp_f32_e32 v140, v140
	v_rcp_f32_e32 v141, v141
	s_nop 0
	v_pk_mul_f32 v[62:63], v[62:63], v[138:139]
	v_pk_mul_f32 v[64:65], v[64:65], v[140:141]
	v_cvt_pk_bf16_f32 v146, v62, v63
	v_cvt_pk_bf16_f32 v147, v64, v65
	global_load_dwordx2 v[114:115], v[118:119], off offset:32
	s_waitcnt vmcnt(12)
	v_lshlrev_b32_e32 v138, 16, v162
	v_and_b32_e32 v139, 0xffff0000, v162
	v_lshlrev_b32_e32 v140, 16, v163
	v_and_b32_e32 v141, 0xffff0000, v163
	v_add_f32_e32 v138, v172, v138
	v_add_f32_e32 v139, v173, v139
	v_add_f32_e32 v140, v174, v140
	v_add_f32_e32 v141, v175, v141
	v_mul_f32_e32 v138, 0xbfb8aa3b, v138
	v_mul_f32_e32 v139, 0xbfb8aa3b, v139
	v_mul_f32_e32 v140, 0xbfb8aa3b, v140
	v_mul_f32_e32 v141, 0xbfb8aa3b, v141
	v_exp_f32_e32 v138, v138
	v_exp_f32_e32 v139, v139
	v_exp_f32_e32 v140, v140
	v_exp_f32_e32 v141, v141
	v_add_f32_e32 v138, 1.0, v138
	v_add_f32_e32 v139, 1.0, v139
	v_add_f32_e32 v140, 1.0, v140
	v_add_f32_e32 v141, 1.0, v141
	v_rcp_f32_e32 v138, v138
	v_rcp_f32_e32 v139, v139
	v_rcp_f32_e32 v140, v140
	v_rcp_f32_e32 v141, v141
	s_nop 0
	v_pk_mul_f32 v[58:59], v[58:59], v[138:139]
	v_pk_mul_f32 v[60:61], v[60:61], v[140:141]
	v_cvt_pk_bf16_f32 v148, v58, v59
	v_cvt_pk_bf16_f32 v149, v60, v61
	v_lshl_add_u64 v[154:155], v[238:239], 0, v[136:137]
	s_nop 1
	v_permlane16_swap_b32_e32 v146, v148
	v_permlane16_swap_b32_e32 v147, v149
	global_store_dwordx4 v[154:155], v[146:149], off
	global_load_dwordx2 v[116:117], v[118:119], off offset:64
	s_waitcnt vmcnt(12)
; DI u32 pack2(float a, float b) { f2_t v = {a, b}; bf2_t r = __builtin_convertvector(v, bf2_t); return __builtin_bit_cast(u32, r); }
; DI float bflo(u32 v) { return __uint_as_float(v << 16); }
; DI float bfhi(u32 v) { return __uint_as_float(v & 0xffff0000u); }
; DI float sigmoidf_(float x) { return __builtin_amdgcn_rcpf(1.f + __builtin_amdgcn_exp2f(-LOG2E * x)); }
; DI void branch_tile8(const Params& P, const WsPtrs& W, int layer, int mt, int nt, unsigned char* smem) {
;     ...
;     const float* gbp = P.in[I_GATEB] + layer * 4096 + jb * 1024;
; #pragma unroll
;     for (int bj = 0; bj < 2; ++bj)
; #pragma unroll
;       for (int n = 0; n < 2; ++n) {
;         const int row = m0 + bj * 128 + wc * 32 + n * 16 + fr;
;         const u16* gp = W.Y + (size_t)row * LDY + O_GT + jb * 1024;
;         u16* mp = W.MERGED + (size_t)row * 1024;
; #pragma unroll
;         for (int ai = 0; ai < 2; ++ai)
; #pragma unroll
;           for (int m = 0; m < 4; ++m) {
;             const int f = n0 + ai * 128 + wr * 64 + m * 16 + fq * 4;
;             const u32x2 gv = *(const u32x2*)(gp + f);
;             const f32x4 b4 = *(const f32x4*)(gbp + f);
;             f32x4v a = acc[ai][bj][m][n];
;             float v0 = sigmoidf_(bflo(gv.x) + b4.x) * a.x, v1 = sigmoidf_(bfhi(gv.x) + b4.y) * a.y;
;             float v2 = sigmoidf_(bflo(gv.y) + b4.z) * a.z, v3 = sigmoidf_(bfhi(gv.y) + b4.w) * a.w;
;             if (jb > 0) { const u32x2 pv = *(const u32x2*)(mp + f); v0 += bflo(pv.x); v1 += bfhi(pv.x); v2 += bflo(pv.y); v3 += bfhi(pv.y); }
;             u32x2 o2; o2.x = pack2(v0, v1); o2.y = pack2(v2, v3);
;             *(u32x2*)(mp + f) = o2;
;           }
;       }
	v_lshlrev_b32_e32 v138, 16, v126
	v_and_b32_e32 v139, 0xffff0000, v126
	v_lshlrev_b32_e32 v140, 16, v127
	v_and_b32_e32 v141, 0xffff0000, v127
	v_add_f32_e32 v138, v176, v138
	v_add_f32_e32 v139, v177, v139
	v_add_f32_e32 v140, v178, v140
	v_add_f32_e32 v141, v179, v141
	v_mul_f32_e32 v138, 0xbfb8aa3b, v138
	v_mul_f32_e32 v139, 0xbfb8aa3b, v139
	v_mul_f32_e32 v140, 0xbfb8aa3b, v140
	v_mul_f32_e32 v141, 0xbfb8aa3b, v141
	v_exp_f32_e32 v138, v138
	v_exp_f32_e32 v139, v139
	v_exp_f32_e32 v140, v140
	v_exp_f32_e32 v141, v141
	v_add_f32_e32 v138, 1.0, v138
	v_add_f32_e32 v139, 1.0, v139
	v_add_f32_e32 v140, 1.0, v140
	v_add_f32_e32 v141, 1.0, v141
	v_rcp_f32_e32 v138, v138
	v_rcp_f32_e32 v139, v139
	v_rcp_f32_e32 v140, v140
	v_rcp_f32_e32 v141, v141
	s_nop 0
	v_pk_mul_f32 v[54:55], v[54:55], v[138:139]
	v_pk_mul_f32 v[56:57], v[56:57], v[140:141]
	v_cvt_pk_bf16_f32 v150, v54, v55
	v_cvt_pk_bf16_f32 v151, v56, v57
	global_load_dwordx2 v[202:203], v[118:119], off offset:96
	s_waitcnt vmcnt(12)
	v_lshlrev_b32_e32 v138, 16, v128
	v_and_b32_e32 v139, 0xffff0000, v128
	v_lshlrev_b32_e32 v140, 16, v129
	v_and_b32_e32 v141, 0xffff0000, v129
	v_add_f32_e32 v138, v180, v138
	v_add_f32_e32 v139, v181, v139
	v_add_f32_e32 v140, v182, v140
	v_add_f32_e32 v141, v183, v141
	v_mul_f32_e32 v138, 0xbfb8aa3b, v138
	v_mul_f32_e32 v139, 0xbfb8aa3b, v139
	v_mul_f32_e32 v140, 0xbfb8aa3b, v140
	v_mul_f32_e32 v141, 0xbfb8aa3b, v141
	v_exp_f32_e32 v138, v138
	v_exp_f32_e32 v139, v139
	v_exp_f32_e32 v140, v140
	v_exp_f32_e32 v141, v141
	v_add_f32_e32 v138, 1.0, v138
	v_add_f32_e32 v139, 1.0, v139
	v_add_f32_e32 v140, 1.0, v140
	v_add_f32_e32 v141, 1.0, v141
	v_rcp_f32_e32 v138, v138
	v_rcp_f32_e32 v139, v139
	v_rcp_f32_e32 v140, v140
	v_rcp_f32_e32 v141, v141
	s_nop 0
	v_pk_mul_f32 v[50:51], v[50:51], v[138:139]
	v_pk_mul_f32 v[52:53], v[52:53], v[140:141]
	v_cvt_pk_bf16_f32 v152, v50, v51
	v_cvt_pk_bf16_f32 v153, v52, v53
	v_lshl_add_u64 v[154:155], v[238:239], 0, v[136:137]
	s_nop 1
	v_permlane16_swap_b32_e32 v150, v152
	v_permlane16_swap_b32_e32 v151, v153
	global_store_dwordx4 v[154:155], v[150:153], off offset:64
	global_load_dwordx2 v[110:111], v[118:119], off offset:256
	s_waitcnt vmcnt(12)
	v_lshlrev_b32_e32 v138, 16, v164
	v_and_b32_e32 v139, 0xffff0000, v164
	v_lshlrev_b32_e32 v140, 16, v165
	v_and_b32_e32 v141, 0xffff0000, v165
	v_add_f32_e32 v138, v184, v138
	v_add_f32_e32 v139, v185, v139
	v_add_f32_e32 v140, v186, v140
	v_add_f32_e32 v141, v187, v141
	v_mul_f32_e32 v138, 0xbfb8aa3b, v138
	v_mul_f32_e32 v139, 0xbfb8aa3b, v139
	v_mul_f32_e32 v140, 0xbfb8aa3b, v140
	v_mul_f32_e32 v141, 0xbfb8aa3b, v141
	v_exp_f32_e32 v138, v138
	v_exp_f32_e32 v139, v139
	v_exp_f32_e32 v140, v140
	v_exp_f32_e32 v141, v141
	v_add_f32_e32 v138, 1.0, v138
	v_add_f32_e32 v139, 1.0, v139
	v_add_f32_e32 v140, 1.0, v140
	v_add_f32_e32 v141, 1.0, v141
	v_rcp_f32_e32 v138, v138
	v_rcp_f32_e32 v139, v139
	v_rcp_f32_e32 v140, v140
	v_rcp_f32_e32 v141, v141
	s_nop 0
	v_pk_mul_f32 v[46:47], v[46:47], v[138:139]
	v_pk_mul_f32 v[48:49], v[48:49], v[140:141]
	v_cvt_pk_bf16_f32 v146, v46, v47
	v_cvt_pk_bf16_f32 v147, v48, v49
	global_load_dwordx2 v[112:113], v[118:119], off offset:288
	s_waitcnt vmcnt(12)
	v_lshlrev_b32_e32 v138, 16, v122
	v_and_b32_e32 v139, 0xffff0000, v122
	v_lshlrev_b32_e32 v140, 16, v123
	v_and_b32_e32 v141, 0xffff0000, v123
	v_add_f32_e32 v138, v188, v138
	v_add_f32_e32 v139, v189, v139
	v_add_f32_e32 v140, v190, v140
	v_add_f32_e32 v141, v191, v141
	v_mul_f32_e32 v138, 0xbfb8aa3b, v138
	v_mul_f32_e32 v139, 0xbfb8aa3b, v139
	v_mul_f32_e32 v140, 0xbfb8aa3b, v140
	v_mul_f32_e32 v141, 0xbfb8aa3b, v141
	v_exp_f32_e32 v138, v138
	v_exp_f32_e32 v139, v139
	v_exp_f32_e32 v140, v140
	v_exp_f32_e32 v141, v141
	v_add_f32_e32 v138, 1.0, v138
	v_add_f32_e32 v139, 1.0, v139
	v_add_f32_e32 v140, 1.0, v140
	v_add_f32_e32 v141, 1.0, v141
	v_rcp_f32_e32 v138, v138
	v_rcp_f32_e32 v139, v139
	v_rcp_f32_e32 v140, v140
	v_rcp_f32_e32 v141, v141
	s_nop 0
	v_pk_mul_f32 v[42:43], v[42:43], v[138:139]
	v_pk_mul_f32 v[44:45], v[44:45], v[140:141]
	v_cvt_pk_bf16_f32 v148, v42, v43
	v_cvt_pk_bf16_f32 v149, v44, v45
	v_lshl_add_u64 v[154:155], v[238:239], 0, v[136:137]
	s_nop 1
	v_permlane16_swap_b32_e32 v146, v148
	v_permlane16_swap_b32_e32 v147, v149
	global_store_dwordx4 v[154:155], v[146:149], off offset:256
	global_load_dwordx2 v[204:205], v[118:119], off offset:320
	s_waitcnt vmcnt(12)
	v_lshlrev_b32_e32 v138, 16, v124
	v_and_b32_e32 v139, 0xffff0000, v124
	v_lshlrev_b32_e32 v140, 16, v125
	v_and_b32_e32 v141, 0xffff0000, v125
	v_add_f32_e32 v138, v192, v138
	v_add_f32_e32 v139, v193, v139
	v_add_f32_e32 v140, v194, v140
	v_add_f32_e32 v141, v195, v141
	v_mul_f32_e32 v138, 0xbfb8aa3b, v138
	v_mul_f32_e32 v139, 0xbfb8aa3b, v139
	v_mul_f32_e32 v140, 0xbfb8aa3b, v140
	v_mul_f32_e32 v141, 0xbfb8aa3b, v141
	v_exp_f32_e32 v138, v138
	v_exp_f32_e32 v139, v139
	v_exp_f32_e32 v140, v140
	v_exp_f32_e32 v141, v141
	v_add_f32_e32 v138, 1.0, v138
	v_add_f32_e32 v139, 1.0, v139
	v_add_f32_e32 v140, 1.0, v140
	v_add_f32_e32 v141, 1.0, v141
	v_rcp_f32_e32 v138, v138
	v_rcp_f32_e32 v139, v139
	v_rcp_f32_e32 v140, v140
	v_rcp_f32_e32 v141, v141
	s_nop 0
	v_pk_mul_f32 v[38:39], v[38:39], v[138:139]
	v_pk_mul_f32 v[40:41], v[40:41], v[140:141]
	v_cvt_pk_bf16_f32 v150, v38, v39
	v_cvt_pk_bf16_f32 v151, v40, v41
	global_load_dwordx2 v[106:107], v[118:119], off offset:352
	s_waitcnt vmcnt(12)
; DI u32 pack2(float a, float b) { f2_t v = {a, b}; bf2_t r = __builtin_convertvector(v, bf2_t); return __builtin_bit_cast(u32, r); }
; DI float bflo(u32 v) { return __uint_as_float(v << 16); }
; DI float bfhi(u32 v) { return __uint_as_float(v & 0xffff0000u); }
; DI float sigmoidf_(float x) { return __builtin_amdgcn_rcpf(1.f + __builtin_amdgcn_exp2f(-LOG2E * x)); }
; DI void branch_tile8(const Params& P, const WsPtrs& W, int layer, int mt, int nt, unsigned char* smem) {
;     ...
;     const float* gbp = P.in[I_GATEB] + layer * 4096 + jb * 1024;
; #pragma unroll
;     for (int bj = 0; bj < 2; ++bj)
; #pragma unroll
;       for (int n = 0; n < 2; ++n) {
;         const int row = m0 + bj * 128 + wc * 32 + n * 16 + fr;
;         const u16* gp = W.Y + (size_t)row * LDY + O_GT + jb * 1024;
;         u16* mp = W.MERGED + (size_t)row * 1024;
; #pragma unroll
;         for (int ai = 0; ai < 2; ++ai)
; #pragma unroll
;           for (int m = 0; m < 4; ++m) {
;             const int f = n0 + ai * 128 + wr * 64 + m * 16 + fq * 4;
;             const u32x2 gv = *(const u32x2*)(gp + f);
;             const f32x4 b4 = *(const f32x4*)(gbp + f);
;             f32x4v a = acc[ai][bj][m][n];
;             float v0 = sigmoidf_(bflo(gv.x) + b4.x) * a.x, v1 = sigmoidf_(bfhi(gv.x) + b4.y) * a.y;
;             float v2 = sigmoidf_(bflo(gv.y) + b4.z) * a.z, v3 = sigmoidf_(bfhi(gv.y) + b4.w) * a.w;
;             if (jb > 0) { const u32x2 pv = *(const u32x2*)(mp + f); v0 += bflo(pv.x); v1 += bfhi(pv.x); v2 += bflo(pv.y); v3 += bfhi(pv.y); }
;             u32x2 o2; o2.x = pack2(v0, v1); o2.y = pack2(v2, v3);
;             *(u32x2*)(mp + f) = o2;
;           }
;       }
	v_lshlrev_b32_e32 v138, 16, v166
	v_and_b32_e32 v139, 0xffff0000, v166
	v_lshlrev_b32_e32 v140, 16, v167
	v_and_b32_e32 v141, 0xffff0000, v167
	v_add_f32_e32 v138, v196, v138
	v_add_f32_e32 v139, v197, v139
	v_add_f32_e32 v140, v198, v140
	v_add_f32_e32 v141, v199, v141
	v_mul_f32_e32 v138, 0xbfb8aa3b, v138
	v_mul_f32_e32 v139, 0xbfb8aa3b, v139
	v_mul_f32_e32 v140, 0xbfb8aa3b, v140
	v_mul_f32_e32 v141, 0xbfb8aa3b, v141
	v_exp_f32_e32 v138, v138
	v_exp_f32_e32 v139, v139
	v_exp_f32_e32 v140, v140
	v_exp_f32_e32 v141, v141
	v_add_f32_e32 v138, 1.0, v138
	v_add_f32_e32 v139, 1.0, v139
	v_add_f32_e32 v140, 1.0, v140
	v_add_f32_e32 v141, 1.0, v141
	v_rcp_f32_e32 v138, v138
	v_rcp_f32_e32 v139, v139
	v_rcp_f32_e32 v140, v140
	v_rcp_f32_e32 v141, v141
	s_nop 0
	v_pk_mul_f32 v[34:35], v[34:35], v[138:139]
	v_pk_mul_f32 v[36:37], v[36:37], v[140:141]
	v_cvt_pk_bf16_f32 v152, v34, v35
	v_cvt_pk_bf16_f32 v153, v36, v37
	v_lshl_add_u64 v[154:155], v[238:239], 0, v[136:137]
	s_nop 1
	v_permlane16_swap_b32_e32 v150, v152
	v_permlane16_swap_b32_e32 v151, v153
	global_store_dwordx4 v[154:155], v[150:153], off offset:320
	s_waitcnt vmcnt(11)
	v_lshlrev_b32_e32 v138, 16, v200
	v_and_b32_e32 v139, 0xffff0000, v200
	v_lshlrev_b32_e32 v140, 16, v201
	v_and_b32_e32 v141, 0xffff0000, v201
	v_add_f32_e32 v138, v168, v138
	v_add_f32_e32 v139, v169, v139
	v_add_f32_e32 v140, v170, v140
	v_add_f32_e32 v141, v171, v141
	v_mul_f32_e32 v138, 0xbfb8aa3b, v138
	v_mul_f32_e32 v139, 0xbfb8aa3b, v139
	v_mul_f32_e32 v140, 0xbfb8aa3b, v140
	v_mul_f32_e32 v141, 0xbfb8aa3b, v141
	v_exp_f32_e32 v138, v138
	v_exp_f32_e32 v139, v139
	v_exp_f32_e32 v140, v140
	v_exp_f32_e32 v141, v141
	v_add_f32_e32 v138, 1.0, v138
	v_add_f32_e32 v139, 1.0, v139
	v_add_f32_e32 v140, 1.0, v140
	v_add_f32_e32 v141, 1.0, v141
	v_rcp_f32_e32 v138, v138
	v_rcp_f32_e32 v139, v139
	v_rcp_f32_e32 v140, v140
	v_rcp_f32_e32 v141, v141
	s_nop 0
	v_pk_mul_f32 v[30:31], v[30:31], v[138:139]
	v_pk_mul_f32 v[32:33], v[32:33], v[140:141]
	v_cvt_pk_bf16_f32 v146, v30, v31
	v_cvt_pk_bf16_f32 v147, v32, v33
	s_waitcnt vmcnt(10)
	v_lshlrev_b32_e32 v138, 16, v114
	v_and_b32_e32 v139, 0xffff0000, v114
	v_lshlrev_b32_e32 v140, 16, v115
	v_and_b32_e32 v141, 0xffff0000, v115
	v_add_f32_e32 v138, v172, v138
	v_add_f32_e32 v139, v173, v139
	v_add_f32_e32 v140, v174, v140
	v_add_f32_e32 v141, v175, v141
	v_mul_f32_e32 v138, 0xbfb8aa3b, v138
	v_mul_f32_e32 v139, 0xbfb8aa3b, v139
	v_mul_f32_e32 v140, 0xbfb8aa3b, v140
	v_mul_f32_e32 v141, 0xbfb8aa3b, v141
	v_exp_f32_e32 v138, v138
	v_exp_f32_e32 v139, v139
	v_exp_f32_e32 v140, v140
	v_exp_f32_e32 v141, v141
	v_add_f32_e32 v138, 1.0, v138
	v_add_f32_e32 v139, 1.0, v139
	v_add_f32_e32 v140, 1.0, v140
	v_add_f32_e32 v141, 1.0, v141
	v_rcp_f32_e32 v138, v138
	v_rcp_f32_e32 v139, v139
	v_rcp_f32_e32 v140, v140
	v_rcp_f32_e32 v141, v141
	s_nop 0
	v_pk_mul_f32 v[26:27], v[26:27], v[138:139]
	v_pk_mul_f32 v[28:29], v[28:29], v[140:141]
	v_cvt_pk_bf16_f32 v148, v26, v27
	v_cvt_pk_bf16_f32 v149, v28, v29
	v_lshl_add_u64 v[154:155], v[120:121], 0, v[136:137]
	s_nop 1
	v_permlane16_swap_b32_e32 v146, v148
	v_permlane16_swap_b32_e32 v147, v149
	global_store_dwordx4 v[154:155], v[146:149], off
	s_waitcnt vmcnt(9)
	v_lshlrev_b32_e32 v138, 16, v116
	v_and_b32_e32 v139, 0xffff0000, v116
	v_lshlrev_b32_e32 v140, 16, v117
	v_and_b32_e32 v141, 0xffff0000, v117
	v_add_f32_e32 v138, v176, v138
	v_add_f32_e32 v139, v177, v139
	v_add_f32_e32 v140, v178, v140
	v_add_f32_e32 v141, v179, v141
	v_mul_f32_e32 v138, 0xbfb8aa3b, v138
	v_mul_f32_e32 v139, 0xbfb8aa3b, v139
	v_mul_f32_e32 v140, 0xbfb8aa3b, v140
	v_mul_f32_e32 v141, 0xbfb8aa3b, v141
	v_exp_f32_e32 v138, v138
	v_exp_f32_e32 v139, v139
	v_exp_f32_e32 v140, v140
	v_exp_f32_e32 v141, v141
	v_add_f32_e32 v138, 1.0, v138
	v_add_f32_e32 v139, 1.0, v139
	v_add_f32_e32 v140, 1.0, v140
	v_add_f32_e32 v141, 1.0, v141
	v_rcp_f32_e32 v138, v138
	v_rcp_f32_e32 v139, v139
	v_rcp_f32_e32 v140, v140
	v_rcp_f32_e32 v141, v141
	s_nop 0
	v_pk_mul_f32 v[22:23], v[22:23], v[138:139]
	v_pk_mul_f32 v[24:25], v[24:25], v[140:141]
	v_cvt_pk_bf16_f32 v150, v22, v23
	v_cvt_pk_bf16_f32 v151, v24, v25
	s_waitcnt vmcnt(8)
; DI u32 pack2(float a, float b) { f2_t v = {a, b}; bf2_t r = __builtin_convertvector(v, bf2_t); return __builtin_bit_cast(u32, r); }
; DI float bflo(u32 v) { return __uint_as_float(v << 16); }
; DI float bfhi(u32 v) { return __uint_as_float(v & 0xffff0000u); }
; DI float sigmoidf_(float x) { return __builtin_amdgcn_rcpf(1.f + __builtin_amdgcn_exp2f(-LOG2E * x)); }
; DI void branch_tile8(const Params& P, const WsPtrs& W, int layer, int mt, int nt, unsigned char* smem) {
;     ...
;     const float* gbp = P.in[I_GATEB] + layer * 4096 + jb * 1024;
; #pragma unroll
;     for (int bj = 0; bj < 2; ++bj)
; #pragma unroll
;       for (int n = 0; n < 2; ++n) {
;         const int row = m0 + bj * 128 + wc * 32 + n * 16 + fr;
;         const u16* gp = W.Y + (size_t)row * LDY + O_GT + jb * 1024;
;         u16* mp = W.MERGED + (size_t)row * 1024;
; #pragma unroll
;         for (int ai = 0; ai < 2; ++ai)
; #pragma unroll
;           for (int m = 0; m < 4; ++m) {
;             const int f = n0 + ai * 128 + wr * 64 + m * 16 + fq * 4;
;             const u32x2 gv = *(const u32x2*)(gp + f);
;             const f32x4 b4 = *(const f32x4*)(gbp + f);
;             f32x4v a = acc[ai][bj][m][n];
;             float v0 = sigmoidf_(bflo(gv.x) + b4.x) * a.x, v1 = sigmoidf_(bfhi(gv.x) + b4.y) * a.y;
;             float v2 = sigmoidf_(bflo(gv.y) + b4.z) * a.z, v3 = sigmoidf_(bfhi(gv.y) + b4.w) * a.w;
;             if (jb > 0) { const u32x2 pv = *(const u32x2*)(mp + f); v0 += bflo(pv.x); v1 += bfhi(pv.x); v2 += bflo(pv.y); v3 += bfhi(pv.y); }
;             u32x2 o2; o2.x = pack2(v0, v1); o2.y = pack2(v2, v3);
;             *(u32x2*)(mp + f) = o2;
;           }
;       }
	v_lshlrev_b32_e32 v138, 16, v202
	v_and_b32_e32 v139, 0xffff0000, v202
	v_lshlrev_b32_e32 v140, 16, v203
	v_and_b32_e32 v141, 0xffff0000, v203
	v_add_f32_e32 v138, v180, v138
	v_add_f32_e32 v139, v181, v139
	v_add_f32_e32 v140, v182, v140
	v_add_f32_e32 v141, v183, v141
	v_mul_f32_e32 v138, 0xbfb8aa3b, v138
	v_mul_f32_e32 v139, 0xbfb8aa3b, v139
	v_mul_f32_e32 v140, 0xbfb8aa3b, v140
	v_mul_f32_e32 v141, 0xbfb8aa3b, v141
	v_exp_f32_e32 v138, v138
	v_exp_f32_e32 v139, v139
	v_exp_f32_e32 v140, v140
	v_exp_f32_e32 v141, v141
	v_add_f32_e32 v138, 1.0, v138
	v_add_f32_e32 v139, 1.0, v139
	v_add_f32_e32 v140, 1.0, v140
	v_add_f32_e32 v141, 1.0, v141
	v_rcp_f32_e32 v138, v138
	v_rcp_f32_e32 v139, v139
	v_rcp_f32_e32 v140, v140
	v_rcp_f32_e32 v141, v141
	s_nop 0
	v_pk_mul_f32 v[18:19], v[18:19], v[138:139]
	v_pk_mul_f32 v[20:21], v[20:21], v[140:141]
	v_cvt_pk_bf16_f32 v152, v18, v19
	v_cvt_pk_bf16_f32 v153, v20, v21
	v_lshl_add_u64 v[154:155], v[120:121], 0, v[136:137]
	s_nop 1
	v_permlane16_swap_b32_e32 v150, v152
	v_permlane16_swap_b32_e32 v151, v153
	global_store_dwordx4 v[154:155], v[150:153], off offset:64
	s_waitcnt vmcnt(7)
	v_lshlrev_b32_e32 v138, 16, v110
	v_and_b32_e32 v139, 0xffff0000, v110
	v_lshlrev_b32_e32 v140, 16, v111
	v_and_b32_e32 v141, 0xffff0000, v111
	v_add_f32_e32 v138, v184, v138
	v_add_f32_e32 v139, v185, v139
	v_add_f32_e32 v140, v186, v140
	v_add_f32_e32 v141, v187, v141
	v_mul_f32_e32 v138, 0xbfb8aa3b, v138
	v_mul_f32_e32 v139, 0xbfb8aa3b, v139
	v_mul_f32_e32 v140, 0xbfb8aa3b, v140
	v_mul_f32_e32 v141, 0xbfb8aa3b, v141
	v_exp_f32_e32 v138, v138
	v_exp_f32_e32 v139, v139
	v_exp_f32_e32 v140, v140
	v_exp_f32_e32 v141, v141
	v_add_f32_e32 v138, 1.0, v138
	v_add_f32_e32 v139, 1.0, v139
	v_add_f32_e32 v140, 1.0, v140
	v_add_f32_e32 v141, 1.0, v141
	v_rcp_f32_e32 v138, v138
	v_rcp_f32_e32 v139, v139
	v_rcp_f32_e32 v140, v140
	v_rcp_f32_e32 v141, v141
	s_nop 0
	v_pk_mul_f32 v[14:15], v[14:15], v[138:139]
	v_pk_mul_f32 v[16:17], v[16:17], v[140:141]
	v_cvt_pk_bf16_f32 v146, v14, v15
	v_cvt_pk_bf16_f32 v147, v16, v17
	s_waitcnt vmcnt(6)
	v_lshlrev_b32_e32 v138, 16, v112
	v_and_b32_e32 v139, 0xffff0000, v112
	v_lshlrev_b32_e32 v140, 16, v113
	v_and_b32_e32 v141, 0xffff0000, v113
	v_add_f32_e32 v138, v188, v138
	v_add_f32_e32 v139, v189, v139
	v_add_f32_e32 v140, v190, v140
	v_add_f32_e32 v141, v191, v141
	v_mul_f32_e32 v138, 0xbfb8aa3b, v138
	v_mul_f32_e32 v139, 0xbfb8aa3b, v139
	v_mul_f32_e32 v140, 0xbfb8aa3b, v140
	v_mul_f32_e32 v141, 0xbfb8aa3b, v141
	v_exp_f32_e32 v138, v138
	v_exp_f32_e32 v139, v139
	v_exp_f32_e32 v140, v140
	v_exp_f32_e32 v141, v141
	v_add_f32_e32 v138, 1.0, v138
	v_add_f32_e32 v139, 1.0, v139
	v_add_f32_e32 v140, 1.0, v140
	v_add_f32_e32 v141, 1.0, v141
	v_rcp_f32_e32 v138, v138
	v_rcp_f32_e32 v139, v139
	v_rcp_f32_e32 v140, v140
	v_rcp_f32_e32 v141, v141
	s_nop 0
	v_pk_mul_f32 v[10:11], v[10:11], v[138:139]
	v_pk_mul_f32 v[12:13], v[12:13], v[140:141]
	v_cvt_pk_bf16_f32 v148, v10, v11
	v_cvt_pk_bf16_f32 v149, v12, v13
	v_lshl_add_u64 v[154:155], v[120:121], 0, v[136:137]
	s_nop 1
	v_permlane16_swap_b32_e32 v146, v148
	v_permlane16_swap_b32_e32 v147, v149
	global_store_dwordx4 v[154:155], v[146:149], off offset:256
	s_waitcnt vmcnt(5)
	v_lshlrev_b32_e32 v138, 16, v204
	v_and_b32_e32 v139, 0xffff0000, v204
	v_lshlrev_b32_e32 v140, 16, v205
	v_and_b32_e32 v141, 0xffff0000, v205
	v_add_f32_e32 v138, v192, v138
	v_add_f32_e32 v139, v193, v139
	v_add_f32_e32 v140, v194, v140
	v_add_f32_e32 v141, v195, v141
	v_mul_f32_e32 v138, 0xbfb8aa3b, v138
	v_mul_f32_e32 v139, 0xbfb8aa3b, v139
	v_mul_f32_e32 v140, 0xbfb8aa3b, v140
	v_mul_f32_e32 v141, 0xbfb8aa3b, v141
	v_exp_f32_e32 v138, v138
	v_exp_f32_e32 v139, v139
	v_exp_f32_e32 v140, v140
	v_exp_f32_e32 v141, v141
	v_add_f32_e32 v138, 1.0, v138
	v_add_f32_e32 v139, 1.0, v139
	v_add_f32_e32 v140, 1.0, v140
	v_add_f32_e32 v141, 1.0, v141
	v_rcp_f32_e32 v138, v138
	v_rcp_f32_e32 v139, v139
	v_rcp_f32_e32 v140, v140
	v_rcp_f32_e32 v141, v141
	s_nop 0
	v_pk_mul_f32 v[6:7], v[6:7], v[138:139]
	v_pk_mul_f32 v[8:9], v[8:9], v[140:141]
	v_cvt_pk_bf16_f32 v150, v6, v7
	v_cvt_pk_bf16_f32 v151, v8, v9
	s_waitcnt vmcnt(4)
	v_lshlrev_b32_e32 v138, 16, v106
	v_and_b32_e32 v139, 0xffff0000, v106
	v_lshlrev_b32_e32 v140, 16, v107
	v_and_b32_e32 v141, 0xffff0000, v107
	v_add_f32_e32 v138, v196, v138
	v_add_f32_e32 v139, v197, v139
	v_add_f32_e32 v140, v198, v140
	v_add_f32_e32 v141, v199, v141
	v_mul_f32_e32 v138, 0xbfb8aa3b, v138
	v_mul_f32_e32 v139, 0xbfb8aa3b, v139
	v_mul_f32_e32 v140, 0xbfb8aa3b, v140
	v_mul_f32_e32 v141, 0xbfb8aa3b, v141
	v_exp_f32_e32 v138, v138
	v_exp_f32_e32 v139, v139
	v_exp_f32_e32 v140, v140
	v_exp_f32_e32 v141, v141
	v_add_f32_e32 v138, 1.0, v138
	v_add_f32_e32 v139, 1.0, v139
	v_add_f32_e32 v140, 1.0, v140
	v_add_f32_e32 v141, 1.0, v141
	v_rcp_f32_e32 v138, v138
	v_rcp_f32_e32 v139, v139
	v_rcp_f32_e32 v140, v140
	v_rcp_f32_e32 v141, v141
	s_nop 0
	v_pk_mul_f32 v[2:3], v[2:3], v[138:139]
	v_pk_mul_f32 v[4:5], v[4:5], v[140:141]
	v_cvt_pk_bf16_f32 v152, v2, v3
	v_cvt_pk_bf16_f32 v153, v4, v5
	v_lshl_add_u64 v[154:155], v[120:121], 0, v[136:137]
	s_nop 1
	v_permlane16_swap_b32_e32 v150, v152
	v_permlane16_swap_b32_e32 v151, v153
	global_store_dwordx4 v[154:155], v[150:153], off offset:320
	s_branch .LBB0_703
